# E22 variant: activation-fragment runs of 4 chains (across both weight groups), snake over the weight fragments
# baseline (speedup 1.0000x reference)
;     __device__ __forceinline__ int nt(const Unit& u) const { return (u.pn >> 1) < 2 ? 22 : 20; }
; #define PG8_STAGE(bufoff, gbase, voff) do { _Pragma("unroll") for (int _i = 0; _i < 2; ++_i) \
;         __builtin_amdgcn_global_load_lds((const unsigned*)((const char*)(gbase) + (voff)[_i]), (LAS unsigned*)(lds + (bufoff) + ldsw + _i * 8192), 16, 0, 0); } while (0)
; #define PG8_LDA(dst, b, h) do { _Pragma("unroll") for (int m = 0; m < 4; ++m) _Pragma("unroll") for (int k = 0; k < 2; ++k) dst[m][k] = *(const LAS bf16x8*)(pA + PG8_SA(b, h) + m * 2048 + k * 1024); } while (0)
; #define PG8_LDB(dst, b, h) do { _Pragma("unroll") for (int n = 0; n < 2; ++n) _Pragma("unroll") for (int k = 0; k < 2; ++k) dst[n][k] = *(const LAS bf16x8*)(pB + (PG8_SB(b, h) - 4 * HTB) + n * 2048 + k * 1024); } while (0)
; #define PG8_MMA(ai, bj, At, Bt) do { __builtin_amdgcn_s_setprio(1); _Pragma("unroll") for (int m = 0; m < 4; ++m) _Pragma("unroll") for (int n = 0; n < 2; ++n) _Pragma("unroll") for (int k = 0; k < 2; ++k) \
;         acc[ai][bj][m][n] = __builtin_amdgcn_mfma_f32_16x16x32_bf16(Bt[n][k], At[m][k], acc[ai][bj][m][n], 0, 0, 0); __builtin_amdgcn_s_setprio(0); } while (0)
; #define PG8_WAIT_V(n) asm volatile("s_waitcnt vmcnt(" #n ")" ::: "memory")
; #define PG8_WAIT_L(n) asm volatile("s_waitcnt lgkmcnt(" #n ")" ::: "memory")
; #define PG8_BAR __builtin_amdgcn_s_barrier()
; template <class Desc, class Epi, bool ALIGN_EPI>
; __device__ __forceinline__ void gemm_phase(LAS unsigned char* lds, const Desc& D, const Epi& E, int G, int c) {
;     ...
;         for (int t = 0; t < nt; t += 2) {
;             const bool last = (t == nt - 2);
;             if (last && has_next) PG8_AWAIT(nxt);
;             const char* a1 = cA + (size_t)(t + 1) * kstep;
;             const char* a2 = last ? nA : cA + (size_t)(t + 2) * kstep; const char* b2 = last ? nB : cB + (size_t)(t + 2) * kstep;
;             const char* a3 = a2 + kstep; const char* b3 = b2 + kstep;
;             PG8_LDB(B0, 0, 0); PG8_LDB(B1, 0, 1); PG8_SCHED; PG8_LDA(At, 0, 0); PG8_STAGE(PG8_SA(1, 1), a1 + hstepA, voffA);
;             PG8_WAIT_V(8); PG8_WAIT_L(0); PG8_BAR; PG8_MMA(0, 0, At, B0); PG8_MMA(0, 1, At, B1); PG8_BAR; PG8_SCHED;
;             PG8_LDA(At, 0, 1); PG8_STAGE(PG8_SB(0, 0), b2, voffB); PG8_STAGE(PG8_SB(0, 1), b2 + hstepB, voffB); PG8_STAGE(PG8_SA(0, 0), a2, voffA);
.LBB0_172:
	s_or_b32 s14, s17, 1
	s_lshl_b64 s[26:27], s[14:15], 7
	s_add_i32 s14, s17, 2
	s_lshl_b64 s[40:41], s[14:15], 7
	s_add_u32 s17, s12, s40
	ds_read_b128 v[134:137], v169
	ds_read_b128 v[138:141], v169 offset:1024
	ds_read_b128 v[142:145], v169 offset:2048
	ds_read_b128 v[146:149], v169 offset:3072
	ds_read_b128 v[160:163], v169 offset:16384
	ds_read_b128 v[164:167], v169 offset:17408
	ds_read_b128 v[174:177], v169 offset:18432
	ds_read_b128 v[178:181], v169 offset:19456
	s_addc_u32 s21, s13, s41
	s_and_b64 s[38:39], s[30:31], exec
	s_cselect_b32 s39, s61, s21
	s_cselect_b32 s38, s60, s17
	s_add_u32 s17, s18, s40
	s_addc_u32 s21, s19, s41
	s_and_b64 s[30:31], s[30:31], exec
	s_cselect_b32 s31, s63, s21
	s_cselect_b32 s30, s62, s17
	s_add_u32 s17, s12, s26
	s_addc_u32 s21, s13, s27
	s_add_u32 s26, s17, 0x100000
	s_addc_u32 s27, s21, 0
	s_mov_b32 m0, s50
	v_lshl_add_u64 v[150:151], s[26:27], 0, v[152:153]
	ds_read_b128 v[182:185], v168
	ds_read_b128 v[186:189], v168 offset:1024
	ds_read_b128 v[190:193], v168 offset:2048
	ds_read_b128 v[194:197], v168 offset:3072
	ds_read_b128 v[198:201], v168 offset:4096
	ds_read_b128 v[202:205], v168 offset:5120
	ds_read_b128 v[206:209], v168 offset:6144
	ds_read_b128 v[210:213], v168 offset:7168
	global_load_lds_dwordx4 v[150:151], off
	v_lshl_add_u64 v[150:151], s[26:27], 0, v[156:157]
	s_mov_b32 m0, s51
	s_nop 0
	global_load_lds_dwordx4 v[150:151], off
	s_waitcnt vmcnt(8)
	s_waitcnt lgkmcnt(0)
	s_barrier
	v_mfma_f32_16x16x32_bf16 v[128:131], v[134:137], v[182:185], v[128:131]
	v_mfma_f32_16x16x32_bf16 v[128:131], v[138:141], v[186:189], v[128:131]
	v_mfma_f32_16x16x32_bf16 v[124:127], v[142:145], v[182:185], v[124:127]
	v_mfma_f32_16x16x32_bf16 v[124:127], v[146:149], v[186:189], v[124:127]
	v_mfma_f32_16x16x32_bf16 v[96:99], v[160:163], v[182:185], v[96:99]
	v_mfma_f32_16x16x32_bf16 v[96:99], v[164:167], v[186:189], v[96:99]
	v_mfma_f32_16x16x32_bf16 v[92:95], v[174:177], v[182:185], v[92:95]
	v_mfma_f32_16x16x32_bf16 v[92:95], v[178:181], v[186:189], v[92:95]
	v_mfma_f32_16x16x32_bf16 v[84:87], v[174:177], v[190:193], v[84:87]
	v_mfma_f32_16x16x32_bf16 v[84:87], v[178:181], v[194:197], v[84:87]
	v_mfma_f32_16x16x32_bf16 v[88:91], v[160:163], v[190:193], v[88:91]
	v_mfma_f32_16x16x32_bf16 v[88:91], v[164:167], v[194:197], v[88:91]
	v_mfma_f32_16x16x32_bf16 v[116:119], v[142:145], v[190:193], v[116:119]
	v_mfma_f32_16x16x32_bf16 v[116:119], v[146:149], v[194:197], v[116:119]
	v_mfma_f32_16x16x32_bf16 v[120:123], v[134:137], v[190:193], v[120:123]
	v_mfma_f32_16x16x32_bf16 v[120:123], v[138:141], v[194:197], v[120:123]
	v_mfma_f32_16x16x32_bf16 v[112:115], v[134:137], v[198:201], v[112:115]
	v_mfma_f32_16x16x32_bf16 v[112:115], v[138:141], v[202:205], v[112:115]
	v_mfma_f32_16x16x32_bf16 v[108:111], v[142:145], v[198:201], v[108:111]
	v_mfma_f32_16x16x32_bf16 v[108:111], v[146:149], v[202:205], v[108:111]
	v_mfma_f32_16x16x32_bf16 v[80:83], v[160:163], v[198:201], v[80:83]
	v_mfma_f32_16x16x32_bf16 v[80:83], v[164:167], v[202:205], v[80:83]
	v_mfma_f32_16x16x32_bf16 v[76:79], v[174:177], v[198:201], v[76:79]
	v_mfma_f32_16x16x32_bf16 v[76:79], v[178:181], v[202:205], v[76:79]
	v_mfma_f32_16x16x32_bf16 v[68:71], v[174:177], v[206:209], v[68:71]
	v_mfma_f32_16x16x32_bf16 v[68:71], v[178:181], v[210:213], v[68:71]
	v_mfma_f32_16x16x32_bf16 v[72:75], v[160:163], v[206:209], v[72:75]
	v_mfma_f32_16x16x32_bf16 v[72:75], v[164:167], v[210:213], v[72:75]
	v_mfma_f32_16x16x32_bf16 v[100:103], v[142:145], v[206:209], v[100:103]
	v_mfma_f32_16x16x32_bf16 v[100:103], v[146:149], v[210:213], v[100:103]
	v_mfma_f32_16x16x32_bf16 v[104:107], v[134:137], v[206:209], v[104:107]
	v_mfma_f32_16x16x32_bf16 v[104:107], v[138:141], v[210:213], v[104:107]
	s_barrier
	s_mov_b32 m0, s84
	v_lshl_add_u64 v[150:151], s[30:31], 0, v[154:155]
	s_add_u32 s26, s30, 0x100000
	ds_read_b128 v[182:185], v168 offset:16384
	ds_read_b128 v[186:189], v168 offset:17408
	ds_read_b128 v[190:193], v168 offset:18432
	ds_read_b128 v[194:197], v168 offset:19456
	ds_read_b128 v[198:201], v168 offset:20480
	ds_read_b128 v[202:205], v168 offset:21504
	ds_read_b128 v[206:209], v168 offset:22528
	ds_read_b128 v[210:213], v168 offset:23552
	global_load_lds_dwordx4 v[150:151], off
	v_lshl_add_u64 v[214:215], s[30:31], 0, v[158:159]
	s_mov_b32 m0, s85
	s_addc_u32 s27, s31, 0
	global_load_lds_dwordx4 v[214:215], off
	v_lshl_add_u64 v[216:217], s[26:27], 0, v[154:155]
	s_mov_b32 m0, s86
	v_lshl_add_u64 v[218:219], s[38:39], 0, v[156:157]
	global_load_lds_dwordx4 v[216:217], off
	v_lshl_add_u64 v[216:217], s[26:27], 0, v[158:159]
	s_mov_b32 m0, s87
	s_nop 0
	global_load_lds_dwordx4 v[216:217], off
	v_lshl_add_u64 v[216:217], s[38:39], 0, v[152:153]
	s_mov_b32 m0, s83
	s_nop 0
	global_load_lds_dwordx4 v[216:217], off
	s_mov_b32 m0, s88
	s_nop 0
	global_load_lds_dwordx4 v[218:219], off
	s_waitcnt vmcnt(8)
	s_waitcnt lgkmcnt(0)
	s_barrier
; #define PG8_STAGE(bufoff, gbase, voff) do { _Pragma("unroll") for (int _i = 0; _i < 2; ++_i) \
;         __builtin_amdgcn_global_load_lds((const unsigned*)((const char*)(gbase) + (voff)[_i]), (LAS unsigned*)(lds + (bufoff) + ldsw + _i * 8192), 16, 0, 0); } while (0)
; #define PG8_LDA(dst, b, h) do { _Pragma("unroll") for (int m = 0; m < 4; ++m) _Pragma("unroll") for (int k = 0; k < 2; ++k) dst[m][k] = *(const LAS bf16x8*)(pA + PG8_SA(b, h) + m * 2048 + k * 1024); } while (0)
; #define PG8_LDB(dst, b, h) do { _Pragma("unroll") for (int n = 0; n < 2; ++n) _Pragma("unroll") for (int k = 0; k < 2; ++k) dst[n][k] = *(const LAS bf16x8*)(pB + (PG8_SB(b, h) - 4 * HTB) + n * 2048 + k * 1024); } while (0)
; #define PG8_MMA(ai, bj, At, Bt) do { __builtin_amdgcn_s_setprio(1); _Pragma("unroll") for (int m = 0; m < 4; ++m) _Pragma("unroll") for (int n = 0; n < 2; ++n) _Pragma("unroll") for (int k = 0; k < 2; ++k) \
;         acc[ai][bj][m][n] = __builtin_amdgcn_mfma_f32_16x16x32_bf16(Bt[n][k], At[m][k], acc[ai][bj][m][n], 0, 0, 0); __builtin_amdgcn_s_setprio(0); } while (0)
; #define PG8_WAIT_V(n) asm volatile("s_waitcnt vmcnt(" #n ")" ::: "memory")
; #define PG8_WAIT_L(n) asm volatile("s_waitcnt lgkmcnt(" #n ")" ::: "memory")
; #define PG8_BAR __builtin_amdgcn_s_barrier()
; #define PG8_SCHED __builtin_amdgcn_sched_barrier(0)
; template <class Desc, class Epi, bool ALIGN_EPI>
; __device__ __forceinline__ void gemm_phase(LAS unsigned char* lds, const Desc& D, const Epi& E, int G, int c) {
;     ...
;             PG8_WAIT_V(8); PG8_WAIT_L(0); PG8_BAR; PG8_MMA(1, 0, At, B0); PG8_MMA(1, 1, At, B1); PG8_BAR; PG8_SCHED;
;             PG8_LDB(B0, 1, 0); PG8_LDB(B1, 1, 1); PG8_SCHED; PG8_LDA(At, 1, 0); PG8_STAGE(PG8_SA(0, 1), a2 + hstepA, voffA);
;             PG8_WAIT_V(8); PG8_WAIT_L(0); PG8_BAR; PG8_MMA(0, 0, At, B0); PG8_MMA(0, 1, At, B1); PG8_BAR; PG8_SCHED;
	v_mfma_f32_16x16x32_bf16 v[64:67], v[134:137], v[182:185], v[64:67]
	v_mfma_f32_16x16x32_bf16 v[64:67], v[138:141], v[186:189], v[64:67]
	v_mfma_f32_16x16x32_bf16 v[52:55], v[142:145], v[182:185], v[52:55]
	v_mfma_f32_16x16x32_bf16 v[52:55], v[146:149], v[186:189], v[52:55]
	v_mfma_f32_16x16x32_bf16 v[60:63], v[160:163], v[182:185], v[60:63]
	v_mfma_f32_16x16x32_bf16 v[60:63], v[164:167], v[186:189], v[60:63]
	v_mfma_f32_16x16x32_bf16 v[56:59], v[174:177], v[182:185], v[56:59]
	v_mfma_f32_16x16x32_bf16 v[56:59], v[178:181], v[186:189], v[56:59]
	v_mfma_f32_16x16x32_bf16 v[44:47], v[174:177], v[190:193], v[44:47]
	v_mfma_f32_16x16x32_bf16 v[44:47], v[178:181], v[194:197], v[44:47]
	v_mfma_f32_16x16x32_bf16 v[48:51], v[160:163], v[190:193], v[48:51]
	v_mfma_f32_16x16x32_bf16 v[48:51], v[164:167], v[194:197], v[48:51]
	v_mfma_f32_16x16x32_bf16 v[20:23], v[142:145], v[190:193], v[20:23]
	v_mfma_f32_16x16x32_bf16 v[20:23], v[146:149], v[194:197], v[20:23]
	v_mfma_f32_16x16x32_bf16 v[32:35], v[134:137], v[190:193], v[32:35]
	v_mfma_f32_16x16x32_bf16 v[32:35], v[138:141], v[194:197], v[32:35]
	v_mfma_f32_16x16x32_bf16 v[16:19], v[134:137], v[198:201], v[16:19]
	v_mfma_f32_16x16x32_bf16 v[16:19], v[138:141], v[202:205], v[16:19]
	v_mfma_f32_16x16x32_bf16 v[12:15], v[142:145], v[198:201], v[12:15]
	v_mfma_f32_16x16x32_bf16 v[12:15], v[146:149], v[202:205], v[12:15]
	v_mfma_f32_16x16x32_bf16 v[40:43], v[160:163], v[198:201], v[40:43]
	v_mfma_f32_16x16x32_bf16 v[40:43], v[164:167], v[202:205], v[40:43]
	v_mfma_f32_16x16x32_bf16 v[36:39], v[174:177], v[198:201], v[36:39]
	v_mfma_f32_16x16x32_bf16 v[36:39], v[178:181], v[202:205], v[36:39]
	v_mfma_f32_16x16x32_bf16 v[24:27], v[174:177], v[206:209], v[24:27]
	v_mfma_f32_16x16x32_bf16 v[24:27], v[178:181], v[210:213], v[24:27]
	v_mfma_f32_16x16x32_bf16 v[28:31], v[160:163], v[206:209], v[28:31]
	v_mfma_f32_16x16x32_bf16 v[28:31], v[164:167], v[210:213], v[28:31]
	v_mfma_f32_16x16x32_bf16 v[4:7], v[142:145], v[206:209], v[4:7]
	v_mfma_f32_16x16x32_bf16 v[4:7], v[146:149], v[210:213], v[4:7]
	v_mfma_f32_16x16x32_bf16 v[8:11], v[134:137], v[206:209], v[8:11]
	v_mfma_f32_16x16x32_bf16 v[8:11], v[138:141], v[210:213], v[8:11]
	s_barrier
	ds_read_b128 v[134:137], v169 offset:32768
	ds_read_b128 v[138:141], v169 offset:33792
	ds_read_b128 v[142:145], v169 offset:34816
	ds_read_b128 v[146:149], v169 offset:35840
	ds_read_b128 v[160:163], v169 offset:49152
	ds_read_b128 v[164:167], v169 offset:50176
	ds_read_b128 v[174:177], v169 offset:51200
	ds_read_b128 v[178:181], v169 offset:52224
	s_add_u32 s26, s38, 0x100000
	s_addc_u32 s27, s39, 0
	s_mov_b32 m0, s89
	v_lshl_add_u64 v[220:221], s[26:27], 0, v[152:153]
	ds_read_b128 v[182:185], v168 offset:32768
	ds_read_b128 v[186:189], v168 offset:33792
	ds_read_b128 v[190:193], v168 offset:34816
	ds_read_b128 v[194:197], v168 offset:35840
	ds_read_b128 v[198:201], v168 offset:36864
	ds_read_b128 v[202:205], v168 offset:37888
	ds_read_b128 v[206:209], v168 offset:38912
	ds_read_b128 v[210:213], v168 offset:39936
	global_load_lds_dwordx4 v[220:221], off
	v_lshl_add_u64 v[220:221], s[26:27], 0, v[156:157]
	s_mov_b32 m0, s90
	s_nop 0
	global_load_lds_dwordx4 v[220:221], off
	s_waitcnt vmcnt(8)
	s_waitcnt lgkmcnt(0)
	s_barrier
	v_mfma_f32_16x16x32_bf16 v[128:131], v[134:137], v[182:185], v[128:131]
	v_mfma_f32_16x16x32_bf16 v[128:131], v[138:141], v[186:189], v[128:131]
	v_mfma_f32_16x16x32_bf16 v[124:127], v[142:145], v[182:185], v[124:127]
	v_mfma_f32_16x16x32_bf16 v[124:127], v[146:149], v[186:189], v[124:127]
	v_mfma_f32_16x16x32_bf16 v[96:99], v[160:163], v[182:185], v[96:99]
	v_mfma_f32_16x16x32_bf16 v[96:99], v[164:167], v[186:189], v[96:99]
	v_mfma_f32_16x16x32_bf16 v[92:95], v[174:177], v[182:185], v[92:95]
	v_mfma_f32_16x16x32_bf16 v[92:95], v[178:181], v[186:189], v[92:95]
	v_mfma_f32_16x16x32_bf16 v[84:87], v[174:177], v[190:193], v[84:87]
	v_mfma_f32_16x16x32_bf16 v[84:87], v[178:181], v[194:197], v[84:87]
	v_mfma_f32_16x16x32_bf16 v[88:91], v[160:163], v[190:193], v[88:91]
	v_mfma_f32_16x16x32_bf16 v[88:91], v[164:167], v[194:197], v[88:91]
	v_mfma_f32_16x16x32_bf16 v[116:119], v[142:145], v[190:193], v[116:119]
	v_mfma_f32_16x16x32_bf16 v[116:119], v[146:149], v[194:197], v[116:119]
	v_mfma_f32_16x16x32_bf16 v[120:123], v[134:137], v[190:193], v[120:123]
	v_mfma_f32_16x16x32_bf16 v[120:123], v[138:141], v[194:197], v[120:123]
	v_mfma_f32_16x16x32_bf16 v[112:115], v[134:137], v[198:201], v[112:115]
	v_mfma_f32_16x16x32_bf16 v[112:115], v[138:141], v[202:205], v[112:115]
	v_mfma_f32_16x16x32_bf16 v[108:111], v[142:145], v[198:201], v[108:111]
	v_mfma_f32_16x16x32_bf16 v[108:111], v[146:149], v[202:205], v[108:111]
	v_mfma_f32_16x16x32_bf16 v[80:83], v[160:163], v[198:201], v[80:83]
	v_mfma_f32_16x16x32_bf16 v[80:83], v[164:167], v[202:205], v[80:83]
	v_mfma_f32_16x16x32_bf16 v[76:79], v[174:177], v[198:201], v[76:79]
	v_mfma_f32_16x16x32_bf16 v[76:79], v[178:181], v[202:205], v[76:79]
	v_mfma_f32_16x16x32_bf16 v[68:71], v[174:177], v[206:209], v[68:71]
	v_mfma_f32_16x16x32_bf16 v[68:71], v[178:181], v[210:213], v[68:71]
	v_mfma_f32_16x16x32_bf16 v[72:75], v[160:163], v[206:209], v[72:75]
	v_mfma_f32_16x16x32_bf16 v[72:75], v[164:167], v[210:213], v[72:75]
	v_mfma_f32_16x16x32_bf16 v[100:103], v[142:145], v[206:209], v[100:103]
	v_mfma_f32_16x16x32_bf16 v[100:103], v[146:149], v[210:213], v[100:103]
	v_mfma_f32_16x16x32_bf16 v[104:107], v[134:137], v[206:209], v[104:107]
	v_mfma_f32_16x16x32_bf16 v[104:107], v[138:141], v[210:213], v[104:107]
	s_barrier
; #define PG8_STAGE(bufoff, gbase, voff) do { _Pragma("unroll") for (int _i = 0; _i < 2; ++_i) \
;         __builtin_amdgcn_global_load_lds((const unsigned*)((const char*)(gbase) + (voff)[_i]), (LAS unsigned*)(lds + (bufoff) + ldsw + _i * 8192), 16, 0, 0); } while (0)
; #define PG8_LDA(dst, b, h) do { _Pragma("unroll") for (int m = 0; m < 4; ++m) _Pragma("unroll") for (int k = 0; k < 2; ++k) dst[m][k] = *(const LAS bf16x8*)(pA + PG8_SA(b, h) + m * 2048 + k * 1024); } while (0)
; #define PG8_MMA(ai, bj, At, Bt) do { __builtin_amdgcn_s_setprio(1); _Pragma("unroll") for (int m = 0; m < 4; ++m) _Pragma("unroll") for (int n = 0; n < 2; ++n) _Pragma("unroll") for (int k = 0; k < 2; ++k) \
;         acc[ai][bj][m][n] = __builtin_amdgcn_mfma_f32_16x16x32_bf16(Bt[n][k], At[m][k], acc[ai][bj][m][n], 0, 0, 0); __builtin_amdgcn_s_setprio(0); } while (0)
; #define PG8_WAIT_V(n) asm volatile("s_waitcnt vmcnt(" #n ")" ::: "memory")
; #define PG8_WAIT_L(n) asm volatile("s_waitcnt lgkmcnt(" #n ")" ::: "memory")
; #define PG8_BAR __builtin_amdgcn_s_barrier()
; #define PG8_SCHED __builtin_amdgcn_sched_barrier(0)
; template <class Desc, class Epi, bool ALIGN_EPI>
; __device__ __forceinline__ void gemm_phase(LAS unsigned char* lds, const Desc& D, const Epi& E, int G, int c) {
;     ...
;             PG8_LDA(At, 1, 1); PG8_STAGE(PG8_SB(1, 0), b3, voffB); PG8_STAGE(PG8_SB(1, 1), b3 + hstepB, voffB); PG8_STAGE(PG8_SA(1, 0), a3, voffA);
;             PG8_WAIT_V(8); PG8_WAIT_L(0); PG8_BAR; PG8_MMA(1, 0, At, B0); PG8_MMA(1, 1, At, B1); PG8_BAR; PG8_SCHED;
;         }
	s_mov_b32 m0, s92
	v_lshl_add_u64 v[150:151], v[150:151], 0, s[76:77]
	s_add_u32 s26, s30, 0x100080
	ds_read_b128 v[182:185], v168 offset:49152
	ds_read_b128 v[186:189], v168 offset:50176
	ds_read_b128 v[190:193], v168 offset:51200
	ds_read_b128 v[194:197], v168 offset:52224
	ds_read_b128 v[198:201], v168 offset:53248
	ds_read_b128 v[202:205], v168 offset:54272
	ds_read_b128 v[206:209], v168 offset:55296
	ds_read_b128 v[210:213], v168 offset:56320
	global_load_lds_dwordx4 v[150:151], off
	v_lshl_add_u64 v[150:151], v[214:215], 0, s[76:77]
	s_mov_b32 m0, s93
	s_addc_u32 s27, s31, 0
	global_load_lds_dwordx4 v[150:151], off
	v_lshl_add_u64 v[150:151], s[26:27], 0, v[154:155]
	s_mov_b32 m0, s97
	s_nop 0
	global_load_lds_dwordx4 v[150:151], off
	v_lshl_add_u64 v[150:151], s[26:27], 0, v[158:159]
	s_mov_b32 m0, s82
	s_nop 0
	global_load_lds_dwordx4 v[150:151], off
	v_lshl_add_u64 v[150:151], v[216:217], 0, s[76:77]
	s_mov_b32 m0, s94
	s_nop 0
	global_load_lds_dwordx4 v[150:151], off
	v_lshl_add_u64 v[150:151], v[218:219], 0, s[76:77]
	s_mov_b32 m0, s95
	s_nop 0
	global_load_lds_dwordx4 v[150:151], off
	s_waitcnt vmcnt(8)
	s_waitcnt lgkmcnt(0)
	s_barrier
	v_mfma_f32_16x16x32_bf16 v[64:67], v[134:137], v[182:185], v[64:67]
	v_mfma_f32_16x16x32_bf16 v[64:67], v[138:141], v[186:189], v[64:67]
	v_mfma_f32_16x16x32_bf16 v[52:55], v[142:145], v[182:185], v[52:55]
	v_mfma_f32_16x16x32_bf16 v[52:55], v[146:149], v[186:189], v[52:55]
	v_mfma_f32_16x16x32_bf16 v[60:63], v[160:163], v[182:185], v[60:63]
	v_mfma_f32_16x16x32_bf16 v[60:63], v[164:167], v[186:189], v[60:63]
	v_mfma_f32_16x16x32_bf16 v[56:59], v[174:177], v[182:185], v[56:59]
	v_mfma_f32_16x16x32_bf16 v[56:59], v[178:181], v[186:189], v[56:59]
	v_mfma_f32_16x16x32_bf16 v[44:47], v[174:177], v[190:193], v[44:47]
	v_mfma_f32_16x16x32_bf16 v[44:47], v[178:181], v[194:197], v[44:47]
	v_mfma_f32_16x16x32_bf16 v[48:51], v[160:163], v[190:193], v[48:51]
	v_mfma_f32_16x16x32_bf16 v[48:51], v[164:167], v[194:197], v[48:51]
	v_mfma_f32_16x16x32_bf16 v[20:23], v[142:145], v[190:193], v[20:23]
	v_mfma_f32_16x16x32_bf16 v[20:23], v[146:149], v[194:197], v[20:23]
	v_mfma_f32_16x16x32_bf16 v[32:35], v[134:137], v[190:193], v[32:35]
	v_mfma_f32_16x16x32_bf16 v[32:35], v[138:141], v[194:197], v[32:35]
	v_mfma_f32_16x16x32_bf16 v[16:19], v[134:137], v[198:201], v[16:19]
	v_mfma_f32_16x16x32_bf16 v[16:19], v[138:141], v[202:205], v[16:19]
	v_mfma_f32_16x16x32_bf16 v[12:15], v[142:145], v[198:201], v[12:15]
	v_mfma_f32_16x16x32_bf16 v[12:15], v[146:149], v[202:205], v[12:15]
	v_mfma_f32_16x16x32_bf16 v[40:43], v[160:163], v[198:201], v[40:43]
	v_mfma_f32_16x16x32_bf16 v[40:43], v[164:167], v[202:205], v[40:43]
	v_mfma_f32_16x16x32_bf16 v[36:39], v[174:177], v[198:201], v[36:39]
	v_mfma_f32_16x16x32_bf16 v[36:39], v[178:181], v[202:205], v[36:39]
	v_mfma_f32_16x16x32_bf16 v[24:27], v[174:177], v[206:209], v[24:27]
	v_mfma_f32_16x16x32_bf16 v[24:27], v[178:181], v[210:213], v[24:27]
	v_mfma_f32_16x16x32_bf16 v[28:31], v[160:163], v[206:209], v[28:31]
	v_mfma_f32_16x16x32_bf16 v[28:31], v[164:167], v[210:213], v[28:31]
	v_mfma_f32_16x16x32_bf16 v[4:7], v[142:145], v[206:209], v[4:7]
	v_mfma_f32_16x16x32_bf16 v[4:7], v[146:149], v[210:213], v[4:7]
	v_mfma_f32_16x16x32_bf16 v[8:11], v[134:137], v[206:209], v[8:11]
	v_mfma_f32_16x16x32_bf16 v[8:11], v[138:141], v[210:213], v[8:11]
	s_barrier
	s_cmp_ge_u32 s14, s3
	s_mov_b32 s17, s14
	s_cbranch_scc1 .LBB0_183

;     __device__ __forceinline__ int nt(const Unit& u) const { return (u.pn >> 1) < 2 ? 22 : 20; }
; #define PG8_STAGE(bufoff, gbase, voff) do { _Pragma("unroll") for (int _i = 0; _i < 2; ++_i) \
;         __builtin_amdgcn_global_load_lds((const unsigned*)((const char*)(gbase) + (voff)[_i]), (LAS unsigned*)(lds + (bufoff) + ldsw + _i * 8192), 16, 0, 0); } while (0)
; #define PG8_LDA(dst, b, h) do { _Pragma("unroll") for (int m = 0; m < 4; ++m) _Pragma("unroll") for (int k = 0; k < 2; ++k) dst[m][k] = *(const LAS bf16x8*)(pA + PG8_SA(b, h) + m * 2048 + k * 1024); } while (0)
; #define PG8_LDB(dst, b, h) do { _Pragma("unroll") for (int n = 0; n < 2; ++n) _Pragma("unroll") for (int k = 0; k < 2; ++k) dst[n][k] = *(const LAS bf16x8*)(pB + (PG8_SB(b, h) - 4 * HTB) + n * 2048 + k * 1024); } while (0)
; #define PG8_MMA(ai, bj, At, Bt) do { __builtin_amdgcn_s_setprio(1); _Pragma("unroll") for (int m = 0; m < 4; ++m) _Pragma("unroll") for (int n = 0; n < 2; ++n) _Pragma("unroll") for (int k = 0; k < 2; ++k) \
;         acc[ai][bj][m][n] = __builtin_amdgcn_mfma_f32_16x16x32_bf16(Bt[n][k], At[m][k], acc[ai][bj][m][n], 0, 0, 0); __builtin_amdgcn_s_setprio(0); } while (0)
; #define PG8_WAIT_V(n) asm volatile("s_waitcnt vmcnt(" #n ")" ::: "memory")
; #define PG8_WAIT_L(n) asm volatile("s_waitcnt lgkmcnt(" #n ")" ::: "memory")
; #define PG8_BAR __builtin_amdgcn_s_barrier()
; template <class Desc, class Epi, bool ALIGN_EPI>
; __device__ __forceinline__ void gemm_phase(LAS unsigned char* lds, const Desc& D, const Epi& E, int G, int c) {
;     ...
;         for (int t = 0; t < nt; t += 2) {
;             const bool last = (t == nt - 2);
;             if (last && has_next) PG8_AWAIT(nxt);
;             const char* a1 = cA + (size_t)(t + 1) * kstep;
;             const char* a2 = last ? nA : cA + (size_t)(t + 2) * kstep; const char* b2 = last ? nB : cB + (size_t)(t + 2) * kstep;
;             const char* a3 = a2 + kstep; const char* b3 = b2 + kstep;
;             PG8_LDB(B0, 0, 0); PG8_LDB(B1, 0, 1); PG8_SCHED; PG8_LDA(At, 0, 0); PG8_STAGE(PG8_SA(1, 1), a1 + hstepA, voffA);
;             PG8_WAIT_V(8); PG8_WAIT_L(0); PG8_BAR; PG8_MMA(0, 0, At, B0); PG8_MMA(0, 1, At, B1); PG8_BAR; PG8_SCHED;
;             PG8_LDA(At, 0, 1); PG8_STAGE(PG8_SB(0, 0), b2, voffB); PG8_STAGE(PG8_SB(0, 1), b2 + hstepB, voffB); PG8_STAGE(PG8_SA(0, 0), a2, voffA);
.LBB0_603:
	ds_read_b128 v[144:147], v149
	ds_read_b128 v[152:155], v149 offset:1024
	ds_read_b128 v[156:159], v149 offset:2048
	ds_read_b128 v[160:163], v149 offset:3072
	ds_read_b128 v[164:167], v149 offset:16384
	ds_read_b128 v[168:171], v149 offset:17408
	ds_read_b128 v[172:175], v149 offset:18432
	ds_read_b128 v[176:179], v149 offset:19456
	s_add_u32 s16, s12, 0xfff80080
	s_addc_u32 s17, s13, -1
	s_cmp_eq_u32 s46, 4
	s_cselect_b32 s19, s9, s17
	s_cselect_b32 s18, s8, s16
	s_cselect_b32 s17, s11, s45
	s_cselect_b32 s16, s10, s7
	v_lshl_add_u64 v[212:213], s[12:13], 0, v[140:141]
	s_add_i32 m0, s20, 0xc000
	ds_read_b128 v[180:183], v148
	ds_read_b128 v[184:187], v148 offset:1024
	ds_read_b128 v[188:191], v148 offset:2048
	ds_read_b128 v[192:195], v148 offset:3072
	ds_read_b128 v[196:199], v148 offset:4096
	ds_read_b128 v[200:203], v148 offset:5120
	ds_read_b128 v[204:207], v148 offset:6144
	ds_read_b128 v[208:211], v148 offset:7168
	global_load_lds_dwordx4 v[212:213], off
	v_lshl_add_u64 v[212:213], s[12:13], 0, v[142:143]
	s_add_i32 m0, s20, 0xe000
	s_nop 0
	global_load_lds_dwordx4 v[212:213], off
	s_waitcnt vmcnt(8)
	s_waitcnt lgkmcnt(0)
	s_barrier
	v_mfma_f32_16x16x32_bf16 v[128:131], v[144:147], v[180:183], v[128:131]
	v_mfma_f32_16x16x32_bf16 v[128:131], v[152:155], v[184:187], v[128:131]
	v_mfma_f32_16x16x32_bf16 v[124:127], v[156:159], v[180:183], v[124:127]
	v_mfma_f32_16x16x32_bf16 v[124:127], v[160:163], v[184:187], v[124:127]
	v_mfma_f32_16x16x32_bf16 v[120:123], v[164:167], v[180:183], v[120:123]
	v_mfma_f32_16x16x32_bf16 v[120:123], v[168:171], v[184:187], v[120:123]
	v_mfma_f32_16x16x32_bf16 v[112:115], v[172:175], v[180:183], v[112:115]
	v_mfma_f32_16x16x32_bf16 v[112:115], v[176:179], v[184:187], v[112:115]
	v_mfma_f32_16x16x32_bf16 v[96:99], v[172:175], v[188:191], v[96:99]
	v_mfma_f32_16x16x32_bf16 v[96:99], v[176:179], v[192:195], v[96:99]
	v_mfma_f32_16x16x32_bf16 v[104:107], v[164:167], v[188:191], v[104:107]
	v_mfma_f32_16x16x32_bf16 v[104:107], v[168:171], v[192:195], v[104:107]
	v_mfma_f32_16x16x32_bf16 v[108:111], v[156:159], v[188:191], v[108:111]
	v_mfma_f32_16x16x32_bf16 v[108:111], v[160:163], v[192:195], v[108:111]
	v_mfma_f32_16x16x32_bf16 v[116:119], v[144:147], v[188:191], v[116:119]
	v_mfma_f32_16x16x32_bf16 v[116:119], v[152:155], v[192:195], v[116:119]
	v_mfma_f32_16x16x32_bf16 v[100:103], v[144:147], v[196:199], v[100:103]
	v_mfma_f32_16x16x32_bf16 v[100:103], v[152:155], v[200:203], v[100:103]
	v_mfma_f32_16x16x32_bf16 v[92:95], v[156:159], v[196:199], v[92:95]
	v_mfma_f32_16x16x32_bf16 v[92:95], v[160:163], v[200:203], v[92:95]
	v_mfma_f32_16x16x32_bf16 v[88:91], v[164:167], v[196:199], v[88:91]
	v_mfma_f32_16x16x32_bf16 v[88:91], v[168:171], v[200:203], v[88:91]
	v_mfma_f32_16x16x32_bf16 v[80:83], v[172:175], v[196:199], v[80:83]
	v_mfma_f32_16x16x32_bf16 v[80:83], v[176:179], v[200:203], v[80:83]
	v_mfma_f32_16x16x32_bf16 v[68:71], v[172:175], v[204:207], v[68:71]
	v_mfma_f32_16x16x32_bf16 v[68:71], v[176:179], v[208:211], v[68:71]
	v_mfma_f32_16x16x32_bf16 v[72:75], v[164:167], v[204:207], v[72:75]
	v_mfma_f32_16x16x32_bf16 v[72:75], v[168:171], v[208:211], v[72:75]
	v_mfma_f32_16x16x32_bf16 v[76:79], v[156:159], v[204:207], v[76:79]
	v_mfma_f32_16x16x32_bf16 v[76:79], v[160:163], v[208:211], v[76:79]
	v_mfma_f32_16x16x32_bf16 v[84:87], v[144:147], v[204:207], v[84:87]
	v_mfma_f32_16x16x32_bf16 v[84:87], v[152:155], v[208:211], v[84:87]
	s_barrier
	s_mov_b32 m0, s21
	v_lshl_add_u64 v[212:213], s[16:17], 0, v[136:137]
	s_add_u32 s48, s16, 0x20000
	ds_read_b128 v[180:183], v148 offset:16384
	ds_read_b128 v[184:187], v148 offset:17408
	ds_read_b128 v[188:191], v148 offset:18432
	ds_read_b128 v[192:195], v148 offset:19456
	ds_read_b128 v[196:199], v148 offset:20480
	ds_read_b128 v[200:203], v148 offset:21504
	ds_read_b128 v[204:207], v148 offset:22528
	ds_read_b128 v[208:211], v148 offset:23552
	global_load_lds_dwordx4 v[212:213], off
	v_lshl_add_u64 v[214:215], s[16:17], 0, v[132:133]
	s_mov_b32 m0, s23
	s_addc_u32 s49, s17, 0
	global_load_lds_dwordx4 v[214:215], off
	v_lshl_add_u64 v[216:217], s[48:49], 0, v[136:137]
	s_mov_b32 m0, s24
	v_lshl_add_u64 v[218:219], s[18:19], 0, v[134:135]
	global_load_lds_dwordx4 v[216:217], off
	v_lshl_add_u64 v[216:217], s[48:49], 0, v[132:133]
	s_mov_b32 m0, s25
	s_nop 0
	global_load_lds_dwordx4 v[216:217], off
	v_lshl_add_u64 v[216:217], s[18:19], 0, v[138:139]
	s_mov_b32 m0, s20
	s_nop 0
	global_load_lds_dwordx4 v[216:217], off
	s_mov_b32 m0, s26
	s_nop 0
	global_load_lds_dwordx4 v[218:219], off
	s_waitcnt vmcnt(8)
	s_waitcnt lgkmcnt(0)
	s_barrier
; #define PG8_STAGE(bufoff, gbase, voff) do { _Pragma("unroll") for (int _i = 0; _i < 2; ++_i) \
;         __builtin_amdgcn_global_load_lds((const unsigned*)((const char*)(gbase) + (voff)[_i]), (LAS unsigned*)(lds + (bufoff) + ldsw + _i * 8192), 16, 0, 0); } while (0)
; #define PG8_LDA(dst, b, h) do { _Pragma("unroll") for (int m = 0; m < 4; ++m) _Pragma("unroll") for (int k = 0; k < 2; ++k) dst[m][k] = *(const LAS bf16x8*)(pA + PG8_SA(b, h) + m * 2048 + k * 1024); } while (0)
; #define PG8_LDB(dst, b, h) do { _Pragma("unroll") for (int n = 0; n < 2; ++n) _Pragma("unroll") for (int k = 0; k < 2; ++k) dst[n][k] = *(const LAS bf16x8*)(pB + (PG8_SB(b, h) - 4 * HTB) + n * 2048 + k * 1024); } while (0)
; #define PG8_MMA(ai, bj, At, Bt) do { __builtin_amdgcn_s_setprio(1); _Pragma("unroll") for (int m = 0; m < 4; ++m) _Pragma("unroll") for (int n = 0; n < 2; ++n) _Pragma("unroll") for (int k = 0; k < 2; ++k) \
;         acc[ai][bj][m][n] = __builtin_amdgcn_mfma_f32_16x16x32_bf16(Bt[n][k], At[m][k], acc[ai][bj][m][n], 0, 0, 0); __builtin_amdgcn_s_setprio(0); } while (0)
; #define PG8_WAIT_V(n) asm volatile("s_waitcnt vmcnt(" #n ")" ::: "memory")
; #define PG8_WAIT_L(n) asm volatile("s_waitcnt lgkmcnt(" #n ")" ::: "memory")
; #define PG8_BAR __builtin_amdgcn_s_barrier()
; #define PG8_SCHED __builtin_amdgcn_sched_barrier(0)
; template <class Desc, class Epi, bool ALIGN_EPI>
; __device__ __forceinline__ void gemm_phase(LAS unsigned char* lds, const Desc& D, const Epi& E, int G, int c) {
;     ...
;             PG8_WAIT_V(8); PG8_WAIT_L(0); PG8_BAR; PG8_MMA(1, 0, At, B0); PG8_MMA(1, 1, At, B1); PG8_BAR; PG8_SCHED;
;             PG8_LDB(B0, 1, 0); PG8_LDB(B1, 1, 1); PG8_SCHED; PG8_LDA(At, 1, 0); PG8_STAGE(PG8_SA(0, 1), a2 + hstepA, voffA);
;             PG8_WAIT_V(8); PG8_WAIT_L(0); PG8_BAR; PG8_MMA(0, 0, At, B0); PG8_MMA(0, 1, At, B1); PG8_BAR; PG8_SCHED;
	v_mfma_f32_16x16x32_bf16 v[64:67], v[144:147], v[180:183], v[64:67]
	v_mfma_f32_16x16x32_bf16 v[64:67], v[152:155], v[184:187], v[64:67]
	v_mfma_f32_16x16x32_bf16 v[60:63], v[156:159], v[180:183], v[60:63]
	v_mfma_f32_16x16x32_bf16 v[60:63], v[160:163], v[184:187], v[60:63]
	v_mfma_f32_16x16x32_bf16 v[56:59], v[164:167], v[180:183], v[56:59]
	v_mfma_f32_16x16x32_bf16 v[56:59], v[168:171], v[184:187], v[56:59]
	v_mfma_f32_16x16x32_bf16 v[48:51], v[172:175], v[180:183], v[48:51]
	v_mfma_f32_16x16x32_bf16 v[48:51], v[176:179], v[184:187], v[48:51]
	v_mfma_f32_16x16x32_bf16 v[32:35], v[172:175], v[188:191], v[32:35]
	v_mfma_f32_16x16x32_bf16 v[32:35], v[176:179], v[192:195], v[32:35]
	v_mfma_f32_16x16x32_bf16 v[40:43], v[164:167], v[188:191], v[40:43]
	v_mfma_f32_16x16x32_bf16 v[40:43], v[168:171], v[192:195], v[40:43]
	v_mfma_f32_16x16x32_bf16 v[44:47], v[156:159], v[188:191], v[44:47]
	v_mfma_f32_16x16x32_bf16 v[44:47], v[160:163], v[192:195], v[44:47]
	v_mfma_f32_16x16x32_bf16 v[52:55], v[144:147], v[188:191], v[52:55]
	v_mfma_f32_16x16x32_bf16 v[52:55], v[152:155], v[192:195], v[52:55]
	v_mfma_f32_16x16x32_bf16 v[36:39], v[144:147], v[196:199], v[36:39]
	v_mfma_f32_16x16x32_bf16 v[36:39], v[152:155], v[200:203], v[36:39]
	v_mfma_f32_16x16x32_bf16 v[28:31], v[156:159], v[196:199], v[28:31]
	v_mfma_f32_16x16x32_bf16 v[28:31], v[160:163], v[200:203], v[28:31]
	v_mfma_f32_16x16x32_bf16 v[24:27], v[164:167], v[196:199], v[24:27]
	v_mfma_f32_16x16x32_bf16 v[24:27], v[168:171], v[200:203], v[24:27]
	v_mfma_f32_16x16x32_bf16 v[16:19], v[172:175], v[196:199], v[16:19]
	v_mfma_f32_16x16x32_bf16 v[16:19], v[176:179], v[200:203], v[16:19]
	v_mfma_f32_16x16x32_bf16 v[4:7], v[172:175], v[204:207], v[4:7]
	v_mfma_f32_16x16x32_bf16 v[4:7], v[176:179], v[208:211], v[4:7]
	v_mfma_f32_16x16x32_bf16 v[8:11], v[164:167], v[204:207], v[8:11]
	v_mfma_f32_16x16x32_bf16 v[8:11], v[168:171], v[208:211], v[8:11]
	v_mfma_f32_16x16x32_bf16 v[12:15], v[156:159], v[204:207], v[12:15]
	v_mfma_f32_16x16x32_bf16 v[12:15], v[160:163], v[208:211], v[12:15]
	v_mfma_f32_16x16x32_bf16 v[20:23], v[144:147], v[204:207], v[20:23]
	v_mfma_f32_16x16x32_bf16 v[20:23], v[152:155], v[208:211], v[20:23]
	s_barrier
	ds_read_b128 v[144:147], v149 offset:32768
	ds_read_b128 v[152:155], v149 offset:33792
	ds_read_b128 v[156:159], v149 offset:34816
	ds_read_b128 v[160:163], v149 offset:35840
	ds_read_b128 v[164:167], v149 offset:49152
	ds_read_b128 v[168:171], v149 offset:50176
	ds_read_b128 v[172:175], v149 offset:51200
	ds_read_b128 v[176:179], v149 offset:52224
	s_add_u32 s18, s18, 0x80000
	s_addc_u32 s19, s19, 0
	s_mov_b32 m0, s27
	v_lshl_add_u64 v[220:221], s[18:19], 0, v[138:139]
	ds_read_b128 v[180:183], v148 offset:32768
	ds_read_b128 v[184:187], v148 offset:33792
	ds_read_b128 v[188:191], v148 offset:34816
	ds_read_b128 v[192:195], v148 offset:35840
	ds_read_b128 v[196:199], v148 offset:36864
	ds_read_b128 v[200:203], v148 offset:37888
	ds_read_b128 v[204:207], v148 offset:38912
	ds_read_b128 v[208:211], v148 offset:39936
	global_load_lds_dwordx4 v[220:221], off
	v_lshl_add_u64 v[220:221], s[18:19], 0, v[134:135]
	s_mov_b32 m0, s30
	s_nop 0
	global_load_lds_dwordx4 v[220:221], off
	s_waitcnt vmcnt(8)
	s_waitcnt lgkmcnt(0)
	s_barrier
	v_mfma_f32_16x16x32_bf16 v[128:131], v[144:147], v[180:183], v[128:131]
	v_mfma_f32_16x16x32_bf16 v[128:131], v[152:155], v[184:187], v[128:131]
	v_mfma_f32_16x16x32_bf16 v[124:127], v[156:159], v[180:183], v[124:127]
	v_mfma_f32_16x16x32_bf16 v[124:127], v[160:163], v[184:187], v[124:127]
	v_mfma_f32_16x16x32_bf16 v[120:123], v[164:167], v[180:183], v[120:123]
	v_mfma_f32_16x16x32_bf16 v[120:123], v[168:171], v[184:187], v[120:123]
	v_mfma_f32_16x16x32_bf16 v[112:115], v[172:175], v[180:183], v[112:115]
	v_mfma_f32_16x16x32_bf16 v[112:115], v[176:179], v[184:187], v[112:115]
	v_mfma_f32_16x16x32_bf16 v[96:99], v[172:175], v[188:191], v[96:99]
	v_mfma_f32_16x16x32_bf16 v[96:99], v[176:179], v[192:195], v[96:99]
	v_mfma_f32_16x16x32_bf16 v[104:107], v[164:167], v[188:191], v[104:107]
	v_mfma_f32_16x16x32_bf16 v[104:107], v[168:171], v[192:195], v[104:107]
	v_mfma_f32_16x16x32_bf16 v[108:111], v[156:159], v[188:191], v[108:111]
	v_mfma_f32_16x16x32_bf16 v[108:111], v[160:163], v[192:195], v[108:111]
	v_mfma_f32_16x16x32_bf16 v[116:119], v[144:147], v[188:191], v[116:119]
	v_mfma_f32_16x16x32_bf16 v[116:119], v[152:155], v[192:195], v[116:119]
	v_mfma_f32_16x16x32_bf16 v[100:103], v[144:147], v[196:199], v[100:103]
	v_mfma_f32_16x16x32_bf16 v[100:103], v[152:155], v[200:203], v[100:103]
	v_mfma_f32_16x16x32_bf16 v[92:95], v[156:159], v[196:199], v[92:95]
	v_mfma_f32_16x16x32_bf16 v[92:95], v[160:163], v[200:203], v[92:95]
	v_mfma_f32_16x16x32_bf16 v[88:91], v[164:167], v[196:199], v[88:91]
	v_mfma_f32_16x16x32_bf16 v[88:91], v[168:171], v[200:203], v[88:91]
	v_mfma_f32_16x16x32_bf16 v[80:83], v[172:175], v[196:199], v[80:83]
	v_mfma_f32_16x16x32_bf16 v[80:83], v[176:179], v[200:203], v[80:83]
	v_mfma_f32_16x16x32_bf16 v[68:71], v[172:175], v[204:207], v[68:71]
	v_mfma_f32_16x16x32_bf16 v[68:71], v[176:179], v[208:211], v[68:71]
	v_mfma_f32_16x16x32_bf16 v[72:75], v[164:167], v[204:207], v[72:75]
	v_mfma_f32_16x16x32_bf16 v[72:75], v[168:171], v[208:211], v[72:75]
	v_mfma_f32_16x16x32_bf16 v[76:79], v[156:159], v[204:207], v[76:79]
	v_mfma_f32_16x16x32_bf16 v[76:79], v[160:163], v[208:211], v[76:79]
	v_mfma_f32_16x16x32_bf16 v[84:87], v[144:147], v[204:207], v[84:87]
	v_mfma_f32_16x16x32_bf16 v[84:87], v[152:155], v[208:211], v[84:87]
	s_barrier
; #define PG8_STAGE(bufoff, gbase, voff) do { _Pragma("unroll") for (int _i = 0; _i < 2; ++_i) \
;         __builtin_amdgcn_global_load_lds((const unsigned*)((const char*)(gbase) + (voff)[_i]), (LAS unsigned*)(lds + (bufoff) + ldsw + _i * 8192), 16, 0, 0); } while (0)
; #define PG8_LDA(dst, b, h) do { _Pragma("unroll") for (int m = 0; m < 4; ++m) _Pragma("unroll") for (int k = 0; k < 2; ++k) dst[m][k] = *(const LAS bf16x8*)(pA + PG8_SA(b, h) + m * 2048 + k * 1024); } while (0)
; #define PG8_MMA(ai, bj, At, Bt) do { __builtin_amdgcn_s_setprio(1); _Pragma("unroll") for (int m = 0; m < 4; ++m) _Pragma("unroll") for (int n = 0; n < 2; ++n) _Pragma("unroll") for (int k = 0; k < 2; ++k) \
;         acc[ai][bj][m][n] = __builtin_amdgcn_mfma_f32_16x16x32_bf16(Bt[n][k], At[m][k], acc[ai][bj][m][n], 0, 0, 0); __builtin_amdgcn_s_setprio(0); } while (0)
; #define PG8_WAIT_V(n) asm volatile("s_waitcnt vmcnt(" #n ")" ::: "memory")
; #define PG8_WAIT_L(n) asm volatile("s_waitcnt lgkmcnt(" #n ")" ::: "memory")
; #define PG8_BAR __builtin_amdgcn_s_barrier()
; #define PG8_SCHED __builtin_amdgcn_sched_barrier(0)
; template <class Desc, class Epi, bool ALIGN_EPI>
; __device__ __forceinline__ void gemm_phase(LAS unsigned char* lds, const Desc& D, const Epi& E, int G, int c) {
;     ...
;             PG8_LDA(At, 1, 1); PG8_STAGE(PG8_SB(1, 0), b3, voffB); PG8_STAGE(PG8_SB(1, 1), b3 + hstepB, voffB); PG8_STAGE(PG8_SA(1, 0), a3, voffA);
;             PG8_WAIT_V(8); PG8_WAIT_L(0); PG8_BAR; PG8_MMA(1, 0, At, B0); PG8_MMA(1, 1, At, B1); PG8_BAR; PG8_SCHED;
;         }
;         if constexpr (ALIGN_EPI) { if (wr == 0) PG8_BAR; }
	s_mov_b32 m0, s31
	v_lshl_add_u64 v[212:213], v[212:213], 0, s[76:77]
	s_add_u32 s16, s16, 0x20080
	ds_read_b128 v[180:183], v148 offset:49152
	ds_read_b128 v[184:187], v148 offset:50176
	ds_read_b128 v[188:191], v148 offset:51200
	ds_read_b128 v[192:195], v148 offset:52224
	ds_read_b128 v[196:199], v148 offset:53248
	ds_read_b128 v[200:203], v148 offset:54272
	ds_read_b128 v[204:207], v148 offset:55296
	ds_read_b128 v[208:211], v148 offset:56320
	global_load_lds_dwordx4 v[212:213], off
	v_lshl_add_u64 v[212:213], v[214:215], 0, s[76:77]
	s_mov_b32 m0, s33
	s_addc_u32 s17, s17, 0
	global_load_lds_dwordx4 v[212:213], off
	v_lshl_add_u64 v[212:213], s[16:17], 0, v[136:137]
	s_mov_b32 m0, s38
	s_nop 0
	global_load_lds_dwordx4 v[212:213], off
	v_lshl_add_u64 v[212:213], s[16:17], 0, v[132:133]
	s_mov_b32 m0, s39
	s_nop 0
	global_load_lds_dwordx4 v[212:213], off
	v_lshl_add_u64 v[212:213], v[216:217], 0, s[76:77]
	s_mov_b32 m0, s34
	s_nop 0
	global_load_lds_dwordx4 v[212:213], off
	v_lshl_add_u64 v[212:213], v[218:219], 0, s[76:77]
	s_mov_b32 m0, s35
	s_nop 0
	global_load_lds_dwordx4 v[212:213], off
	s_waitcnt vmcnt(8)
	s_waitcnt lgkmcnt(0)
	s_barrier
	v_mfma_f32_16x16x32_bf16 v[64:67], v[144:147], v[180:183], v[64:67]
	v_mfma_f32_16x16x32_bf16 v[64:67], v[152:155], v[184:187], v[64:67]
	v_mfma_f32_16x16x32_bf16 v[60:63], v[156:159], v[180:183], v[60:63]
	v_mfma_f32_16x16x32_bf16 v[60:63], v[160:163], v[184:187], v[60:63]
	v_mfma_f32_16x16x32_bf16 v[56:59], v[164:167], v[180:183], v[56:59]
	v_mfma_f32_16x16x32_bf16 v[56:59], v[168:171], v[184:187], v[56:59]
	v_mfma_f32_16x16x32_bf16 v[48:51], v[172:175], v[180:183], v[48:51]
	v_mfma_f32_16x16x32_bf16 v[48:51], v[176:179], v[184:187], v[48:51]
	v_mfma_f32_16x16x32_bf16 v[32:35], v[172:175], v[188:191], v[32:35]
	v_mfma_f32_16x16x32_bf16 v[32:35], v[176:179], v[192:195], v[32:35]
	v_mfma_f32_16x16x32_bf16 v[40:43], v[164:167], v[188:191], v[40:43]
	v_mfma_f32_16x16x32_bf16 v[40:43], v[168:171], v[192:195], v[40:43]
	v_mfma_f32_16x16x32_bf16 v[44:47], v[156:159], v[188:191], v[44:47]
	v_mfma_f32_16x16x32_bf16 v[44:47], v[160:163], v[192:195], v[44:47]
	v_mfma_f32_16x16x32_bf16 v[52:55], v[144:147], v[188:191], v[52:55]
	v_mfma_f32_16x16x32_bf16 v[52:55], v[152:155], v[192:195], v[52:55]
	v_mfma_f32_16x16x32_bf16 v[36:39], v[144:147], v[196:199], v[36:39]
	v_mfma_f32_16x16x32_bf16 v[36:39], v[152:155], v[200:203], v[36:39]
	v_mfma_f32_16x16x32_bf16 v[28:31], v[156:159], v[196:199], v[28:31]
	v_mfma_f32_16x16x32_bf16 v[28:31], v[160:163], v[200:203], v[28:31]
	v_mfma_f32_16x16x32_bf16 v[24:27], v[164:167], v[196:199], v[24:27]
	v_mfma_f32_16x16x32_bf16 v[24:27], v[168:171], v[200:203], v[24:27]
	v_mfma_f32_16x16x32_bf16 v[16:19], v[172:175], v[196:199], v[16:19]
	v_mfma_f32_16x16x32_bf16 v[16:19], v[176:179], v[200:203], v[16:19]
	v_mfma_f32_16x16x32_bf16 v[4:7], v[172:175], v[204:207], v[4:7]
	v_mfma_f32_16x16x32_bf16 v[4:7], v[176:179], v[208:211], v[4:7]
	v_mfma_f32_16x16x32_bf16 v[8:11], v[164:167], v[204:207], v[8:11]
	v_mfma_f32_16x16x32_bf16 v[8:11], v[168:171], v[208:211], v[8:11]
	v_mfma_f32_16x16x32_bf16 v[12:15], v[156:159], v[204:207], v[12:15]
	v_mfma_f32_16x16x32_bf16 v[12:15], v[160:163], v[208:211], v[12:15]
	v_mfma_f32_16x16x32_bf16 v[20:23], v[144:147], v[204:207], v[20:23]
	v_mfma_f32_16x16x32_bf16 v[20:23], v[152:155], v[208:211], v[20:23]
	s_barrier
	s_add_i32 s46, s46, 2
	s_add_u32 s12, s12, 0x100
	s_addc_u32 s13, s13, 0
	s_add_u32 s7, s7, 0x100
	s_addc_u32 s45, s45, 0
	s_cmp_gt_u32 s46, 5
	s_cbranch_scc0 .LBB0_603
	v_readlane_b32 s46, v255, 36
	s_and_b64 vcc, exec, s[4:5]
	v_readlane_b32 s47, v255, 37
	s_cbranch_vccz .LBB0_606
	s_barrier

;     __device__ __forceinline__ int nt(const Unit& u) const { return (u.pn >> 1) < 2 ? 22 : 20; }
; #define PG8_STAGE(bufoff, gbase, voff) do { _Pragma("unroll") for (int _i = 0; _i < 2; ++_i) \
;         __builtin_amdgcn_global_load_lds((const unsigned*)((const char*)(gbase) + (voff)[_i]), (LAS unsigned*)(lds + (bufoff) + ldsw + _i * 8192), 16, 0, 0); } while (0)
; #define PG8_LDA(dst, b, h) do { _Pragma("unroll") for (int m = 0; m < 4; ++m) _Pragma("unroll") for (int k = 0; k < 2; ++k) dst[m][k] = *(const LAS bf16x8*)(pA + PG8_SA(b, h) + m * 2048 + k * 1024); } while (0)
; #define PG8_LDB(dst, b, h) do { _Pragma("unroll") for (int n = 0; n < 2; ++n) _Pragma("unroll") for (int k = 0; k < 2; ++k) dst[n][k] = *(const LAS bf16x8*)(pB + (PG8_SB(b, h) - 4 * HTB) + n * 2048 + k * 1024); } while (0)
; #define PG8_MMA(ai, bj, At, Bt) do { __builtin_amdgcn_s_setprio(1); _Pragma("unroll") for (int m = 0; m < 4; ++m) _Pragma("unroll") for (int n = 0; n < 2; ++n) _Pragma("unroll") for (int k = 0; k < 2; ++k) \
;         acc[ai][bj][m][n] = __builtin_amdgcn_mfma_f32_16x16x32_bf16(Bt[n][k], At[m][k], acc[ai][bj][m][n], 0, 0, 0); __builtin_amdgcn_s_setprio(0); } while (0)
; #define PG8_WAIT_V(n) asm volatile("s_waitcnt vmcnt(" #n ")" ::: "memory")
; #define PG8_WAIT_L(n) asm volatile("s_waitcnt lgkmcnt(" #n ")" ::: "memory")
; #define PG8_BAR __builtin_amdgcn_s_barrier()
; template <class Desc, class Epi, bool ALIGN_EPI>
; __device__ __forceinline__ void gemm_phase(LAS unsigned char* lds, const Desc& D, const Epi& E, int G, int c) {
;     ...
;         for (int t = 0; t < nt; t += 2) {
;             const bool last = (t == nt - 2);
;             if (last && has_next) PG8_AWAIT(nxt);
;             const char* a1 = cA + (size_t)(t + 1) * kstep;
;             const char* a2 = last ? nA : cA + (size_t)(t + 2) * kstep; const char* b2 = last ? nB : cB + (size_t)(t + 2) * kstep;
;             const char* a3 = a2 + kstep; const char* b3 = b2 + kstep;
;             PG8_LDB(B0, 0, 0); PG8_LDB(B1, 0, 1); PG8_SCHED; PG8_LDA(At, 0, 0); PG8_STAGE(PG8_SA(1, 1), a1 + hstepA, voffA);
;             PG8_WAIT_V(8); PG8_WAIT_L(0); PG8_BAR; PG8_MMA(0, 0, At, B0); PG8_MMA(0, 1, At, B1); PG8_BAR; PG8_SCHED;
;             PG8_LDA(At, 0, 1); PG8_STAGE(PG8_SB(0, 0), b2, voffB); PG8_STAGE(PG8_SB(0, 1), b2 + hstepB, voffB); PG8_STAGE(PG8_SA(0, 0), a2, voffA);
.LBB0_1164:
	s_waitcnt lgkmcnt(0)
	ds_read_b128 v[132:135], v229
	ds_read_b128 v[136:139], v229 offset:1024
	ds_read_b128 v[140:143], v229 offset:2048
	ds_read_b128 v[144:147], v229 offset:3072
	ds_read_b128 v[148:151], v229 offset:16384
	ds_read_b128 v[152:155], v229 offset:17408
	ds_read_b128 v[156:159], v229 offset:18432
	ds_read_b128 v[160:163], v229 offset:19456
	s_add_i32 s20, s14, 2
	s_add_u32 s16, s12, 0xfff00080
	s_addc_u32 s17, s13, -1
	s_cmp_eq_u32 s1, s14
	s_cselect_b32 s19, s39, s17
	s_cselect_b32 s18, s38, s16
	s_cselect_b32 s17, s41, s11
	s_cselect_b32 s16, s40, s3
	v_lshl_add_u64 v[208:209], s[12:13], 0, v[204:205]
	s_add_i32 m0, s35, 0xc000
	ds_read_b128 v[164:167], v228
	ds_read_b128 v[168:171], v228 offset:1024
	ds_read_b128 v[172:175], v228 offset:2048
	ds_read_b128 v[176:179], v228 offset:3072
	ds_read_b128 v[180:183], v228 offset:4096
	ds_read_b128 v[184:187], v228 offset:5120
	ds_read_b128 v[188:191], v228 offset:6144
	ds_read_b128 v[192:195], v228 offset:7168
	global_load_lds_dwordx4 v[208:209], off
	v_lshl_add_u64 v[208:209], s[12:13], 0, v[206:207]
	s_add_i32 m0, s35, 0xe000
	s_nop 0
	global_load_lds_dwordx4 v[208:209], off
	s_waitcnt vmcnt(8)
	s_waitcnt lgkmcnt(0)
	s_barrier
	v_mfma_f32_16x16x32_bf16 v[128:131], v[132:135], v[164:167], v[128:131]
	v_mfma_f32_16x16x32_bf16 v[128:131], v[136:139], v[168:171], v[128:131]
	v_mfma_f32_16x16x32_bf16 v[124:127], v[140:143], v[164:167], v[124:127]
	v_mfma_f32_16x16x32_bf16 v[124:127], v[144:147], v[168:171], v[124:127]
	v_mfma_f32_16x16x32_bf16 v[96:99], v[148:151], v[164:167], v[96:99]
	v_mfma_f32_16x16x32_bf16 v[96:99], v[152:155], v[168:171], v[96:99]
	v_mfma_f32_16x16x32_bf16 v[92:95], v[156:159], v[164:167], v[92:95]
	v_mfma_f32_16x16x32_bf16 v[92:95], v[160:163], v[168:171], v[92:95]
	v_mfma_f32_16x16x32_bf16 v[80:83], v[156:159], v[172:175], v[80:83]
	v_mfma_f32_16x16x32_bf16 v[80:83], v[160:163], v[176:179], v[80:83]
	v_mfma_f32_16x16x32_bf16 v[88:91], v[148:151], v[172:175], v[88:91]
	v_mfma_f32_16x16x32_bf16 v[88:91], v[152:155], v[176:179], v[88:91]
	v_mfma_f32_16x16x32_bf16 v[116:119], v[140:143], v[172:175], v[116:119]
	v_mfma_f32_16x16x32_bf16 v[116:119], v[144:147], v[176:179], v[116:119]
	v_mfma_f32_16x16x32_bf16 v[120:123], v[132:135], v[172:175], v[120:123]
	v_mfma_f32_16x16x32_bf16 v[120:123], v[136:139], v[176:179], v[120:123]
	v_mfma_f32_16x16x32_bf16 v[112:115], v[132:135], v[180:183], v[112:115]
	v_mfma_f32_16x16x32_bf16 v[112:115], v[136:139], v[184:187], v[112:115]
	v_mfma_f32_16x16x32_bf16 v[108:111], v[140:143], v[180:183], v[108:111]
	v_mfma_f32_16x16x32_bf16 v[108:111], v[144:147], v[184:187], v[108:111]
	v_mfma_f32_16x16x32_bf16 v[64:67], v[148:151], v[180:183], v[64:67]
	v_mfma_f32_16x16x32_bf16 v[64:67], v[152:155], v[184:187], v[64:67]
	v_mfma_f32_16x16x32_bf16 v[52:55], v[156:159], v[180:183], v[52:55]
	v_mfma_f32_16x16x32_bf16 v[52:55], v[160:163], v[184:187], v[52:55]
	v_mfma_f32_16x16x32_bf16 v[20:23], v[156:159], v[188:191], v[20:23]
	v_mfma_f32_16x16x32_bf16 v[20:23], v[160:163], v[192:195], v[20:23]
	v_mfma_f32_16x16x32_bf16 v[32:35], v[148:151], v[188:191], v[32:35]
	v_mfma_f32_16x16x32_bf16 v[32:35], v[152:155], v[192:195], v[32:35]
	v_mfma_f32_16x16x32_bf16 v[100:103], v[140:143], v[188:191], v[100:103]
	v_mfma_f32_16x16x32_bf16 v[100:103], v[144:147], v[192:195], v[100:103]
	v_mfma_f32_16x16x32_bf16 v[104:107], v[132:135], v[188:191], v[104:107]
	v_mfma_f32_16x16x32_bf16 v[104:107], v[136:139], v[192:195], v[104:107]
	s_barrier
	s_mov_b32 m0, s44
	v_lshl_add_u64 v[208:209], s[16:17], 0, v[198:199]
	s_add_u32 s62, s16, 0x100000
	ds_read_b128 v[164:167], v228 offset:16384
	ds_read_b128 v[168:171], v228 offset:17408
	ds_read_b128 v[172:175], v228 offset:18432
	ds_read_b128 v[176:179], v228 offset:19456
	ds_read_b128 v[180:183], v228 offset:20480
	ds_read_b128 v[184:187], v228 offset:21504
	ds_read_b128 v[188:191], v228 offset:22528
	ds_read_b128 v[192:195], v228 offset:23552
	global_load_lds_dwordx4 v[208:209], off
	v_lshl_add_u64 v[210:211], s[16:17], 0, v[202:203]
	s_mov_b32 m0, s45
	s_addc_u32 s63, s17, 0
	global_load_lds_dwordx4 v[210:211], off
	v_lshl_add_u64 v[212:213], s[62:63], 0, v[198:199]
	s_mov_b32 m0, s46
	v_lshl_add_u64 v[214:215], s[18:19], 0, v[200:201]
	global_load_lds_dwordx4 v[212:213], off
	v_lshl_add_u64 v[212:213], s[62:63], 0, v[202:203]
	s_mov_b32 m0, s47
	s_nop 0
	global_load_lds_dwordx4 v[212:213], off
	v_lshl_add_u64 v[212:213], s[18:19], 0, v[196:197]
	s_mov_b32 m0, s35
	s_nop 0
	global_load_lds_dwordx4 v[212:213], off
	s_mov_b32 m0, s48
	s_nop 0
	global_load_lds_dwordx4 v[214:215], off
	s_waitcnt vmcnt(8)
	s_waitcnt lgkmcnt(0)
	s_barrier
; #define PG8_STAGE(bufoff, gbase, voff) do { _Pragma("unroll") for (int _i = 0; _i < 2; ++_i) \
;         __builtin_amdgcn_global_load_lds((const unsigned*)((const char*)(gbase) + (voff)[_i]), (LAS unsigned*)(lds + (bufoff) + ldsw + _i * 8192), 16, 0, 0); } while (0)
; #define PG8_LDA(dst, b, h) do { _Pragma("unroll") for (int m = 0; m < 4; ++m) _Pragma("unroll") for (int k = 0; k < 2; ++k) dst[m][k] = *(const LAS bf16x8*)(pA + PG8_SA(b, h) + m * 2048 + k * 1024); } while (0)
; #define PG8_LDB(dst, b, h) do { _Pragma("unroll") for (int n = 0; n < 2; ++n) _Pragma("unroll") for (int k = 0; k < 2; ++k) dst[n][k] = *(const LAS bf16x8*)(pB + (PG8_SB(b, h) - 4 * HTB) + n * 2048 + k * 1024); } while (0)
; #define PG8_MMA(ai, bj, At, Bt) do { __builtin_amdgcn_s_setprio(1); _Pragma("unroll") for (int m = 0; m < 4; ++m) _Pragma("unroll") for (int n = 0; n < 2; ++n) _Pragma("unroll") for (int k = 0; k < 2; ++k) \
;         acc[ai][bj][m][n] = __builtin_amdgcn_mfma_f32_16x16x32_bf16(Bt[n][k], At[m][k], acc[ai][bj][m][n], 0, 0, 0); __builtin_amdgcn_s_setprio(0); } while (0)
; #define PG8_WAIT_V(n) asm volatile("s_waitcnt vmcnt(" #n ")" ::: "memory")
; #define PG8_WAIT_L(n) asm volatile("s_waitcnt lgkmcnt(" #n ")" ::: "memory")
; #define PG8_BAR __builtin_amdgcn_s_barrier()
; #define PG8_SCHED __builtin_amdgcn_sched_barrier(0)
; template <class Desc, class Epi, bool ALIGN_EPI>
; __device__ __forceinline__ void gemm_phase(LAS unsigned char* lds, const Desc& D, const Epi& E, int G, int c) {
;     ...
;             PG8_WAIT_V(8); PG8_WAIT_L(0); PG8_BAR; PG8_MMA(1, 0, At, B0); PG8_MMA(1, 1, At, B1); PG8_BAR; PG8_SCHED;
;             PG8_LDB(B0, 1, 0); PG8_LDB(B1, 1, 1); PG8_SCHED; PG8_LDA(At, 1, 0); PG8_STAGE(PG8_SA(0, 1), a2 + hstepA, voffA);
;             PG8_WAIT_V(8); PG8_WAIT_L(0); PG8_BAR; PG8_MMA(0, 0, At, B0); PG8_MMA(0, 1, At, B1); PG8_BAR; PG8_SCHED;
	v_mfma_f32_16x16x32_bf16 v[84:87], v[132:135], v[164:167], v[84:87]
	v_mfma_f32_16x16x32_bf16 v[84:87], v[136:139], v[168:171], v[84:87]
	v_mfma_f32_16x16x32_bf16 v[76:79], v[140:143], v[164:167], v[76:79]
	v_mfma_f32_16x16x32_bf16 v[76:79], v[144:147], v[168:171], v[76:79]
	v_mfma_f32_16x16x32_bf16 v[40:43], v[148:151], v[164:167], v[40:43]
	v_mfma_f32_16x16x32_bf16 v[40:43], v[152:155], v[168:171], v[40:43]
	v_mfma_f32_16x16x32_bf16 v[36:39], v[156:159], v[164:167], v[36:39]
	v_mfma_f32_16x16x32_bf16 v[36:39], v[160:163], v[168:171], v[36:39]
	v_mfma_f32_16x16x32_bf16 v[24:27], v[156:159], v[172:175], v[24:27]
	v_mfma_f32_16x16x32_bf16 v[24:27], v[160:163], v[176:179], v[24:27]
	v_mfma_f32_16x16x32_bf16 v[28:31], v[148:151], v[172:175], v[28:31]
	v_mfma_f32_16x16x32_bf16 v[28:31], v[152:155], v[176:179], v[28:31]
	v_mfma_f32_16x16x32_bf16 v[68:71], v[140:143], v[172:175], v[68:71]
	v_mfma_f32_16x16x32_bf16 v[68:71], v[144:147], v[176:179], v[68:71]
	v_mfma_f32_16x16x32_bf16 v[72:75], v[132:135], v[172:175], v[72:75]
	v_mfma_f32_16x16x32_bf16 v[72:75], v[136:139], v[176:179], v[72:75]
	v_mfma_f32_16x16x32_bf16 v[60:63], v[132:135], v[180:183], v[60:63]
	v_mfma_f32_16x16x32_bf16 v[60:63], v[136:139], v[184:187], v[60:63]
	v_mfma_f32_16x16x32_bf16 v[56:59], v[140:143], v[180:183], v[56:59]
	v_mfma_f32_16x16x32_bf16 v[56:59], v[144:147], v[184:187], v[56:59]
	v_mfma_f32_16x16x32_bf16 v[16:19], v[148:151], v[180:183], v[16:19]
	v_mfma_f32_16x16x32_bf16 v[16:19], v[152:155], v[184:187], v[16:19]
	v_mfma_f32_16x16x32_bf16 v[12:15], v[156:159], v[180:183], v[12:15]
	v_mfma_f32_16x16x32_bf16 v[12:15], v[160:163], v[184:187], v[12:15]
	v_mfma_f32_16x16x32_bf16 v[4:7], v[156:159], v[188:191], v[4:7]
	v_mfma_f32_16x16x32_bf16 v[4:7], v[160:163], v[192:195], v[4:7]
	v_mfma_f32_16x16x32_bf16 v[8:11], v[148:151], v[188:191], v[8:11]
	v_mfma_f32_16x16x32_bf16 v[8:11], v[152:155], v[192:195], v[8:11]
	v_mfma_f32_16x16x32_bf16 v[44:47], v[140:143], v[188:191], v[44:47]
	v_mfma_f32_16x16x32_bf16 v[44:47], v[144:147], v[192:195], v[44:47]
	v_mfma_f32_16x16x32_bf16 v[48:51], v[132:135], v[188:191], v[48:51]
	v_mfma_f32_16x16x32_bf16 v[48:51], v[136:139], v[192:195], v[48:51]
	s_barrier
	ds_read_b128 v[132:135], v229 offset:32768
	ds_read_b128 v[136:139], v229 offset:33792
	ds_read_b128 v[140:143], v229 offset:34816
	ds_read_b128 v[144:147], v229 offset:35840
	ds_read_b128 v[148:151], v229 offset:49152
	ds_read_b128 v[152:155], v229 offset:50176
	ds_read_b128 v[156:159], v229 offset:51200
	ds_read_b128 v[160:163], v229 offset:52224
	s_add_u32 s18, s18, 0x100000
	s_addc_u32 s19, s19, 0
	s_mov_b32 m0, s49
	v_lshl_add_u64 v[216:217], s[18:19], 0, v[196:197]
	ds_read_b128 v[164:167], v228 offset:32768
	ds_read_b128 v[168:171], v228 offset:33792
	ds_read_b128 v[172:175], v228 offset:34816
	ds_read_b128 v[176:179], v228 offset:35840
	ds_read_b128 v[180:183], v228 offset:36864
	ds_read_b128 v[184:187], v228 offset:37888
	ds_read_b128 v[188:191], v228 offset:38912
	ds_read_b128 v[192:195], v228 offset:39936
	global_load_lds_dwordx4 v[216:217], off
	v_lshl_add_u64 v[216:217], s[18:19], 0, v[200:201]
	s_mov_b32 m0, s50
	s_nop 0
	global_load_lds_dwordx4 v[216:217], off
	s_waitcnt vmcnt(8)
	s_waitcnt lgkmcnt(0)
	s_barrier
	v_mfma_f32_16x16x32_bf16 v[128:131], v[132:135], v[164:167], v[128:131]
	v_mfma_f32_16x16x32_bf16 v[128:131], v[136:139], v[168:171], v[128:131]
	v_mfma_f32_16x16x32_bf16 v[124:127], v[140:143], v[164:167], v[124:127]
	v_mfma_f32_16x16x32_bf16 v[124:127], v[144:147], v[168:171], v[124:127]
	v_mfma_f32_16x16x32_bf16 v[96:99], v[148:151], v[164:167], v[96:99]
	v_mfma_f32_16x16x32_bf16 v[96:99], v[152:155], v[168:171], v[96:99]
	v_mfma_f32_16x16x32_bf16 v[92:95], v[156:159], v[164:167], v[92:95]
	v_mfma_f32_16x16x32_bf16 v[92:95], v[160:163], v[168:171], v[92:95]
	v_mfma_f32_16x16x32_bf16 v[80:83], v[156:159], v[172:175], v[80:83]
	v_mfma_f32_16x16x32_bf16 v[80:83], v[160:163], v[176:179], v[80:83]
	v_mfma_f32_16x16x32_bf16 v[88:91], v[148:151], v[172:175], v[88:91]
	v_mfma_f32_16x16x32_bf16 v[88:91], v[152:155], v[176:179], v[88:91]
	v_mfma_f32_16x16x32_bf16 v[116:119], v[140:143], v[172:175], v[116:119]
	v_mfma_f32_16x16x32_bf16 v[116:119], v[144:147], v[176:179], v[116:119]
	v_mfma_f32_16x16x32_bf16 v[120:123], v[132:135], v[172:175], v[120:123]
	v_mfma_f32_16x16x32_bf16 v[120:123], v[136:139], v[176:179], v[120:123]
	v_mfma_f32_16x16x32_bf16 v[112:115], v[132:135], v[180:183], v[112:115]
	v_mfma_f32_16x16x32_bf16 v[112:115], v[136:139], v[184:187], v[112:115]
	v_mfma_f32_16x16x32_bf16 v[108:111], v[140:143], v[180:183], v[108:111]
	v_mfma_f32_16x16x32_bf16 v[108:111], v[144:147], v[184:187], v[108:111]
	v_mfma_f32_16x16x32_bf16 v[64:67], v[148:151], v[180:183], v[64:67]
	v_mfma_f32_16x16x32_bf16 v[64:67], v[152:155], v[184:187], v[64:67]
	v_mfma_f32_16x16x32_bf16 v[52:55], v[156:159], v[180:183], v[52:55]
	v_mfma_f32_16x16x32_bf16 v[52:55], v[160:163], v[184:187], v[52:55]
	v_mfma_f32_16x16x32_bf16 v[20:23], v[156:159], v[188:191], v[20:23]
	v_mfma_f32_16x16x32_bf16 v[20:23], v[160:163], v[192:195], v[20:23]
	v_mfma_f32_16x16x32_bf16 v[32:35], v[148:151], v[188:191], v[32:35]
	v_mfma_f32_16x16x32_bf16 v[32:35], v[152:155], v[192:195], v[32:35]
	v_mfma_f32_16x16x32_bf16 v[100:103], v[140:143], v[188:191], v[100:103]
	v_mfma_f32_16x16x32_bf16 v[100:103], v[144:147], v[192:195], v[100:103]
	v_mfma_f32_16x16x32_bf16 v[104:107], v[132:135], v[188:191], v[104:107]
	v_mfma_f32_16x16x32_bf16 v[104:107], v[136:139], v[192:195], v[104:107]
	s_barrier
; #define PG8_STAGE(bufoff, gbase, voff) do { _Pragma("unroll") for (int _i = 0; _i < 2; ++_i) \
;         __builtin_amdgcn_global_load_lds((const unsigned*)((const char*)(gbase) + (voff)[_i]), (LAS unsigned*)(lds + (bufoff) + ldsw + _i * 8192), 16, 0, 0); } while (0)
; #define PG8_LDA(dst, b, h) do { _Pragma("unroll") for (int m = 0; m < 4; ++m) _Pragma("unroll") for (int k = 0; k < 2; ++k) dst[m][k] = *(const LAS bf16x8*)(pA + PG8_SA(b, h) + m * 2048 + k * 1024); } while (0)
; #define PG8_MMA(ai, bj, At, Bt) do { __builtin_amdgcn_s_setprio(1); _Pragma("unroll") for (int m = 0; m < 4; ++m) _Pragma("unroll") for (int n = 0; n < 2; ++n) _Pragma("unroll") for (int k = 0; k < 2; ++k) \
;         acc[ai][bj][m][n] = __builtin_amdgcn_mfma_f32_16x16x32_bf16(Bt[n][k], At[m][k], acc[ai][bj][m][n], 0, 0, 0); __builtin_amdgcn_s_setprio(0); } while (0)
; #define PG8_WAIT_V(n) asm volatile("s_waitcnt vmcnt(" #n ")" ::: "memory")
; #define PG8_WAIT_L(n) asm volatile("s_waitcnt lgkmcnt(" #n ")" ::: "memory")
; #define PG8_BAR __builtin_amdgcn_s_barrier()
; #define PG8_SCHED __builtin_amdgcn_sched_barrier(0)
; template <class Desc, class Epi, bool ALIGN_EPI>
; __device__ __forceinline__ void gemm_phase(LAS unsigned char* lds, const Desc& D, const Epi& E, int G, int c) {
;     ...
;             PG8_LDA(At, 1, 1); PG8_STAGE(PG8_SB(1, 0), b3, voffB); PG8_STAGE(PG8_SB(1, 1), b3 + hstepB, voffB); PG8_STAGE(PG8_SA(1, 0), a3, voffA);
;             PG8_WAIT_V(8); PG8_WAIT_L(0); PG8_BAR; PG8_MMA(1, 0, At, B0); PG8_MMA(1, 1, At, B1); PG8_BAR; PG8_SCHED;
;         }
;         if constexpr (ALIGN_EPI) { if (wr == 0) PG8_BAR; }
	s_mov_b32 m0, s52
	v_lshl_add_u64 v[208:209], v[208:209], 0, s[76:77]
	s_add_u32 s16, s16, 0x100080
	ds_read_b128 v[164:167], v228 offset:49152
	ds_read_b128 v[168:171], v228 offset:50176
	ds_read_b128 v[172:175], v228 offset:51200
	ds_read_b128 v[176:179], v228 offset:52224
	ds_read_b128 v[180:183], v228 offset:53248
	ds_read_b128 v[184:187], v228 offset:54272
	ds_read_b128 v[188:191], v228 offset:55296
	ds_read_b128 v[192:195], v228 offset:56320
	global_load_lds_dwordx4 v[208:209], off
	v_lshl_add_u64 v[208:209], v[210:211], 0, s[76:77]
	s_mov_b32 m0, s53
	s_addc_u32 s17, s17, 0
	global_load_lds_dwordx4 v[208:209], off
	v_lshl_add_u64 v[208:209], s[16:17], 0, v[198:199]
	s_mov_b32 m0, s56
	s_nop 0
	global_load_lds_dwordx4 v[208:209], off
	v_lshl_add_u64 v[208:209], s[16:17], 0, v[202:203]
	s_mov_b32 m0, s57
	s_nop 0
	global_load_lds_dwordx4 v[208:209], off
	v_lshl_add_u64 v[208:209], v[212:213], 0, s[76:77]
	s_mov_b32 m0, s54
	s_nop 0
	global_load_lds_dwordx4 v[208:209], off
	v_lshl_add_u64 v[208:209], v[214:215], 0, s[76:77]
	s_mov_b32 m0, s55
	s_nop 0
	global_load_lds_dwordx4 v[208:209], off
	s_waitcnt vmcnt(8)
	s_waitcnt lgkmcnt(0)
	s_barrier
	v_mfma_f32_16x16x32_bf16 v[84:87], v[132:135], v[164:167], v[84:87]
	v_mfma_f32_16x16x32_bf16 v[84:87], v[136:139], v[168:171], v[84:87]
	v_mfma_f32_16x16x32_bf16 v[76:79], v[140:143], v[164:167], v[76:79]
	v_mfma_f32_16x16x32_bf16 v[76:79], v[144:147], v[168:171], v[76:79]
	v_mfma_f32_16x16x32_bf16 v[40:43], v[148:151], v[164:167], v[40:43]
	v_mfma_f32_16x16x32_bf16 v[40:43], v[152:155], v[168:171], v[40:43]
	v_mfma_f32_16x16x32_bf16 v[36:39], v[156:159], v[164:167], v[36:39]
	v_mfma_f32_16x16x32_bf16 v[36:39], v[160:163], v[168:171], v[36:39]
	v_mfma_f32_16x16x32_bf16 v[24:27], v[156:159], v[172:175], v[24:27]
	v_mfma_f32_16x16x32_bf16 v[24:27], v[160:163], v[176:179], v[24:27]
	v_mfma_f32_16x16x32_bf16 v[28:31], v[148:151], v[172:175], v[28:31]
	v_mfma_f32_16x16x32_bf16 v[28:31], v[152:155], v[176:179], v[28:31]
	v_mfma_f32_16x16x32_bf16 v[68:71], v[140:143], v[172:175], v[68:71]
	v_mfma_f32_16x16x32_bf16 v[68:71], v[144:147], v[176:179], v[68:71]
	v_mfma_f32_16x16x32_bf16 v[72:75], v[132:135], v[172:175], v[72:75]
	v_mfma_f32_16x16x32_bf16 v[72:75], v[136:139], v[176:179], v[72:75]
	v_mfma_f32_16x16x32_bf16 v[60:63], v[132:135], v[180:183], v[60:63]
	v_mfma_f32_16x16x32_bf16 v[60:63], v[136:139], v[184:187], v[60:63]
	v_mfma_f32_16x16x32_bf16 v[56:59], v[140:143], v[180:183], v[56:59]
	v_mfma_f32_16x16x32_bf16 v[56:59], v[144:147], v[184:187], v[56:59]
	v_mfma_f32_16x16x32_bf16 v[16:19], v[148:151], v[180:183], v[16:19]
	v_mfma_f32_16x16x32_bf16 v[16:19], v[152:155], v[184:187], v[16:19]
	v_mfma_f32_16x16x32_bf16 v[12:15], v[156:159], v[180:183], v[12:15]
	v_mfma_f32_16x16x32_bf16 v[12:15], v[160:163], v[184:187], v[12:15]
	v_mfma_f32_16x16x32_bf16 v[4:7], v[156:159], v[188:191], v[4:7]
	v_mfma_f32_16x16x32_bf16 v[4:7], v[160:163], v[192:195], v[4:7]
	v_mfma_f32_16x16x32_bf16 v[8:11], v[148:151], v[188:191], v[8:11]
	v_mfma_f32_16x16x32_bf16 v[8:11], v[152:155], v[192:195], v[8:11]
	v_mfma_f32_16x16x32_bf16 v[44:47], v[140:143], v[188:191], v[44:47]
	v_mfma_f32_16x16x32_bf16 v[44:47], v[144:147], v[192:195], v[44:47]
	v_mfma_f32_16x16x32_bf16 v[48:51], v[132:135], v[188:191], v[48:51]
	v_mfma_f32_16x16x32_bf16 v[48:51], v[136:139], v[192:195], v[48:51]
	s_barrier
	s_add_u32 s12, s12, 0x100
	s_addc_u32 s13, s13, 0
	s_add_u32 s3, s3, 0x100
	s_addc_u32 s11, s11, 0
	s_cmp_ge_u32 s20, s2
	s_mov_b32 s14, s20
	s_cbranch_scc0 .LBB0_1164
	s_and_b64 vcc, exec, s[8:9]
	s_cbranch_vccz .LBB0_1167
	s_barrier

;     __device__ __forceinline__ int nt(const Unit& u) const { return (u.pn >> 1) < 2 ? 22 : 20; }
; #define PG8_STAGE(bufoff, gbase, voff) do { _Pragma("unroll") for (int _i = 0; _i < 2; ++_i) \
;         __builtin_amdgcn_global_load_lds((const unsigned*)((const char*)(gbase) + (voff)[_i]), (LAS unsigned*)(lds + (bufoff) + ldsw + _i * 8192), 16, 0, 0); } while (0)
; #define PG8_LDA(dst, b, h) do { _Pragma("unroll") for (int m = 0; m < 4; ++m) _Pragma("unroll") for (int k = 0; k < 2; ++k) dst[m][k] = *(const LAS bf16x8*)(pA + PG8_SA(b, h) + m * 2048 + k * 1024); } while (0)
; #define PG8_LDB(dst, b, h) do { _Pragma("unroll") for (int n = 0; n < 2; ++n) _Pragma("unroll") for (int k = 0; k < 2; ++k) dst[n][k] = *(const LAS bf16x8*)(pB + (PG8_SB(b, h) - 4 * HTB) + n * 2048 + k * 1024); } while (0)
; #define PG8_MMA(ai, bj, At, Bt) do { __builtin_amdgcn_s_setprio(1); _Pragma("unroll") for (int m = 0; m < 4; ++m) _Pragma("unroll") for (int n = 0; n < 2; ++n) _Pragma("unroll") for (int k = 0; k < 2; ++k) \
;         acc[ai][bj][m][n] = __builtin_amdgcn_mfma_f32_16x16x32_bf16(Bt[n][k], At[m][k], acc[ai][bj][m][n], 0, 0, 0); __builtin_amdgcn_s_setprio(0); } while (0)
; #define PG8_WAIT_V(n) asm volatile("s_waitcnt vmcnt(" #n ")" ::: "memory")
; #define PG8_WAIT_L(n) asm volatile("s_waitcnt lgkmcnt(" #n ")" ::: "memory")
; #define PG8_BAR __builtin_amdgcn_s_barrier()
; template <class Desc, class Epi, bool ALIGN_EPI>
; __device__ __forceinline__ void gemm_phase(LAS unsigned char* lds, const Desc& D, const Epi& E, int G, int c) {
;     ...
;         for (int t = 0; t < nt; t += 2) {
;             const bool last = (t == nt - 2);
;             if (last && has_next) PG8_AWAIT(nxt);
;             const char* a1 = cA + (size_t)(t + 1) * kstep;
;             const char* a2 = last ? nA : cA + (size_t)(t + 2) * kstep; const char* b2 = last ? nB : cB + (size_t)(t + 2) * kstep;
;             const char* a3 = a2 + kstep; const char* b3 = b2 + kstep;
;             PG8_LDB(B0, 0, 0); PG8_LDB(B1, 0, 1); PG8_SCHED; PG8_LDA(At, 0, 0); PG8_STAGE(PG8_SA(1, 1), a1 + hstepA, voffA);
;             PG8_WAIT_V(8); PG8_WAIT_L(0); PG8_BAR; PG8_MMA(0, 0, At, B0); PG8_MMA(0, 1, At, B1); PG8_BAR; PG8_SCHED;
;             PG8_LDA(At, 0, 1); PG8_STAGE(PG8_SB(0, 0), b2, voffB); PG8_STAGE(PG8_SB(0, 1), b2 + hstepB, voffB); PG8_STAGE(PG8_SA(0, 0), a2, voffA);
.LBB0_1324:
	ds_read_b128 v[144:147], v149
	ds_read_b128 v[152:155], v149 offset:1024
	ds_read_b128 v[156:159], v149 offset:2048
	ds_read_b128 v[160:163], v149 offset:3072
	ds_read_b128 v[164:167], v149 offset:16384
	ds_read_b128 v[168:171], v149 offset:17408
	ds_read_b128 v[172:175], v149 offset:18432
	ds_read_b128 v[176:179], v149 offset:19456
	s_add_i32 s50, s18, 2
	s_add_u32 s19, s16, 0xfff00080
	s_addc_u32 s20, s17, -1
	s_cmp_eq_u32 s9, s18
	s_cselect_b32 s18, s12, s48
	s_cselect_b32 s21, s11, s20
	s_cselect_b32 s20, s10, s19
	s_cselect_b32 s19, s13, s49
	v_lshl_add_u64 v[212:213], s[16:17], 0, v[140:141]
	s_add_i32 m0, s24, 0xc000
	ds_read_b128 v[180:183], v148
	ds_read_b128 v[184:187], v148 offset:1024
	ds_read_b128 v[188:191], v148 offset:2048
	ds_read_b128 v[192:195], v148 offset:3072
	ds_read_b128 v[196:199], v148 offset:4096
	ds_read_b128 v[200:203], v148 offset:5120
	ds_read_b128 v[204:207], v148 offset:6144
	ds_read_b128 v[208:211], v148 offset:7168
	global_load_lds_dwordx4 v[212:213], off
	v_lshl_add_u64 v[212:213], s[16:17], 0, v[142:143]
	s_add_i32 m0, s24, 0xe000
	s_nop 0
	global_load_lds_dwordx4 v[212:213], off
	s_waitcnt vmcnt(8)
	s_waitcnt lgkmcnt(0)
	s_barrier
	v_mfma_f32_16x16x32_bf16 v[128:131], v[144:147], v[180:183], v[128:131]
	v_mfma_f32_16x16x32_bf16 v[128:131], v[152:155], v[184:187], v[128:131]
	v_mfma_f32_16x16x32_bf16 v[124:127], v[156:159], v[180:183], v[124:127]
	v_mfma_f32_16x16x32_bf16 v[124:127], v[160:163], v[184:187], v[124:127]
	v_mfma_f32_16x16x32_bf16 v[116:119], v[164:167], v[180:183], v[116:119]
	v_mfma_f32_16x16x32_bf16 v[116:119], v[168:171], v[184:187], v[116:119]
	v_mfma_f32_16x16x32_bf16 v[108:111], v[172:175], v[180:183], v[108:111]
	v_mfma_f32_16x16x32_bf16 v[108:111], v[176:179], v[184:187], v[108:111]
	v_mfma_f32_16x16x32_bf16 v[92:95], v[172:175], v[188:191], v[92:95]
	v_mfma_f32_16x16x32_bf16 v[92:95], v[176:179], v[192:195], v[92:95]
	v_mfma_f32_16x16x32_bf16 v[100:103], v[164:167], v[188:191], v[100:103]
	v_mfma_f32_16x16x32_bf16 v[100:103], v[168:171], v[192:195], v[100:103]
	v_mfma_f32_16x16x32_bf16 v[112:115], v[156:159], v[188:191], v[112:115]
	v_mfma_f32_16x16x32_bf16 v[112:115], v[160:163], v[192:195], v[112:115]
	v_mfma_f32_16x16x32_bf16 v[120:123], v[144:147], v[188:191], v[120:123]
	v_mfma_f32_16x16x32_bf16 v[120:123], v[152:155], v[192:195], v[120:123]
	v_mfma_f32_16x16x32_bf16 v[104:107], v[144:147], v[196:199], v[104:107]
	v_mfma_f32_16x16x32_bf16 v[104:107], v[152:155], v[200:203], v[104:107]
	v_mfma_f32_16x16x32_bf16 v[96:99], v[156:159], v[196:199], v[96:99]
	v_mfma_f32_16x16x32_bf16 v[96:99], v[160:163], v[200:203], v[96:99]
	v_mfma_f32_16x16x32_bf16 v[84:87], v[164:167], v[196:199], v[84:87]
	v_mfma_f32_16x16x32_bf16 v[84:87], v[168:171], v[200:203], v[84:87]
	v_mfma_f32_16x16x32_bf16 v[76:79], v[172:175], v[196:199], v[76:79]
	v_mfma_f32_16x16x32_bf16 v[76:79], v[176:179], v[200:203], v[76:79]
	v_mfma_f32_16x16x32_bf16 v[68:71], v[172:175], v[204:207], v[68:71]
	v_mfma_f32_16x16x32_bf16 v[68:71], v[176:179], v[208:211], v[68:71]
	v_mfma_f32_16x16x32_bf16 v[72:75], v[164:167], v[204:207], v[72:75]
	v_mfma_f32_16x16x32_bf16 v[72:75], v[168:171], v[208:211], v[72:75]
	v_mfma_f32_16x16x32_bf16 v[80:83], v[156:159], v[204:207], v[80:83]
	v_mfma_f32_16x16x32_bf16 v[80:83], v[160:163], v[208:211], v[80:83]
	v_mfma_f32_16x16x32_bf16 v[88:91], v[144:147], v[204:207], v[88:91]
	v_mfma_f32_16x16x32_bf16 v[88:91], v[152:155], v[208:211], v[88:91]
	s_barrier
	s_mov_b32 m0, s25
	v_lshl_add_u64 v[212:213], s[18:19], 0, v[136:137]
	s_add_u32 s52, s18, 0x100000
	ds_read_b128 v[180:183], v148 offset:16384
	ds_read_b128 v[184:187], v148 offset:17408
	ds_read_b128 v[188:191], v148 offset:18432
	ds_read_b128 v[192:195], v148 offset:19456
	ds_read_b128 v[196:199], v148 offset:20480
	ds_read_b128 v[200:203], v148 offset:21504
	ds_read_b128 v[204:207], v148 offset:22528
	ds_read_b128 v[208:211], v148 offset:23552
	global_load_lds_dwordx4 v[212:213], off
	v_lshl_add_u64 v[214:215], s[18:19], 0, v[132:133]
	s_mov_b32 m0, s26
	s_addc_u32 s53, s19, 0
	global_load_lds_dwordx4 v[214:215], off
	v_lshl_add_u64 v[216:217], s[52:53], 0, v[136:137]
	s_mov_b32 m0, s27
	v_lshl_add_u64 v[218:219], s[20:21], 0, v[134:135]
	global_load_lds_dwordx4 v[216:217], off
	v_lshl_add_u64 v[216:217], s[52:53], 0, v[132:133]
	s_mov_b32 m0, s30
	s_nop 0
	global_load_lds_dwordx4 v[216:217], off
	v_lshl_add_u64 v[216:217], s[20:21], 0, v[138:139]
	s_mov_b32 m0, s24
	s_nop 0
	global_load_lds_dwordx4 v[216:217], off
	s_mov_b32 m0, s31
	s_nop 0
	global_load_lds_dwordx4 v[218:219], off
	s_waitcnt vmcnt(8)
	s_waitcnt lgkmcnt(0)
	s_barrier
; #define PG8_STAGE(bufoff, gbase, voff) do { _Pragma("unroll") for (int _i = 0; _i < 2; ++_i) \
;         __builtin_amdgcn_global_load_lds((const unsigned*)((const char*)(gbase) + (voff)[_i]), (LAS unsigned*)(lds + (bufoff) + ldsw + _i * 8192), 16, 0, 0); } while (0)
; #define PG8_LDA(dst, b, h) do { _Pragma("unroll") for (int m = 0; m < 4; ++m) _Pragma("unroll") for (int k = 0; k < 2; ++k) dst[m][k] = *(const LAS bf16x8*)(pA + PG8_SA(b, h) + m * 2048 + k * 1024); } while (0)
; #define PG8_LDB(dst, b, h) do { _Pragma("unroll") for (int n = 0; n < 2; ++n) _Pragma("unroll") for (int k = 0; k < 2; ++k) dst[n][k] = *(const LAS bf16x8*)(pB + (PG8_SB(b, h) - 4 * HTB) + n * 2048 + k * 1024); } while (0)
; #define PG8_MMA(ai, bj, At, Bt) do { __builtin_amdgcn_s_setprio(1); _Pragma("unroll") for (int m = 0; m < 4; ++m) _Pragma("unroll") for (int n = 0; n < 2; ++n) _Pragma("unroll") for (int k = 0; k < 2; ++k) \
;         acc[ai][bj][m][n] = __builtin_amdgcn_mfma_f32_16x16x32_bf16(Bt[n][k], At[m][k], acc[ai][bj][m][n], 0, 0, 0); __builtin_amdgcn_s_setprio(0); } while (0)
; #define PG8_WAIT_V(n) asm volatile("s_waitcnt vmcnt(" #n ")" ::: "memory")
; #define PG8_WAIT_L(n) asm volatile("s_waitcnt lgkmcnt(" #n ")" ::: "memory")
; #define PG8_BAR __builtin_amdgcn_s_barrier()
; #define PG8_SCHED __builtin_amdgcn_sched_barrier(0)
; template <class Desc, class Epi, bool ALIGN_EPI>
; __device__ __forceinline__ void gemm_phase(LAS unsigned char* lds, const Desc& D, const Epi& E, int G, int c) {
;     ...
;             PG8_WAIT_V(8); PG8_WAIT_L(0); PG8_BAR; PG8_MMA(1, 0, At, B0); PG8_MMA(1, 1, At, B1); PG8_BAR; PG8_SCHED;
;             PG8_LDB(B0, 1, 0); PG8_LDB(B1, 1, 1); PG8_SCHED; PG8_LDA(At, 1, 0); PG8_STAGE(PG8_SA(0, 1), a2 + hstepA, voffA);
;             PG8_WAIT_V(8); PG8_WAIT_L(0); PG8_BAR; PG8_MMA(0, 0, At, B0); PG8_MMA(0, 1, At, B1); PG8_BAR; PG8_SCHED;
	v_mfma_f32_16x16x32_bf16 v[64:67], v[144:147], v[180:183], v[64:67]
	v_mfma_f32_16x16x32_bf16 v[64:67], v[152:155], v[184:187], v[64:67]
	v_mfma_f32_16x16x32_bf16 v[60:63], v[156:159], v[180:183], v[60:63]
	v_mfma_f32_16x16x32_bf16 v[60:63], v[160:163], v[184:187], v[60:63]
	v_mfma_f32_16x16x32_bf16 v[52:55], v[164:167], v[180:183], v[52:55]
	v_mfma_f32_16x16x32_bf16 v[52:55], v[168:171], v[184:187], v[52:55]
	v_mfma_f32_16x16x32_bf16 v[44:47], v[172:175], v[180:183], v[44:47]
	v_mfma_f32_16x16x32_bf16 v[44:47], v[176:179], v[184:187], v[44:47]
	v_mfma_f32_16x16x32_bf16 v[28:31], v[172:175], v[188:191], v[28:31]
	v_mfma_f32_16x16x32_bf16 v[28:31], v[176:179], v[192:195], v[28:31]
	v_mfma_f32_16x16x32_bf16 v[36:39], v[164:167], v[188:191], v[36:39]
	v_mfma_f32_16x16x32_bf16 v[36:39], v[168:171], v[192:195], v[36:39]
	v_mfma_f32_16x16x32_bf16 v[48:51], v[156:159], v[188:191], v[48:51]
	v_mfma_f32_16x16x32_bf16 v[48:51], v[160:163], v[192:195], v[48:51]
	v_mfma_f32_16x16x32_bf16 v[56:59], v[144:147], v[188:191], v[56:59]
	v_mfma_f32_16x16x32_bf16 v[56:59], v[152:155], v[192:195], v[56:59]
	v_mfma_f32_16x16x32_bf16 v[40:43], v[144:147], v[196:199], v[40:43]
	v_mfma_f32_16x16x32_bf16 v[40:43], v[152:155], v[200:203], v[40:43]
	v_mfma_f32_16x16x32_bf16 v[32:35], v[156:159], v[196:199], v[32:35]
	v_mfma_f32_16x16x32_bf16 v[32:35], v[160:163], v[200:203], v[32:35]
	v_mfma_f32_16x16x32_bf16 v[20:23], v[164:167], v[196:199], v[20:23]
	v_mfma_f32_16x16x32_bf16 v[20:23], v[168:171], v[200:203], v[20:23]
	v_mfma_f32_16x16x32_bf16 v[12:15], v[172:175], v[196:199], v[12:15]
	v_mfma_f32_16x16x32_bf16 v[12:15], v[176:179], v[200:203], v[12:15]
	v_mfma_f32_16x16x32_bf16 v[4:7], v[172:175], v[204:207], v[4:7]
	v_mfma_f32_16x16x32_bf16 v[4:7], v[176:179], v[208:211], v[4:7]
	v_mfma_f32_16x16x32_bf16 v[8:11], v[164:167], v[204:207], v[8:11]
	v_mfma_f32_16x16x32_bf16 v[8:11], v[168:171], v[208:211], v[8:11]
	v_mfma_f32_16x16x32_bf16 v[16:19], v[156:159], v[204:207], v[16:19]
	v_mfma_f32_16x16x32_bf16 v[16:19], v[160:163], v[208:211], v[16:19]
	v_mfma_f32_16x16x32_bf16 v[24:27], v[144:147], v[204:207], v[24:27]
	v_mfma_f32_16x16x32_bf16 v[24:27], v[152:155], v[208:211], v[24:27]
	s_barrier
	ds_read_b128 v[144:147], v149 offset:32768
	ds_read_b128 v[152:155], v149 offset:33792
	ds_read_b128 v[156:159], v149 offset:34816
	ds_read_b128 v[160:163], v149 offset:35840
	ds_read_b128 v[164:167], v149 offset:49152
	ds_read_b128 v[168:171], v149 offset:50176
	ds_read_b128 v[172:175], v149 offset:51200
	ds_read_b128 v[176:179], v149 offset:52224
	s_add_u32 s20, s20, 0x100000
	s_addc_u32 s21, s21, 0
	s_mov_b32 m0, s33
	v_lshl_add_u64 v[220:221], s[20:21], 0, v[138:139]
	ds_read_b128 v[180:183], v148 offset:32768
	ds_read_b128 v[184:187], v148 offset:33792
	ds_read_b128 v[188:191], v148 offset:34816
	ds_read_b128 v[192:195], v148 offset:35840
	ds_read_b128 v[196:199], v148 offset:36864
	ds_read_b128 v[200:203], v148 offset:37888
	ds_read_b128 v[204:207], v148 offset:38912
	ds_read_b128 v[208:211], v148 offset:39936
	global_load_lds_dwordx4 v[220:221], off
	v_lshl_add_u64 v[220:221], s[20:21], 0, v[134:135]
	s_mov_b32 m0, s34
	s_nop 0
	global_load_lds_dwordx4 v[220:221], off
	s_waitcnt vmcnt(8)
	s_waitcnt lgkmcnt(0)
	s_barrier
	v_mfma_f32_16x16x32_bf16 v[128:131], v[144:147], v[180:183], v[128:131]
	v_mfma_f32_16x16x32_bf16 v[128:131], v[152:155], v[184:187], v[128:131]
	v_mfma_f32_16x16x32_bf16 v[124:127], v[156:159], v[180:183], v[124:127]
	v_mfma_f32_16x16x32_bf16 v[124:127], v[160:163], v[184:187], v[124:127]
	v_mfma_f32_16x16x32_bf16 v[116:119], v[164:167], v[180:183], v[116:119]
	v_mfma_f32_16x16x32_bf16 v[116:119], v[168:171], v[184:187], v[116:119]
	v_mfma_f32_16x16x32_bf16 v[108:111], v[172:175], v[180:183], v[108:111]
	v_mfma_f32_16x16x32_bf16 v[108:111], v[176:179], v[184:187], v[108:111]
	v_mfma_f32_16x16x32_bf16 v[92:95], v[172:175], v[188:191], v[92:95]
	v_mfma_f32_16x16x32_bf16 v[92:95], v[176:179], v[192:195], v[92:95]
	v_mfma_f32_16x16x32_bf16 v[100:103], v[164:167], v[188:191], v[100:103]
	v_mfma_f32_16x16x32_bf16 v[100:103], v[168:171], v[192:195], v[100:103]
	v_mfma_f32_16x16x32_bf16 v[112:115], v[156:159], v[188:191], v[112:115]
	v_mfma_f32_16x16x32_bf16 v[112:115], v[160:163], v[192:195], v[112:115]
	v_mfma_f32_16x16x32_bf16 v[120:123], v[144:147], v[188:191], v[120:123]
	v_mfma_f32_16x16x32_bf16 v[120:123], v[152:155], v[192:195], v[120:123]
	v_mfma_f32_16x16x32_bf16 v[104:107], v[144:147], v[196:199], v[104:107]
	v_mfma_f32_16x16x32_bf16 v[104:107], v[152:155], v[200:203], v[104:107]
	v_mfma_f32_16x16x32_bf16 v[96:99], v[156:159], v[196:199], v[96:99]
	v_mfma_f32_16x16x32_bf16 v[96:99], v[160:163], v[200:203], v[96:99]
	v_mfma_f32_16x16x32_bf16 v[84:87], v[164:167], v[196:199], v[84:87]
	v_mfma_f32_16x16x32_bf16 v[84:87], v[168:171], v[200:203], v[84:87]
	v_mfma_f32_16x16x32_bf16 v[76:79], v[172:175], v[196:199], v[76:79]
	v_mfma_f32_16x16x32_bf16 v[76:79], v[176:179], v[200:203], v[76:79]
	v_mfma_f32_16x16x32_bf16 v[68:71], v[172:175], v[204:207], v[68:71]
	v_mfma_f32_16x16x32_bf16 v[68:71], v[176:179], v[208:211], v[68:71]
	v_mfma_f32_16x16x32_bf16 v[72:75], v[164:167], v[204:207], v[72:75]
	v_mfma_f32_16x16x32_bf16 v[72:75], v[168:171], v[208:211], v[72:75]
	v_mfma_f32_16x16x32_bf16 v[80:83], v[156:159], v[204:207], v[80:83]
	v_mfma_f32_16x16x32_bf16 v[80:83], v[160:163], v[208:211], v[80:83]
	v_mfma_f32_16x16x32_bf16 v[88:91], v[144:147], v[204:207], v[88:91]
	v_mfma_f32_16x16x32_bf16 v[88:91], v[152:155], v[208:211], v[88:91]
	s_barrier
; #define PG8_STAGE(bufoff, gbase, voff) do { _Pragma("unroll") for (int _i = 0; _i < 2; ++_i) \
;         __builtin_amdgcn_global_load_lds((const unsigned*)((const char*)(gbase) + (voff)[_i]), (LAS unsigned*)(lds + (bufoff) + ldsw + _i * 8192), 16, 0, 0); } while (0)
; #define PG8_LDA(dst, b, h) do { _Pragma("unroll") for (int m = 0; m < 4; ++m) _Pragma("unroll") for (int k = 0; k < 2; ++k) dst[m][k] = *(const LAS bf16x8*)(pA + PG8_SA(b, h) + m * 2048 + k * 1024); } while (0)
; #define PG8_MMA(ai, bj, At, Bt) do { __builtin_amdgcn_s_setprio(1); _Pragma("unroll") for (int m = 0; m < 4; ++m) _Pragma("unroll") for (int n = 0; n < 2; ++n) _Pragma("unroll") for (int k = 0; k < 2; ++k) \
;         acc[ai][bj][m][n] = __builtin_amdgcn_mfma_f32_16x16x32_bf16(Bt[n][k], At[m][k], acc[ai][bj][m][n], 0, 0, 0); __builtin_amdgcn_s_setprio(0); } while (0)
; #define PG8_WAIT_V(n) asm volatile("s_waitcnt vmcnt(" #n ")" ::: "memory")
; #define PG8_WAIT_L(n) asm volatile("s_waitcnt lgkmcnt(" #n ")" ::: "memory")
; #define PG8_BAR __builtin_amdgcn_s_barrier()
; #define PG8_SCHED __builtin_amdgcn_sched_barrier(0)
; template <class Desc, class Epi, bool ALIGN_EPI>
; __device__ __forceinline__ void gemm_phase(LAS unsigned char* lds, const Desc& D, const Epi& E, int G, int c) {
;     ...
;             PG8_LDA(At, 1, 1); PG8_STAGE(PG8_SB(1, 0), b3, voffB); PG8_STAGE(PG8_SB(1, 1), b3 + hstepB, voffB); PG8_STAGE(PG8_SA(1, 0), a3, voffA);
;             PG8_WAIT_V(8); PG8_WAIT_L(0); PG8_BAR; PG8_MMA(1, 0, At, B0); PG8_MMA(1, 1, At, B1); PG8_BAR; PG8_SCHED;
;         }
;         if constexpr (ALIGN_EPI) { if (wr == 0) PG8_BAR; }
	s_mov_b32 m0, s35
	v_lshl_add_u64 v[212:213], v[212:213], 0, s[76:77]
	s_add_u32 s18, s18, 0x100080
	ds_read_b128 v[180:183], v148 offset:49152
	ds_read_b128 v[184:187], v148 offset:50176
	ds_read_b128 v[188:191], v148 offset:51200
	ds_read_b128 v[192:195], v148 offset:52224
	ds_read_b128 v[196:199], v148 offset:53248
	ds_read_b128 v[200:203], v148 offset:54272
	ds_read_b128 v[204:207], v148 offset:55296
	ds_read_b128 v[208:211], v148 offset:56320
	global_load_lds_dwordx4 v[212:213], off
	v_lshl_add_u64 v[212:213], v[214:215], 0, s[76:77]
	s_mov_b32 m0, s38
	s_addc_u32 s19, s19, 0
	global_load_lds_dwordx4 v[212:213], off
	v_lshl_add_u64 v[212:213], s[18:19], 0, v[136:137]
	s_mov_b32 m0, s41
	s_nop 0
	global_load_lds_dwordx4 v[212:213], off
	v_lshl_add_u64 v[212:213], s[18:19], 0, v[132:133]
	s_mov_b32 m0, s42
	s_nop 0
	global_load_lds_dwordx4 v[212:213], off
	v_lshl_add_u64 v[212:213], v[216:217], 0, s[76:77]
	s_mov_b32 m0, s39
	s_nop 0
	global_load_lds_dwordx4 v[212:213], off
	v_lshl_add_u64 v[212:213], v[218:219], 0, s[76:77]
	s_mov_b32 m0, s40
	s_nop 0
	global_load_lds_dwordx4 v[212:213], off
	s_waitcnt vmcnt(8)
	s_waitcnt lgkmcnt(0)
	s_barrier
	v_mfma_f32_16x16x32_bf16 v[64:67], v[144:147], v[180:183], v[64:67]
	v_mfma_f32_16x16x32_bf16 v[64:67], v[152:155], v[184:187], v[64:67]
	v_mfma_f32_16x16x32_bf16 v[60:63], v[156:159], v[180:183], v[60:63]
	v_mfma_f32_16x16x32_bf16 v[60:63], v[160:163], v[184:187], v[60:63]
	v_mfma_f32_16x16x32_bf16 v[52:55], v[164:167], v[180:183], v[52:55]
	v_mfma_f32_16x16x32_bf16 v[52:55], v[168:171], v[184:187], v[52:55]
	v_mfma_f32_16x16x32_bf16 v[44:47], v[172:175], v[180:183], v[44:47]
	v_mfma_f32_16x16x32_bf16 v[44:47], v[176:179], v[184:187], v[44:47]
	v_mfma_f32_16x16x32_bf16 v[28:31], v[172:175], v[188:191], v[28:31]
	v_mfma_f32_16x16x32_bf16 v[28:31], v[176:179], v[192:195], v[28:31]
	v_mfma_f32_16x16x32_bf16 v[36:39], v[164:167], v[188:191], v[36:39]
	v_mfma_f32_16x16x32_bf16 v[36:39], v[168:171], v[192:195], v[36:39]
	v_mfma_f32_16x16x32_bf16 v[48:51], v[156:159], v[188:191], v[48:51]
	v_mfma_f32_16x16x32_bf16 v[48:51], v[160:163], v[192:195], v[48:51]
	v_mfma_f32_16x16x32_bf16 v[56:59], v[144:147], v[188:191], v[56:59]
	v_mfma_f32_16x16x32_bf16 v[56:59], v[152:155], v[192:195], v[56:59]
	v_mfma_f32_16x16x32_bf16 v[40:43], v[144:147], v[196:199], v[40:43]
	v_mfma_f32_16x16x32_bf16 v[40:43], v[152:155], v[200:203], v[40:43]
	v_mfma_f32_16x16x32_bf16 v[32:35], v[156:159], v[196:199], v[32:35]
	v_mfma_f32_16x16x32_bf16 v[32:35], v[160:163], v[200:203], v[32:35]
	v_mfma_f32_16x16x32_bf16 v[20:23], v[164:167], v[196:199], v[20:23]
	v_mfma_f32_16x16x32_bf16 v[20:23], v[168:171], v[200:203], v[20:23]
	v_mfma_f32_16x16x32_bf16 v[12:15], v[172:175], v[196:199], v[12:15]
	v_mfma_f32_16x16x32_bf16 v[12:15], v[176:179], v[200:203], v[12:15]
	v_mfma_f32_16x16x32_bf16 v[4:7], v[172:175], v[204:207], v[4:7]
	v_mfma_f32_16x16x32_bf16 v[4:7], v[176:179], v[208:211], v[4:7]
	v_mfma_f32_16x16x32_bf16 v[8:11], v[164:167], v[204:207], v[8:11]
	v_mfma_f32_16x16x32_bf16 v[8:11], v[168:171], v[208:211], v[8:11]
	v_mfma_f32_16x16x32_bf16 v[16:19], v[156:159], v[204:207], v[16:19]
	v_mfma_f32_16x16x32_bf16 v[16:19], v[160:163], v[208:211], v[16:19]
	v_mfma_f32_16x16x32_bf16 v[24:27], v[144:147], v[204:207], v[24:27]
	v_mfma_f32_16x16x32_bf16 v[24:27], v[152:155], v[208:211], v[24:27]
	s_barrier
	s_add_u32 s16, s16, 0x100
	s_addc_u32 s17, s17, 0
	s_add_u32 s48, s48, 0x100
	s_addc_u32 s49, s49, 0
	s_cmp_ge_u32 s50, s46
	s_mov_b32 s18, s50
	s_cbranch_scc0 .LBB0_1324
	s_and_b64 vcc, exec, s[6:7]
	s_cbranch_vccz .LBB0_1327
	s_barrier

;     __device__ __forceinline__ int nt(const Unit& u) const { return (u.pn >> 1) < 2 ? 22 : 20; }
; #define PG8_STAGE(bufoff, gbase, voff) do { _Pragma("unroll") for (int _i = 0; _i < 2; ++_i) \
;         __builtin_amdgcn_global_load_lds((const unsigned*)((const char*)(gbase) + (voff)[_i]), (LAS unsigned*)(lds + (bufoff) + ldsw + _i * 8192), 16, 0, 0); } while (0)
; #define PG8_LDA(dst, b, h) do { _Pragma("unroll") for (int m = 0; m < 4; ++m) _Pragma("unroll") for (int k = 0; k < 2; ++k) dst[m][k] = *(const LAS bf16x8*)(pA + PG8_SA(b, h) + m * 2048 + k * 1024); } while (0)
; #define PG8_LDB(dst, b, h) do { _Pragma("unroll") for (int n = 0; n < 2; ++n) _Pragma("unroll") for (int k = 0; k < 2; ++k) dst[n][k] = *(const LAS bf16x8*)(pB + (PG8_SB(b, h) - 4 * HTB) + n * 2048 + k * 1024); } while (0)
; #define PG8_MMA(ai, bj, At, Bt) do { __builtin_amdgcn_s_setprio(1); _Pragma("unroll") for (int m = 0; m < 4; ++m) _Pragma("unroll") for (int n = 0; n < 2; ++n) _Pragma("unroll") for (int k = 0; k < 2; ++k) \
;         acc[ai][bj][m][n] = __builtin_amdgcn_mfma_f32_16x16x32_bf16(Bt[n][k], At[m][k], acc[ai][bj][m][n], 0, 0, 0); __builtin_amdgcn_s_setprio(0); } while (0)
; #define PG8_WAIT_V(n) asm volatile("s_waitcnt vmcnt(" #n ")" ::: "memory")
; #define PG8_WAIT_L(n) asm volatile("s_waitcnt lgkmcnt(" #n ")" ::: "memory")
; #define PG8_BAR __builtin_amdgcn_s_barrier()
; template <class Desc, class Epi, bool ALIGN_EPI>
; __device__ __forceinline__ void gemm_phase(LAS unsigned char* lds, const Desc& D, const Epi& E, int G, int c) {
;     ...
;         for (int t = 0; t < nt; t += 2) {
;             const bool last = (t == nt - 2);
;             if (last && has_next) PG8_AWAIT(nxt);
;             const char* a1 = cA + (size_t)(t + 1) * kstep;
;             const char* a2 = last ? nA : cA + (size_t)(t + 2) * kstep; const char* b2 = last ? nB : cB + (size_t)(t + 2) * kstep;
;             const char* a3 = a2 + kstep; const char* b3 = b2 + kstep;
;             PG8_LDB(B0, 0, 0); PG8_LDB(B1, 0, 1); PG8_SCHED; PG8_LDA(At, 0, 0); PG8_STAGE(PG8_SA(1, 1), a1 + hstepA, voffA);
;             PG8_WAIT_V(8); PG8_WAIT_L(0); PG8_BAR; PG8_MMA(0, 0, At, B0); PG8_MMA(0, 1, At, B1); PG8_BAR; PG8_SCHED;
;             PG8_LDA(At, 0, 1); PG8_STAGE(PG8_SB(0, 0), b2, voffB); PG8_STAGE(PG8_SB(0, 1), b2 + hstepB, voffB); PG8_STAGE(PG8_SA(0, 0), a2, voffA);
.LBB0_1479:
	ds_read_b128 v[116:119], v225
	ds_read_b128 v[128:131], v225 offset:1024
	ds_read_b128 v[132:135], v225 offset:2048
	ds_read_b128 v[136:139], v225 offset:3072
	ds_read_b128 v[140:143], v225 offset:16384
	ds_read_b128 v[144:147], v225 offset:17408
	ds_read_b128 v[148:151], v225 offset:18432
	ds_read_b128 v[152:155], v225 offset:19456
	s_add_u32 s12, s0, 0xfffe0080
	s_addc_u32 s13, s1, -1
	s_cmp_eq_u32 s52, 4
	s_cselect_b32 s17, s37, s13
	s_cselect_b32 s16, s36, s12
	s_cselect_b32 s13, s21, s33
	s_cselect_b32 s12, s24, s27
	v_lshl_add_u64 v[208:209], s[0:1], 0, v[200:201]
	s_add_i32 m0, s31, 0xc000
	ds_read_b128 v[164:167], v224
	ds_read_b128 v[168:171], v224 offset:1024
	ds_read_b128 v[172:175], v224 offset:2048
	ds_read_b128 v[176:179], v224 offset:3072
	ds_read_b128 v[180:183], v224 offset:4096
	ds_read_b128 v[184:187], v224 offset:5120
	ds_read_b128 v[188:191], v224 offset:6144
	ds_read_b128 v[204:207], v224 offset:7168
	global_load_lds_dwordx4 v[208:209], off
	v_lshl_add_u64 v[208:209], s[0:1], 0, v[202:203]
	s_add_i32 m0, s31, 0xe000
	s_nop 0
	global_load_lds_dwordx4 v[208:209], off
	s_waitcnt vmcnt(8)
	s_waitcnt lgkmcnt(0)
	s_barrier
	v_mfma_f32_16x16x32_bf16 v[160:163], v[116:119], v[164:167], v[160:163]
	v_mfma_f32_16x16x32_bf16 v[160:163], v[128:131], v[168:171], v[160:163]
	v_mfma_f32_16x16x32_bf16 v[156:159], v[132:135], v[164:167], v[156:159]
	v_mfma_f32_16x16x32_bf16 v[156:159], v[136:139], v[168:171], v[156:159]
	v_mfma_f32_16x16x32_bf16 v[124:127], v[140:143], v[164:167], v[124:127]
	v_mfma_f32_16x16x32_bf16 v[124:127], v[144:147], v[168:171], v[124:127]
	v_mfma_f32_16x16x32_bf16 v[120:123], v[148:151], v[164:167], v[120:123]
	v_mfma_f32_16x16x32_bf16 v[120:123], v[152:155], v[168:171], v[120:123]
	v_mfma_f32_16x16x32_bf16 v[100:103], v[148:151], v[172:175], v[100:103]
	v_mfma_f32_16x16x32_bf16 v[100:103], v[152:155], v[176:179], v[100:103]
	v_mfma_f32_16x16x32_bf16 v[104:107], v[140:143], v[172:175], v[104:107]
	v_mfma_f32_16x16x32_bf16 v[104:107], v[144:147], v[176:179], v[104:107]
	v_mfma_f32_16x16x32_bf16 v[108:111], v[132:135], v[172:175], v[108:111]
	v_mfma_f32_16x16x32_bf16 v[108:111], v[136:139], v[176:179], v[108:111]
	v_mfma_f32_16x16x32_bf16 v[112:115], v[116:119], v[172:175], v[112:115]
	v_mfma_f32_16x16x32_bf16 v[112:115], v[128:131], v[176:179], v[112:115]
	v_mfma_f32_16x16x32_bf16 v[96:99], v[116:119], v[180:183], v[96:99]
	v_mfma_f32_16x16x32_bf16 v[96:99], v[128:131], v[184:187], v[96:99]
	v_mfma_f32_16x16x32_bf16 v[92:95], v[132:135], v[180:183], v[92:95]
	v_mfma_f32_16x16x32_bf16 v[92:95], v[136:139], v[184:187], v[92:95]
	v_mfma_f32_16x16x32_bf16 v[88:91], v[140:143], v[180:183], v[88:91]
	v_mfma_f32_16x16x32_bf16 v[88:91], v[144:147], v[184:187], v[88:91]
	v_mfma_f32_16x16x32_bf16 v[84:87], v[148:151], v[180:183], v[84:87]
	v_mfma_f32_16x16x32_bf16 v[84:87], v[152:155], v[184:187], v[84:87]
	v_mfma_f32_16x16x32_bf16 v[68:71], v[148:151], v[188:191], v[68:71]
	v_mfma_f32_16x16x32_bf16 v[68:71], v[152:155], v[204:207], v[68:71]
	v_mfma_f32_16x16x32_bf16 v[72:75], v[140:143], v[188:191], v[72:75]
	v_mfma_f32_16x16x32_bf16 v[72:75], v[144:147], v[204:207], v[72:75]
	v_mfma_f32_16x16x32_bf16 v[76:79], v[132:135], v[188:191], v[76:79]
	v_mfma_f32_16x16x32_bf16 v[76:79], v[136:139], v[204:207], v[76:79]
	v_mfma_f32_16x16x32_bf16 v[80:83], v[116:119], v[188:191], v[80:83]
	v_mfma_f32_16x16x32_bf16 v[80:83], v[128:131], v[204:207], v[80:83]
	s_barrier
	s_mov_b32 m0, s34
	v_lshl_add_u64 v[208:209], s[12:13], 0, v[196:197]
	s_add_u32 s54, s12, 0x20000
	ds_read_b128 v[164:167], v224 offset:16384
	ds_read_b128 v[168:171], v224 offset:17408
	ds_read_b128 v[172:175], v224 offset:18432
	ds_read_b128 v[176:179], v224 offset:19456
	ds_read_b128 v[180:183], v224 offset:20480
	ds_read_b128 v[184:187], v224 offset:21504
	ds_read_b128 v[188:191], v224 offset:22528
	ds_read_b128 v[204:207], v224 offset:23552
	global_load_lds_dwordx4 v[208:209], off
	v_lshl_add_u64 v[210:211], s[12:13], 0, v[192:193]
	s_mov_b32 m0, s35
	s_addc_u32 s55, s13, 0
	global_load_lds_dwordx4 v[210:211], off
	v_lshl_add_u64 v[212:213], s[54:55], 0, v[196:197]
	s_mov_b32 m0, s40
	v_lshl_add_u64 v[214:215], s[16:17], 0, v[194:195]
	global_load_lds_dwordx4 v[212:213], off
	v_lshl_add_u64 v[212:213], s[54:55], 0, v[192:193]
	s_mov_b32 m0, s41
	s_nop 0
	global_load_lds_dwordx4 v[212:213], off
	v_lshl_add_u64 v[212:213], s[16:17], 0, v[198:199]
	s_mov_b32 m0, s31
	s_nop 0
	global_load_lds_dwordx4 v[212:213], off
	s_mov_b32 m0, s42
	s_nop 0
	global_load_lds_dwordx4 v[214:215], off
	s_waitcnt vmcnt(8)
	s_waitcnt lgkmcnt(0)
	s_barrier
; #define PG8_STAGE(bufoff, gbase, voff) do { _Pragma("unroll") for (int _i = 0; _i < 2; ++_i) \
;         __builtin_amdgcn_global_load_lds((const unsigned*)((const char*)(gbase) + (voff)[_i]), (LAS unsigned*)(lds + (bufoff) + ldsw + _i * 8192), 16, 0, 0); } while (0)
; #define PG8_LDA(dst, b, h) do { _Pragma("unroll") for (int m = 0; m < 4; ++m) _Pragma("unroll") for (int k = 0; k < 2; ++k) dst[m][k] = *(const LAS bf16x8*)(pA + PG8_SA(b, h) + m * 2048 + k * 1024); } while (0)
; #define PG8_LDB(dst, b, h) do { _Pragma("unroll") for (int n = 0; n < 2; ++n) _Pragma("unroll") for (int k = 0; k < 2; ++k) dst[n][k] = *(const LAS bf16x8*)(pB + (PG8_SB(b, h) - 4 * HTB) + n * 2048 + k * 1024); } while (0)
; #define PG8_MMA(ai, bj, At, Bt) do { __builtin_amdgcn_s_setprio(1); _Pragma("unroll") for (int m = 0; m < 4; ++m) _Pragma("unroll") for (int n = 0; n < 2; ++n) _Pragma("unroll") for (int k = 0; k < 2; ++k) \
;         acc[ai][bj][m][n] = __builtin_amdgcn_mfma_f32_16x16x32_bf16(Bt[n][k], At[m][k], acc[ai][bj][m][n], 0, 0, 0); __builtin_amdgcn_s_setprio(0); } while (0)
; #define PG8_WAIT_V(n) asm volatile("s_waitcnt vmcnt(" #n ")" ::: "memory")
; #define PG8_WAIT_L(n) asm volatile("s_waitcnt lgkmcnt(" #n ")" ::: "memory")
; #define PG8_BAR __builtin_amdgcn_s_barrier()
; #define PG8_SCHED __builtin_amdgcn_sched_barrier(0)
; template <class Desc, class Epi, bool ALIGN_EPI>
; __device__ __forceinline__ void gemm_phase(LAS unsigned char* lds, const Desc& D, const Epi& E, int G, int c) {
;     ...
;             PG8_WAIT_V(8); PG8_WAIT_L(0); PG8_BAR; PG8_MMA(1, 0, At, B0); PG8_MMA(1, 1, At, B1); PG8_BAR; PG8_SCHED;
;             PG8_LDB(B0, 1, 0); PG8_LDB(B1, 1, 1); PG8_SCHED; PG8_LDA(At, 1, 0); PG8_STAGE(PG8_SA(0, 1), a2 + hstepA, voffA);
;             PG8_WAIT_V(8); PG8_WAIT_L(0); PG8_BAR; PG8_MMA(0, 0, At, B0); PG8_MMA(0, 1, At, B1); PG8_BAR; PG8_SCHED;
	v_mfma_f32_16x16x32_bf16 v[64:67], v[116:119], v[164:167], v[64:67]
	v_mfma_f32_16x16x32_bf16 v[64:67], v[128:131], v[168:171], v[64:67]
	v_mfma_f32_16x16x32_bf16 v[60:63], v[132:135], v[164:167], v[60:63]
	v_mfma_f32_16x16x32_bf16 v[60:63], v[136:139], v[168:171], v[60:63]
	v_mfma_f32_16x16x32_bf16 v[56:59], v[140:143], v[164:167], v[56:59]
	v_mfma_f32_16x16x32_bf16 v[56:59], v[144:147], v[168:171], v[56:59]
	v_mfma_f32_16x16x32_bf16 v[52:55], v[148:151], v[164:167], v[52:55]
	v_mfma_f32_16x16x32_bf16 v[52:55], v[152:155], v[168:171], v[52:55]
	v_mfma_f32_16x16x32_bf16 v[36:39], v[148:151], v[172:175], v[36:39]
	v_mfma_f32_16x16x32_bf16 v[36:39], v[152:155], v[176:179], v[36:39]
	v_mfma_f32_16x16x32_bf16 v[40:43], v[140:143], v[172:175], v[40:43]
	v_mfma_f32_16x16x32_bf16 v[40:43], v[144:147], v[176:179], v[40:43]
	v_mfma_f32_16x16x32_bf16 v[44:47], v[132:135], v[172:175], v[44:47]
	v_mfma_f32_16x16x32_bf16 v[44:47], v[136:139], v[176:179], v[44:47]
	v_mfma_f32_16x16x32_bf16 v[48:51], v[116:119], v[172:175], v[48:51]
	v_mfma_f32_16x16x32_bf16 v[48:51], v[128:131], v[176:179], v[48:51]
	v_mfma_f32_16x16x32_bf16 v[32:35], v[116:119], v[180:183], v[32:35]
	v_mfma_f32_16x16x32_bf16 v[32:35], v[128:131], v[184:187], v[32:35]
	v_mfma_f32_16x16x32_bf16 v[28:31], v[132:135], v[180:183], v[28:31]
	v_mfma_f32_16x16x32_bf16 v[28:31], v[136:139], v[184:187], v[28:31]
	v_mfma_f32_16x16x32_bf16 v[24:27], v[140:143], v[180:183], v[24:27]
	v_mfma_f32_16x16x32_bf16 v[24:27], v[144:147], v[184:187], v[24:27]
	v_mfma_f32_16x16x32_bf16 v[20:23], v[148:151], v[180:183], v[20:23]
	v_mfma_f32_16x16x32_bf16 v[20:23], v[152:155], v[184:187], v[20:23]
	v_mfma_f32_16x16x32_bf16 v[4:7], v[148:151], v[188:191], v[4:7]
	v_mfma_f32_16x16x32_bf16 v[4:7], v[152:155], v[204:207], v[4:7]
	v_mfma_f32_16x16x32_bf16 v[8:11], v[140:143], v[188:191], v[8:11]
	v_mfma_f32_16x16x32_bf16 v[8:11], v[144:147], v[204:207], v[8:11]
	v_mfma_f32_16x16x32_bf16 v[12:15], v[132:135], v[188:191], v[12:15]
	v_mfma_f32_16x16x32_bf16 v[12:15], v[136:139], v[204:207], v[12:15]
	v_mfma_f32_16x16x32_bf16 v[16:19], v[116:119], v[188:191], v[16:19]
	v_mfma_f32_16x16x32_bf16 v[16:19], v[128:131], v[204:207], v[16:19]
	s_barrier
	ds_read_b128 v[116:119], v225 offset:32768
	ds_read_b128 v[128:131], v225 offset:33792
	ds_read_b128 v[132:135], v225 offset:34816
	ds_read_b128 v[136:139], v225 offset:35840
	ds_read_b128 v[140:143], v225 offset:49152
	ds_read_b128 v[144:147], v225 offset:50176
	ds_read_b128 v[148:151], v225 offset:51200
	ds_read_b128 v[152:155], v225 offset:52224
	s_add_u32 s16, s16, 0x20000
	s_addc_u32 s17, s17, 0
	s_mov_b32 m0, s43
	v_lshl_add_u64 v[216:217], s[16:17], 0, v[198:199]
	ds_read_b128 v[164:167], v224 offset:32768
	ds_read_b128 v[168:171], v224 offset:33792
	ds_read_b128 v[172:175], v224 offset:34816
	ds_read_b128 v[176:179], v224 offset:35840
	ds_read_b128 v[180:183], v224 offset:36864
	ds_read_b128 v[184:187], v224 offset:37888
	ds_read_b128 v[188:191], v224 offset:38912
	ds_read_b128 v[204:207], v224 offset:39936
	global_load_lds_dwordx4 v[216:217], off
	v_lshl_add_u64 v[216:217], s[16:17], 0, v[194:195]
	s_mov_b32 m0, s44
	s_nop 0
	global_load_lds_dwordx4 v[216:217], off
	s_waitcnt vmcnt(8)
	s_waitcnt lgkmcnt(0)
	s_barrier
	v_mfma_f32_16x16x32_bf16 v[160:163], v[116:119], v[164:167], v[160:163]
	v_mfma_f32_16x16x32_bf16 v[160:163], v[128:131], v[168:171], v[160:163]
	v_mfma_f32_16x16x32_bf16 v[156:159], v[132:135], v[164:167], v[156:159]
	v_mfma_f32_16x16x32_bf16 v[156:159], v[136:139], v[168:171], v[156:159]
	v_mfma_f32_16x16x32_bf16 v[124:127], v[140:143], v[164:167], v[124:127]
	v_mfma_f32_16x16x32_bf16 v[124:127], v[144:147], v[168:171], v[124:127]
	v_mfma_f32_16x16x32_bf16 v[120:123], v[148:151], v[164:167], v[120:123]
	v_mfma_f32_16x16x32_bf16 v[120:123], v[152:155], v[168:171], v[120:123]
	v_mfma_f32_16x16x32_bf16 v[100:103], v[148:151], v[172:175], v[100:103]
	v_mfma_f32_16x16x32_bf16 v[100:103], v[152:155], v[176:179], v[100:103]
	v_mfma_f32_16x16x32_bf16 v[104:107], v[140:143], v[172:175], v[104:107]
	v_mfma_f32_16x16x32_bf16 v[104:107], v[144:147], v[176:179], v[104:107]
	v_mfma_f32_16x16x32_bf16 v[108:111], v[132:135], v[172:175], v[108:111]
	v_mfma_f32_16x16x32_bf16 v[108:111], v[136:139], v[176:179], v[108:111]
	v_mfma_f32_16x16x32_bf16 v[112:115], v[116:119], v[172:175], v[112:115]
	v_mfma_f32_16x16x32_bf16 v[112:115], v[128:131], v[176:179], v[112:115]
	v_mfma_f32_16x16x32_bf16 v[96:99], v[116:119], v[180:183], v[96:99]
	v_mfma_f32_16x16x32_bf16 v[96:99], v[128:131], v[184:187], v[96:99]
	v_mfma_f32_16x16x32_bf16 v[92:95], v[132:135], v[180:183], v[92:95]
	v_mfma_f32_16x16x32_bf16 v[92:95], v[136:139], v[184:187], v[92:95]
	v_mfma_f32_16x16x32_bf16 v[88:91], v[140:143], v[180:183], v[88:91]
	v_mfma_f32_16x16x32_bf16 v[88:91], v[144:147], v[184:187], v[88:91]
	v_mfma_f32_16x16x32_bf16 v[84:87], v[148:151], v[180:183], v[84:87]
	v_mfma_f32_16x16x32_bf16 v[84:87], v[152:155], v[184:187], v[84:87]
	v_mfma_f32_16x16x32_bf16 v[68:71], v[148:151], v[188:191], v[68:71]
	v_mfma_f32_16x16x32_bf16 v[68:71], v[152:155], v[204:207], v[68:71]
	v_mfma_f32_16x16x32_bf16 v[72:75], v[140:143], v[188:191], v[72:75]
	v_mfma_f32_16x16x32_bf16 v[72:75], v[144:147], v[204:207], v[72:75]
	v_mfma_f32_16x16x32_bf16 v[76:79], v[132:135], v[188:191], v[76:79]
	v_mfma_f32_16x16x32_bf16 v[76:79], v[136:139], v[204:207], v[76:79]
	v_mfma_f32_16x16x32_bf16 v[80:83], v[116:119], v[188:191], v[80:83]
	v_mfma_f32_16x16x32_bf16 v[80:83], v[128:131], v[204:207], v[80:83]
	s_barrier
; #define PG8_STAGE(bufoff, gbase, voff) do { _Pragma("unroll") for (int _i = 0; _i < 2; ++_i) \
;         __builtin_amdgcn_global_load_lds((const unsigned*)((const char*)(gbase) + (voff)[_i]), (LAS unsigned*)(lds + (bufoff) + ldsw + _i * 8192), 16, 0, 0); } while (0)
; #define PG8_LDA(dst, b, h) do { _Pragma("unroll") for (int m = 0; m < 4; ++m) _Pragma("unroll") for (int k = 0; k < 2; ++k) dst[m][k] = *(const LAS bf16x8*)(pA + PG8_SA(b, h) + m * 2048 + k * 1024); } while (0)
; #define PG8_MMA(ai, bj, At, Bt) do { __builtin_amdgcn_s_setprio(1); _Pragma("unroll") for (int m = 0; m < 4; ++m) _Pragma("unroll") for (int n = 0; n < 2; ++n) _Pragma("unroll") for (int k = 0; k < 2; ++k) \
;         acc[ai][bj][m][n] = __builtin_amdgcn_mfma_f32_16x16x32_bf16(Bt[n][k], At[m][k], acc[ai][bj][m][n], 0, 0, 0); __builtin_amdgcn_s_setprio(0); } while (0)
; #define PG8_WAIT_V(n) asm volatile("s_waitcnt vmcnt(" #n ")" ::: "memory")
; #define PG8_WAIT_L(n) asm volatile("s_waitcnt lgkmcnt(" #n ")" ::: "memory")
; #define PG8_BAR __builtin_amdgcn_s_barrier()
; #define PG8_SCHED __builtin_amdgcn_sched_barrier(0)
; template <class Desc, class Epi, bool ALIGN_EPI>
; __device__ __forceinline__ void gemm_phase(LAS unsigned char* lds, const Desc& D, const Epi& E, int G, int c) {
;     ...
;             PG8_LDA(At, 1, 1); PG8_STAGE(PG8_SB(1, 0), b3, voffB); PG8_STAGE(PG8_SB(1, 1), b3 + hstepB, voffB); PG8_STAGE(PG8_SA(1, 0), a3, voffA);
;             PG8_WAIT_V(8); PG8_WAIT_L(0); PG8_BAR; PG8_MMA(1, 0, At, B0); PG8_MMA(1, 1, At, B1); PG8_BAR; PG8_SCHED;
;         }
;         if constexpr (ALIGN_EPI) { if (wr == 0) PG8_BAR; }
	s_mov_b32 m0, s45
	v_lshl_add_u64 v[208:209], v[208:209], 0, s[76:77]
	s_add_u32 s12, s12, 0x20080
	ds_read_b128 v[164:167], v224 offset:49152
	ds_read_b128 v[168:171], v224 offset:50176
	ds_read_b128 v[172:175], v224 offset:51200
	ds_read_b128 v[176:179], v224 offset:52224
	ds_read_b128 v[180:183], v224 offset:53248
	ds_read_b128 v[184:187], v224 offset:54272
	ds_read_b128 v[188:191], v224 offset:55296
	ds_read_b128 v[204:207], v224 offset:56320
	global_load_lds_dwordx4 v[208:209], off
	v_lshl_add_u64 v[208:209], v[210:211], 0, s[76:77]
	s_mov_b32 m0, s46
	s_addc_u32 s13, s13, 0
	global_load_lds_dwordx4 v[208:209], off
	v_lshl_add_u64 v[208:209], s[12:13], 0, v[196:197]
	s_mov_b32 m0, s49
	s_nop 0
	global_load_lds_dwordx4 v[208:209], off
	v_lshl_add_u64 v[208:209], s[12:13], 0, v[192:193]
	s_mov_b32 m0, s50
	s_nop 0
	global_load_lds_dwordx4 v[208:209], off
	v_lshl_add_u64 v[208:209], v[212:213], 0, s[76:77]
	s_mov_b32 m0, s47
	s_nop 0
	global_load_lds_dwordx4 v[208:209], off
	v_lshl_add_u64 v[208:209], v[214:215], 0, s[76:77]
	s_mov_b32 m0, s48
	s_nop 0
	global_load_lds_dwordx4 v[208:209], off
	s_waitcnt vmcnt(8)
	s_waitcnt lgkmcnt(0)
	s_barrier
	v_mfma_f32_16x16x32_bf16 v[64:67], v[116:119], v[164:167], v[64:67]
	v_mfma_f32_16x16x32_bf16 v[64:67], v[128:131], v[168:171], v[64:67]
	v_mfma_f32_16x16x32_bf16 v[60:63], v[132:135], v[164:167], v[60:63]
	v_mfma_f32_16x16x32_bf16 v[60:63], v[136:139], v[168:171], v[60:63]
	v_mfma_f32_16x16x32_bf16 v[56:59], v[140:143], v[164:167], v[56:59]
	v_mfma_f32_16x16x32_bf16 v[56:59], v[144:147], v[168:171], v[56:59]
	v_mfma_f32_16x16x32_bf16 v[52:55], v[148:151], v[164:167], v[52:55]
	v_mfma_f32_16x16x32_bf16 v[52:55], v[152:155], v[168:171], v[52:55]
	v_mfma_f32_16x16x32_bf16 v[36:39], v[148:151], v[172:175], v[36:39]
	v_mfma_f32_16x16x32_bf16 v[36:39], v[152:155], v[176:179], v[36:39]
	v_mfma_f32_16x16x32_bf16 v[40:43], v[140:143], v[172:175], v[40:43]
	v_mfma_f32_16x16x32_bf16 v[40:43], v[144:147], v[176:179], v[40:43]
	v_mfma_f32_16x16x32_bf16 v[44:47], v[132:135], v[172:175], v[44:47]
	v_mfma_f32_16x16x32_bf16 v[44:47], v[136:139], v[176:179], v[44:47]
	v_mfma_f32_16x16x32_bf16 v[48:51], v[116:119], v[172:175], v[48:51]
	v_mfma_f32_16x16x32_bf16 v[48:51], v[128:131], v[176:179], v[48:51]
	v_mfma_f32_16x16x32_bf16 v[32:35], v[116:119], v[180:183], v[32:35]
	v_mfma_f32_16x16x32_bf16 v[32:35], v[128:131], v[184:187], v[32:35]
	v_mfma_f32_16x16x32_bf16 v[28:31], v[132:135], v[180:183], v[28:31]
	v_mfma_f32_16x16x32_bf16 v[28:31], v[136:139], v[184:187], v[28:31]
	v_mfma_f32_16x16x32_bf16 v[24:27], v[140:143], v[180:183], v[24:27]
	v_mfma_f32_16x16x32_bf16 v[24:27], v[144:147], v[184:187], v[24:27]
	v_mfma_f32_16x16x32_bf16 v[20:23], v[148:151], v[180:183], v[20:23]
	v_mfma_f32_16x16x32_bf16 v[20:23], v[152:155], v[184:187], v[20:23]
	v_mfma_f32_16x16x32_bf16 v[4:7], v[148:151], v[188:191], v[4:7]
	v_mfma_f32_16x16x32_bf16 v[4:7], v[152:155], v[204:207], v[4:7]
	v_mfma_f32_16x16x32_bf16 v[8:11], v[140:143], v[188:191], v[8:11]
	v_mfma_f32_16x16x32_bf16 v[8:11], v[144:147], v[204:207], v[8:11]
	v_mfma_f32_16x16x32_bf16 v[12:15], v[132:135], v[188:191], v[12:15]
	v_mfma_f32_16x16x32_bf16 v[12:15], v[136:139], v[204:207], v[12:15]
	v_mfma_f32_16x16x32_bf16 v[16:19], v[116:119], v[188:191], v[16:19]
	v_mfma_f32_16x16x32_bf16 v[16:19], v[128:131], v[204:207], v[16:19]
	s_barrier
	s_add_i32 s52, s52, 2
	s_add_u32 s0, s0, 0x100
	s_addc_u32 s1, s1, 0
	s_add_u32 s27, s27, 0x100
	s_addc_u32 s33, s33, 0
	s_cmp_gt_u32 s52, 5
	s_cbranch_scc0 .LBB0_1479
	s_and_b64 vcc, exec, s[8:9]
	s_cbranch_vccz .LBB0_1482
	s_barrier

;     __device__ __forceinline__ int nt(const Unit& u) const { return (u.pn >> 1) < 2 ? 22 : 20; }
; #define PG8_STAGE(bufoff, gbase, voff) do { _Pragma("unroll") for (int _i = 0; _i < 2; ++_i) \
;         __builtin_amdgcn_global_load_lds((const unsigned*)((const char*)(gbase) + (voff)[_i]), (LAS unsigned*)(lds + (bufoff) + ldsw + _i * 8192), 16, 0, 0); } while (0)
; #define PG8_LDA(dst, b, h) do { _Pragma("unroll") for (int m = 0; m < 4; ++m) _Pragma("unroll") for (int k = 0; k < 2; ++k) dst[m][k] = *(const LAS bf16x8*)(pA + PG8_SA(b, h) + m * 2048 + k * 1024); } while (0)
; #define PG8_LDB(dst, b, h) do { _Pragma("unroll") for (int n = 0; n < 2; ++n) _Pragma("unroll") for (int k = 0; k < 2; ++k) dst[n][k] = *(const LAS bf16x8*)(pB + (PG8_SB(b, h) - 4 * HTB) + n * 2048 + k * 1024); } while (0)
; #define PG8_MMA(ai, bj, At, Bt) do { __builtin_amdgcn_s_setprio(1); _Pragma("unroll") for (int m = 0; m < 4; ++m) _Pragma("unroll") for (int n = 0; n < 2; ++n) _Pragma("unroll") for (int k = 0; k < 2; ++k) \
;         acc[ai][bj][m][n] = __builtin_amdgcn_mfma_f32_16x16x32_bf16(Bt[n][k], At[m][k], acc[ai][bj][m][n], 0, 0, 0); __builtin_amdgcn_s_setprio(0); } while (0)
; #define PG8_WAIT_V(n) asm volatile("s_waitcnt vmcnt(" #n ")" ::: "memory")
; #define PG8_WAIT_L(n) asm volatile("s_waitcnt lgkmcnt(" #n ")" ::: "memory")
; template <class Desc, class Epi, bool ALIGN_EPI>
; __device__ __forceinline__ void gemm_phase(LAS unsigned char* lds, const Desc& D, const Epi& E, int G, int c) {
;     ...
;             const bool last = (t == nt - 2);
;             if (last && has_next) PG8_AWAIT(nxt);
;             const char* a1 = cA + (size_t)(t + 1) * kstep;
;             const char* a2 = last ? nA : cA + (size_t)(t + 2) * kstep; const char* b2 = last ? nB : cB + (size_t)(t + 2) * kstep;
;             const char* a3 = a2 + kstep; const char* b3 = b2 + kstep;
;             PG8_LDB(B0, 0, 0); PG8_LDB(B1, 0, 1); PG8_SCHED; PG8_LDA(At, 0, 0); PG8_STAGE(PG8_SA(1, 1), a1 + hstepA, voffA);
;             PG8_WAIT_V(8); PG8_WAIT_L(0); PG8_BAR; PG8_MMA(0, 0, At, B0); PG8_MMA(0, 1, At, B1); PG8_BAR; PG8_SCHED;
;             PG8_LDA(At, 0, 1); PG8_STAGE(PG8_SB(0, 0), b2, voffB); PG8_STAGE(PG8_SB(0, 1), b2 + hstepB, voffB); PG8_STAGE(PG8_SA(0, 0), a2, voffA);
;             PG8_WAIT_V(8); PG8_WAIT_L(0); PG8_BAR; PG8_MMA(1, 0, At, B0); PG8_MMA(1, 1, At, B1); PG8_BAR; PG8_SCHED;
.LBB0_1517:
	ds_read_b128 v[116:119], v225
	ds_read_b128 v[128:131], v225 offset:1024
	ds_read_b128 v[132:135], v225 offset:2048
	ds_read_b128 v[136:139], v225 offset:3072
	ds_read_b128 v[140:143], v225 offset:16384
	ds_read_b128 v[144:147], v225 offset:17408
	ds_read_b128 v[148:151], v225 offset:18432
	ds_read_b128 v[152:155], v225 offset:19456
	s_add_u32 s12, s0, 0xfffe0080
	s_addc_u32 s13, s1, -1
	s_cmp_eq_u32 s54, 4
	s_cselect_b32 s17, s37, s13
	s_cselect_b32 s16, s36, s12
	s_cselect_b32 s13, s21, s33
	s_cselect_b32 s12, s24, s27
	v_lshl_add_u64 v[208:209], s[0:1], 0, v[200:201]
	s_add_i32 m0, s31, 0xc000
	ds_read_b128 v[164:167], v224
	ds_read_b128 v[168:171], v224 offset:1024
	ds_read_b128 v[172:175], v224 offset:2048
	ds_read_b128 v[176:179], v224 offset:3072
	ds_read_b128 v[180:183], v224 offset:4096
	ds_read_b128 v[184:187], v224 offset:5120
	ds_read_b128 v[188:191], v224 offset:6144
	ds_read_b128 v[204:207], v224 offset:7168
	global_load_lds_dwordx4 v[208:209], off
	v_lshl_add_u64 v[208:209], s[0:1], 0, v[202:203]
	s_add_i32 m0, s31, 0xe000
	s_nop 0
	global_load_lds_dwordx4 v[208:209], off
	s_waitcnt vmcnt(8)
	s_waitcnt lgkmcnt(0)
	s_barrier
	v_mfma_f32_16x16x32_bf16 v[160:163], v[116:119], v[164:167], v[160:163]
	v_mfma_f32_16x16x32_bf16 v[160:163], v[128:131], v[168:171], v[160:163]
	v_mfma_f32_16x16x32_bf16 v[156:159], v[132:135], v[164:167], v[156:159]
	v_mfma_f32_16x16x32_bf16 v[156:159], v[136:139], v[168:171], v[156:159]
	v_mfma_f32_16x16x32_bf16 v[124:127], v[140:143], v[164:167], v[124:127]
	v_mfma_f32_16x16x32_bf16 v[124:127], v[144:147], v[168:171], v[124:127]
	v_mfma_f32_16x16x32_bf16 v[120:123], v[148:151], v[164:167], v[120:123]
	v_mfma_f32_16x16x32_bf16 v[120:123], v[152:155], v[168:171], v[120:123]
	v_mfma_f32_16x16x32_bf16 v[100:103], v[148:151], v[172:175], v[100:103]
	v_mfma_f32_16x16x32_bf16 v[100:103], v[152:155], v[176:179], v[100:103]
	v_mfma_f32_16x16x32_bf16 v[104:107], v[140:143], v[172:175], v[104:107]
	v_mfma_f32_16x16x32_bf16 v[104:107], v[144:147], v[176:179], v[104:107]
	v_mfma_f32_16x16x32_bf16 v[108:111], v[132:135], v[172:175], v[108:111]
	v_mfma_f32_16x16x32_bf16 v[108:111], v[136:139], v[176:179], v[108:111]
	v_mfma_f32_16x16x32_bf16 v[112:115], v[116:119], v[172:175], v[112:115]
	v_mfma_f32_16x16x32_bf16 v[112:115], v[128:131], v[176:179], v[112:115]
	v_mfma_f32_16x16x32_bf16 v[96:99], v[116:119], v[180:183], v[96:99]
	v_mfma_f32_16x16x32_bf16 v[96:99], v[128:131], v[184:187], v[96:99]
	v_mfma_f32_16x16x32_bf16 v[92:95], v[132:135], v[180:183], v[92:95]
	v_mfma_f32_16x16x32_bf16 v[92:95], v[136:139], v[184:187], v[92:95]
	v_mfma_f32_16x16x32_bf16 v[88:91], v[140:143], v[180:183], v[88:91]
	v_mfma_f32_16x16x32_bf16 v[88:91], v[144:147], v[184:187], v[88:91]
	v_mfma_f32_16x16x32_bf16 v[84:87], v[148:151], v[180:183], v[84:87]
	v_mfma_f32_16x16x32_bf16 v[84:87], v[152:155], v[184:187], v[84:87]
	v_mfma_f32_16x16x32_bf16 v[68:71], v[148:151], v[188:191], v[68:71]
	v_mfma_f32_16x16x32_bf16 v[68:71], v[152:155], v[204:207], v[68:71]
	v_mfma_f32_16x16x32_bf16 v[72:75], v[140:143], v[188:191], v[72:75]
	v_mfma_f32_16x16x32_bf16 v[72:75], v[144:147], v[204:207], v[72:75]
	v_mfma_f32_16x16x32_bf16 v[76:79], v[132:135], v[188:191], v[76:79]
	v_mfma_f32_16x16x32_bf16 v[76:79], v[136:139], v[204:207], v[76:79]
	v_mfma_f32_16x16x32_bf16 v[80:83], v[116:119], v[188:191], v[80:83]
	v_mfma_f32_16x16x32_bf16 v[80:83], v[128:131], v[204:207], v[80:83]
	s_barrier
	s_mov_b32 m0, s34
	v_lshl_add_u64 v[208:209], s[12:13], 0, v[196:197]
	s_add_u32 s56, s12, 0x20000
	ds_read_b128 v[164:167], v224 offset:16384
	ds_read_b128 v[168:171], v224 offset:17408
	ds_read_b128 v[172:175], v224 offset:18432
	ds_read_b128 v[176:179], v224 offset:19456
	ds_read_b128 v[180:183], v224 offset:20480
	ds_read_b128 v[184:187], v224 offset:21504
	ds_read_b128 v[188:191], v224 offset:22528
	ds_read_b128 v[204:207], v224 offset:23552
	global_load_lds_dwordx4 v[208:209], off
	v_lshl_add_u64 v[210:211], s[12:13], 0, v[192:193]
	s_mov_b32 m0, s35
	s_addc_u32 s57, s13, 0
	global_load_lds_dwordx4 v[210:211], off
	v_lshl_add_u64 v[212:213], s[56:57], 0, v[196:197]
	s_mov_b32 m0, s42
	v_lshl_add_u64 v[214:215], s[16:17], 0, v[194:195]
	global_load_lds_dwordx4 v[212:213], off
	v_lshl_add_u64 v[212:213], s[56:57], 0, v[192:193]
	s_mov_b32 m0, s43
	s_nop 0
	global_load_lds_dwordx4 v[212:213], off
	v_lshl_add_u64 v[212:213], s[16:17], 0, v[198:199]
	s_mov_b32 m0, s31
	s_nop 0
	global_load_lds_dwordx4 v[212:213], off
	s_mov_b32 m0, s44
	s_nop 0
	global_load_lds_dwordx4 v[214:215], off
	s_waitcnt vmcnt(8)
	s_waitcnt lgkmcnt(0)
	s_barrier
; #define PG8_STAGE(bufoff, gbase, voff) do { _Pragma("unroll") for (int _i = 0; _i < 2; ++_i) \
;         __builtin_amdgcn_global_load_lds((const unsigned*)((const char*)(gbase) + (voff)[_i]), (LAS unsigned*)(lds + (bufoff) + ldsw + _i * 8192), 16, 0, 0); } while (0)
; #define PG8_LDA(dst, b, h) do { _Pragma("unroll") for (int m = 0; m < 4; ++m) _Pragma("unroll") for (int k = 0; k < 2; ++k) dst[m][k] = *(const LAS bf16x8*)(pA + PG8_SA(b, h) + m * 2048 + k * 1024); } while (0)
; #define PG8_LDB(dst, b, h) do { _Pragma("unroll") for (int n = 0; n < 2; ++n) _Pragma("unroll") for (int k = 0; k < 2; ++k) dst[n][k] = *(const LAS bf16x8*)(pB + (PG8_SB(b, h) - 4 * HTB) + n * 2048 + k * 1024); } while (0)
; #define PG8_MMA(ai, bj, At, Bt) do { __builtin_amdgcn_s_setprio(1); _Pragma("unroll") for (int m = 0; m < 4; ++m) _Pragma("unroll") for (int n = 0; n < 2; ++n) _Pragma("unroll") for (int k = 0; k < 2; ++k) \
;         acc[ai][bj][m][n] = __builtin_amdgcn_mfma_f32_16x16x32_bf16(Bt[n][k], At[m][k], acc[ai][bj][m][n], 0, 0, 0); __builtin_amdgcn_s_setprio(0); } while (0)
; #define PG8_WAIT_V(n) asm volatile("s_waitcnt vmcnt(" #n ")" ::: "memory")
; #define PG8_WAIT_L(n) asm volatile("s_waitcnt lgkmcnt(" #n ")" ::: "memory")
; #define PG8_BAR __builtin_amdgcn_s_barrier()
; #define PG8_SCHED __builtin_amdgcn_sched_barrier(0)
; template <class Desc, class Epi, bool ALIGN_EPI>
; __device__ __forceinline__ void gemm_phase(LAS unsigned char* lds, const Desc& D, const Epi& E, int G, int c) {
;     ...
;             PG8_WAIT_V(8); PG8_WAIT_L(0); PG8_BAR; PG8_MMA(1, 0, At, B0); PG8_MMA(1, 1, At, B1); PG8_BAR; PG8_SCHED;
;             PG8_LDB(B0, 1, 0); PG8_LDB(B1, 1, 1); PG8_SCHED; PG8_LDA(At, 1, 0); PG8_STAGE(PG8_SA(0, 1), a2 + hstepA, voffA);
;             PG8_WAIT_V(8); PG8_WAIT_L(0); PG8_BAR; PG8_MMA(0, 0, At, B0); PG8_MMA(0, 1, At, B1); PG8_BAR; PG8_SCHED;
	v_mfma_f32_16x16x32_bf16 v[64:67], v[116:119], v[164:167], v[64:67]
	v_mfma_f32_16x16x32_bf16 v[64:67], v[128:131], v[168:171], v[64:67]
	v_mfma_f32_16x16x32_bf16 v[60:63], v[132:135], v[164:167], v[60:63]
	v_mfma_f32_16x16x32_bf16 v[60:63], v[136:139], v[168:171], v[60:63]
	v_mfma_f32_16x16x32_bf16 v[56:59], v[140:143], v[164:167], v[56:59]
	v_mfma_f32_16x16x32_bf16 v[56:59], v[144:147], v[168:171], v[56:59]
	v_mfma_f32_16x16x32_bf16 v[52:55], v[148:151], v[164:167], v[52:55]
	v_mfma_f32_16x16x32_bf16 v[52:55], v[152:155], v[168:171], v[52:55]
	v_mfma_f32_16x16x32_bf16 v[36:39], v[148:151], v[172:175], v[36:39]
	v_mfma_f32_16x16x32_bf16 v[36:39], v[152:155], v[176:179], v[36:39]
	v_mfma_f32_16x16x32_bf16 v[40:43], v[140:143], v[172:175], v[40:43]
	v_mfma_f32_16x16x32_bf16 v[40:43], v[144:147], v[176:179], v[40:43]
	v_mfma_f32_16x16x32_bf16 v[44:47], v[132:135], v[172:175], v[44:47]
	v_mfma_f32_16x16x32_bf16 v[44:47], v[136:139], v[176:179], v[44:47]
	v_mfma_f32_16x16x32_bf16 v[48:51], v[116:119], v[172:175], v[48:51]
	v_mfma_f32_16x16x32_bf16 v[48:51], v[128:131], v[176:179], v[48:51]
	v_mfma_f32_16x16x32_bf16 v[32:35], v[116:119], v[180:183], v[32:35]
	v_mfma_f32_16x16x32_bf16 v[32:35], v[128:131], v[184:187], v[32:35]
	v_mfma_f32_16x16x32_bf16 v[28:31], v[132:135], v[180:183], v[28:31]
	v_mfma_f32_16x16x32_bf16 v[28:31], v[136:139], v[184:187], v[28:31]
	v_mfma_f32_16x16x32_bf16 v[24:27], v[140:143], v[180:183], v[24:27]
	v_mfma_f32_16x16x32_bf16 v[24:27], v[144:147], v[184:187], v[24:27]
	v_mfma_f32_16x16x32_bf16 v[20:23], v[148:151], v[180:183], v[20:23]
	v_mfma_f32_16x16x32_bf16 v[20:23], v[152:155], v[184:187], v[20:23]
	v_mfma_f32_16x16x32_bf16 v[4:7], v[148:151], v[188:191], v[4:7]
	v_mfma_f32_16x16x32_bf16 v[4:7], v[152:155], v[204:207], v[4:7]
	v_mfma_f32_16x16x32_bf16 v[8:11], v[140:143], v[188:191], v[8:11]
	v_mfma_f32_16x16x32_bf16 v[8:11], v[144:147], v[204:207], v[8:11]
	v_mfma_f32_16x16x32_bf16 v[12:15], v[132:135], v[188:191], v[12:15]
	v_mfma_f32_16x16x32_bf16 v[12:15], v[136:139], v[204:207], v[12:15]
	v_mfma_f32_16x16x32_bf16 v[16:19], v[116:119], v[188:191], v[16:19]
	v_mfma_f32_16x16x32_bf16 v[16:19], v[128:131], v[204:207], v[16:19]
	s_barrier
	ds_read_b128 v[116:119], v225 offset:32768
	ds_read_b128 v[128:131], v225 offset:33792
	ds_read_b128 v[132:135], v225 offset:34816
	ds_read_b128 v[136:139], v225 offset:35840
	ds_read_b128 v[140:143], v225 offset:49152
	ds_read_b128 v[144:147], v225 offset:50176
	ds_read_b128 v[148:151], v225 offset:51200
	ds_read_b128 v[152:155], v225 offset:52224
	s_add_u32 s16, s16, 0x20000
	s_addc_u32 s17, s17, 0
	s_mov_b32 m0, s45
	v_lshl_add_u64 v[216:217], s[16:17], 0, v[198:199]
	ds_read_b128 v[164:167], v224 offset:32768
	ds_read_b128 v[168:171], v224 offset:33792
	ds_read_b128 v[172:175], v224 offset:34816
	ds_read_b128 v[176:179], v224 offset:35840
	ds_read_b128 v[180:183], v224 offset:36864
	ds_read_b128 v[184:187], v224 offset:37888
	ds_read_b128 v[188:191], v224 offset:38912
	ds_read_b128 v[204:207], v224 offset:39936
	global_load_lds_dwordx4 v[216:217], off
	v_lshl_add_u64 v[216:217], s[16:17], 0, v[194:195]
	s_mov_b32 m0, s46
	s_nop 0
	global_load_lds_dwordx4 v[216:217], off
	s_waitcnt vmcnt(8)
	s_waitcnt lgkmcnt(0)
	s_barrier
	v_mfma_f32_16x16x32_bf16 v[160:163], v[116:119], v[164:167], v[160:163]
	v_mfma_f32_16x16x32_bf16 v[160:163], v[128:131], v[168:171], v[160:163]
	v_mfma_f32_16x16x32_bf16 v[156:159], v[132:135], v[164:167], v[156:159]
	v_mfma_f32_16x16x32_bf16 v[156:159], v[136:139], v[168:171], v[156:159]
	v_mfma_f32_16x16x32_bf16 v[124:127], v[140:143], v[164:167], v[124:127]
	v_mfma_f32_16x16x32_bf16 v[124:127], v[144:147], v[168:171], v[124:127]
	v_mfma_f32_16x16x32_bf16 v[120:123], v[148:151], v[164:167], v[120:123]
	v_mfma_f32_16x16x32_bf16 v[120:123], v[152:155], v[168:171], v[120:123]
	v_mfma_f32_16x16x32_bf16 v[100:103], v[148:151], v[172:175], v[100:103]
	v_mfma_f32_16x16x32_bf16 v[100:103], v[152:155], v[176:179], v[100:103]
	v_mfma_f32_16x16x32_bf16 v[104:107], v[140:143], v[172:175], v[104:107]
	v_mfma_f32_16x16x32_bf16 v[104:107], v[144:147], v[176:179], v[104:107]
	v_mfma_f32_16x16x32_bf16 v[108:111], v[132:135], v[172:175], v[108:111]
	v_mfma_f32_16x16x32_bf16 v[108:111], v[136:139], v[176:179], v[108:111]
	v_mfma_f32_16x16x32_bf16 v[112:115], v[116:119], v[172:175], v[112:115]
	v_mfma_f32_16x16x32_bf16 v[112:115], v[128:131], v[176:179], v[112:115]
	v_mfma_f32_16x16x32_bf16 v[96:99], v[116:119], v[180:183], v[96:99]
	v_mfma_f32_16x16x32_bf16 v[96:99], v[128:131], v[184:187], v[96:99]
	v_mfma_f32_16x16x32_bf16 v[92:95], v[132:135], v[180:183], v[92:95]
	v_mfma_f32_16x16x32_bf16 v[92:95], v[136:139], v[184:187], v[92:95]
	v_mfma_f32_16x16x32_bf16 v[88:91], v[140:143], v[180:183], v[88:91]
	v_mfma_f32_16x16x32_bf16 v[88:91], v[144:147], v[184:187], v[88:91]
	v_mfma_f32_16x16x32_bf16 v[84:87], v[148:151], v[180:183], v[84:87]
	v_mfma_f32_16x16x32_bf16 v[84:87], v[152:155], v[184:187], v[84:87]
	v_mfma_f32_16x16x32_bf16 v[68:71], v[148:151], v[188:191], v[68:71]
	v_mfma_f32_16x16x32_bf16 v[68:71], v[152:155], v[204:207], v[68:71]
	v_mfma_f32_16x16x32_bf16 v[72:75], v[140:143], v[188:191], v[72:75]
	v_mfma_f32_16x16x32_bf16 v[72:75], v[144:147], v[204:207], v[72:75]
	v_mfma_f32_16x16x32_bf16 v[76:79], v[132:135], v[188:191], v[76:79]
	v_mfma_f32_16x16x32_bf16 v[76:79], v[136:139], v[204:207], v[76:79]
	v_mfma_f32_16x16x32_bf16 v[80:83], v[116:119], v[188:191], v[80:83]
	v_mfma_f32_16x16x32_bf16 v[80:83], v[128:131], v[204:207], v[80:83]
	s_barrier
; #define PG8_STAGE(bufoff, gbase, voff) do { _Pragma("unroll") for (int _i = 0; _i < 2; ++_i) \
;         __builtin_amdgcn_global_load_lds((const unsigned*)((const char*)(gbase) + (voff)[_i]), (LAS unsigned*)(lds + (bufoff) + ldsw + _i * 8192), 16, 0, 0); } while (0)
; #define PG8_LDA(dst, b, h) do { _Pragma("unroll") for (int m = 0; m < 4; ++m) _Pragma("unroll") for (int k = 0; k < 2; ++k) dst[m][k] = *(const LAS bf16x8*)(pA + PG8_SA(b, h) + m * 2048 + k * 1024); } while (0)
; #define PG8_MMA(ai, bj, At, Bt) do { __builtin_amdgcn_s_setprio(1); _Pragma("unroll") for (int m = 0; m < 4; ++m) _Pragma("unroll") for (int n = 0; n < 2; ++n) _Pragma("unroll") for (int k = 0; k < 2; ++k) \
;         acc[ai][bj][m][n] = __builtin_amdgcn_mfma_f32_16x16x32_bf16(Bt[n][k], At[m][k], acc[ai][bj][m][n], 0, 0, 0); __builtin_amdgcn_s_setprio(0); } while (0)
; #define PG8_WAIT_V(n) asm volatile("s_waitcnt vmcnt(" #n ")" ::: "memory")
; #define PG8_WAIT_L(n) asm volatile("s_waitcnt lgkmcnt(" #n ")" ::: "memory")
; #define PG8_BAR __builtin_amdgcn_s_barrier()
; #define PG8_SCHED __builtin_amdgcn_sched_barrier(0)
; template <class Desc, class Epi, bool ALIGN_EPI>
; __device__ __forceinline__ void gemm_phase(LAS unsigned char* lds, const Desc& D, const Epi& E, int G, int c) {
;     ...
;             PG8_LDA(At, 1, 1); PG8_STAGE(PG8_SB(1, 0), b3, voffB); PG8_STAGE(PG8_SB(1, 1), b3 + hstepB, voffB); PG8_STAGE(PG8_SA(1, 0), a3, voffA);
;             PG8_WAIT_V(8); PG8_WAIT_L(0); PG8_BAR; PG8_MMA(1, 0, At, B0); PG8_MMA(1, 1, At, B1); PG8_BAR; PG8_SCHED;
;         }
;         if constexpr (ALIGN_EPI) { if (wr == 0) PG8_BAR; }
	s_mov_b32 m0, s47
	v_lshl_add_u64 v[208:209], v[208:209], 0, s[76:77]
	s_add_u32 s12, s12, 0x20080
	ds_read_b128 v[164:167], v224 offset:49152
	ds_read_b128 v[168:171], v224 offset:50176
	ds_read_b128 v[172:175], v224 offset:51200
	ds_read_b128 v[176:179], v224 offset:52224
	ds_read_b128 v[180:183], v224 offset:53248
	ds_read_b128 v[184:187], v224 offset:54272
	ds_read_b128 v[188:191], v224 offset:55296
	ds_read_b128 v[204:207], v224 offset:56320
	global_load_lds_dwordx4 v[208:209], off
	v_lshl_add_u64 v[208:209], v[210:211], 0, s[76:77]
	s_mov_b32 m0, s48
	s_addc_u32 s13, s13, 0
	global_load_lds_dwordx4 v[208:209], off
	v_lshl_add_u64 v[208:209], s[12:13], 0, v[196:197]
	s_mov_b32 m0, s51
	s_nop 0
	global_load_lds_dwordx4 v[208:209], off
	v_lshl_add_u64 v[208:209], s[12:13], 0, v[192:193]
	s_mov_b32 m0, s52
	s_nop 0
	global_load_lds_dwordx4 v[208:209], off
	v_lshl_add_u64 v[208:209], v[212:213], 0, s[76:77]
	s_mov_b32 m0, s49
	s_nop 0
	global_load_lds_dwordx4 v[208:209], off
	v_lshl_add_u64 v[208:209], v[214:215], 0, s[76:77]
	s_mov_b32 m0, s50
	s_nop 0
	global_load_lds_dwordx4 v[208:209], off
	s_waitcnt vmcnt(8)
	s_waitcnt lgkmcnt(0)
	s_barrier
	v_mfma_f32_16x16x32_bf16 v[64:67], v[116:119], v[164:167], v[64:67]
	v_mfma_f32_16x16x32_bf16 v[64:67], v[128:131], v[168:171], v[64:67]
	v_mfma_f32_16x16x32_bf16 v[60:63], v[132:135], v[164:167], v[60:63]
	v_mfma_f32_16x16x32_bf16 v[60:63], v[136:139], v[168:171], v[60:63]
	v_mfma_f32_16x16x32_bf16 v[56:59], v[140:143], v[164:167], v[56:59]
	v_mfma_f32_16x16x32_bf16 v[56:59], v[144:147], v[168:171], v[56:59]
	v_mfma_f32_16x16x32_bf16 v[52:55], v[148:151], v[164:167], v[52:55]
	v_mfma_f32_16x16x32_bf16 v[52:55], v[152:155], v[168:171], v[52:55]
	v_mfma_f32_16x16x32_bf16 v[36:39], v[148:151], v[172:175], v[36:39]
	v_mfma_f32_16x16x32_bf16 v[36:39], v[152:155], v[176:179], v[36:39]
	v_mfma_f32_16x16x32_bf16 v[40:43], v[140:143], v[172:175], v[40:43]
	v_mfma_f32_16x16x32_bf16 v[40:43], v[144:147], v[176:179], v[40:43]
	v_mfma_f32_16x16x32_bf16 v[44:47], v[132:135], v[172:175], v[44:47]
	v_mfma_f32_16x16x32_bf16 v[44:47], v[136:139], v[176:179], v[44:47]
	v_mfma_f32_16x16x32_bf16 v[48:51], v[116:119], v[172:175], v[48:51]
	v_mfma_f32_16x16x32_bf16 v[48:51], v[128:131], v[176:179], v[48:51]
	v_mfma_f32_16x16x32_bf16 v[32:35], v[116:119], v[180:183], v[32:35]
	v_mfma_f32_16x16x32_bf16 v[32:35], v[128:131], v[184:187], v[32:35]
	v_mfma_f32_16x16x32_bf16 v[28:31], v[132:135], v[180:183], v[28:31]
	v_mfma_f32_16x16x32_bf16 v[28:31], v[136:139], v[184:187], v[28:31]
	v_mfma_f32_16x16x32_bf16 v[24:27], v[140:143], v[180:183], v[24:27]
	v_mfma_f32_16x16x32_bf16 v[24:27], v[144:147], v[184:187], v[24:27]
	v_mfma_f32_16x16x32_bf16 v[20:23], v[148:151], v[180:183], v[20:23]
	v_mfma_f32_16x16x32_bf16 v[20:23], v[152:155], v[184:187], v[20:23]
	v_mfma_f32_16x16x32_bf16 v[4:7], v[148:151], v[188:191], v[4:7]
	v_mfma_f32_16x16x32_bf16 v[4:7], v[152:155], v[204:207], v[4:7]
	v_mfma_f32_16x16x32_bf16 v[8:11], v[140:143], v[188:191], v[8:11]
	v_mfma_f32_16x16x32_bf16 v[8:11], v[144:147], v[204:207], v[8:11]
	v_mfma_f32_16x16x32_bf16 v[12:15], v[132:135], v[188:191], v[12:15]
	v_mfma_f32_16x16x32_bf16 v[12:15], v[136:139], v[204:207], v[12:15]
	v_mfma_f32_16x16x32_bf16 v[16:19], v[116:119], v[188:191], v[16:19]
	v_mfma_f32_16x16x32_bf16 v[16:19], v[128:131], v[204:207], v[16:19]
	s_barrier
	s_add_i32 s54, s54, 2
	s_add_u32 s0, s0, 0x100
	s_addc_u32 s1, s1, 0
	s_add_u32 s27, s27, 0x100
	s_addc_u32 s33, s33, 0
	s_cmp_gt_u32 s54, 5
	s_cbranch_scc0 .LBB0_1517
	s_and_b64 vcc, exec, s[10:11]
	s_cbranch_vccz .LBB0_1520
	s_barrier

;     __device__ __forceinline__ int nt(const Unit& u) const { return (u.pn >> 1) < 2 ? 22 : 20; }
; #define PG8_STAGE(bufoff, gbase, voff) do { _Pragma("unroll") for (int _i = 0; _i < 2; ++_i) \
;         __builtin_amdgcn_global_load_lds((const unsigned*)((const char*)(gbase) + (voff)[_i]), (LAS unsigned*)(lds + (bufoff) + ldsw + _i * 8192), 16, 0, 0); } while (0)
; #define PG8_LDA(dst, b, h) do { _Pragma("unroll") for (int m = 0; m < 4; ++m) _Pragma("unroll") for (int k = 0; k < 2; ++k) dst[m][k] = *(const LAS bf16x8*)(pA + PG8_SA(b, h) + m * 2048 + k * 1024); } while (0)
; #define PG8_LDB(dst, b, h) do { _Pragma("unroll") for (int n = 0; n < 2; ++n) _Pragma("unroll") for (int k = 0; k < 2; ++k) dst[n][k] = *(const LAS bf16x8*)(pB + (PG8_SB(b, h) - 4 * HTB) + n * 2048 + k * 1024); } while (0)
; #define PG8_MMA(ai, bj, At, Bt) do { __builtin_amdgcn_s_setprio(1); _Pragma("unroll") for (int m = 0; m < 4; ++m) _Pragma("unroll") for (int n = 0; n < 2; ++n) _Pragma("unroll") for (int k = 0; k < 2; ++k) \
;         acc[ai][bj][m][n] = __builtin_amdgcn_mfma_f32_16x16x32_bf16(Bt[n][k], At[m][k], acc[ai][bj][m][n], 0, 0, 0); __builtin_amdgcn_s_setprio(0); } while (0)
; #define PG8_WAIT_V(n) asm volatile("s_waitcnt vmcnt(" #n ")" ::: "memory")
; #define PG8_WAIT_L(n) asm volatile("s_waitcnt lgkmcnt(" #n ")" ::: "memory")
; template <class Desc, class Epi, bool ALIGN_EPI>
; __device__ __forceinline__ void gemm_phase(LAS unsigned char* lds, const Desc& D, const Epi& E, int G, int c) {
;     ...
;             const bool last = (t == nt - 2);
;             if (last && has_next) PG8_AWAIT(nxt);
;             const char* a1 = cA + (size_t)(t + 1) * kstep;
;             const char* a2 = last ? nA : cA + (size_t)(t + 2) * kstep; const char* b2 = last ? nB : cB + (size_t)(t + 2) * kstep;
;             const char* a3 = a2 + kstep; const char* b3 = b2 + kstep;
;             PG8_LDB(B0, 0, 0); PG8_LDB(B1, 0, 1); PG8_SCHED; PG8_LDA(At, 0, 0); PG8_STAGE(PG8_SA(1, 1), a1 + hstepA, voffA);
;             PG8_WAIT_V(8); PG8_WAIT_L(0); PG8_BAR; PG8_MMA(0, 0, At, B0); PG8_MMA(0, 1, At, B1); PG8_BAR; PG8_SCHED;
;             PG8_LDA(At, 0, 1); PG8_STAGE(PG8_SB(0, 0), b2, voffB); PG8_STAGE(PG8_SB(0, 1), b2 + hstepB, voffB); PG8_STAGE(PG8_SA(0, 0), a2, voffA);
;             PG8_WAIT_V(8); PG8_WAIT_L(0); PG8_BAR; PG8_MMA(1, 0, At, B0); PG8_MMA(1, 1, At, B1); PG8_BAR; PG8_SCHED;
.LBB0_1580:
	s_or_b32 s14, s30, 1
	s_add_i32 s30, s30, 2
	s_mov_b32 s31, s15
	s_lshl_b64 s[72:73], s[14:15], 7
	s_lshl_b64 s[74:75], s[30:31], 7
	s_add_u32 s14, s18, s74
	ds_read_b128 v[140:143], v163
	ds_read_b128 v[144:147], v163 offset:1024
	ds_read_b128 v[148:151], v163 offset:2048
	ds_read_b128 v[152:155], v163 offset:3072
	ds_read_b128 v[156:159], v163 offset:16384
	ds_read_b128 v[166:169], v163 offset:17408
	ds_read_b128 v[170:173], v163 offset:18432
	ds_read_b128 v[174:177], v163 offset:19456
	s_addc_u32 s31, s19, s75
	s_and_b64 s[46:47], s[34:35], exec
	s_cselect_b32 s47, s43, s31
	s_cselect_b32 s46, s42, s14
	s_add_u32 s14, s20, s74
	s_addc_u32 s31, s21, s75
	s_and_b64 s[34:35], s[34:35], exec
	s_cselect_b32 s35, s3, s31
	s_cselect_b32 s34, s13, s14
	s_add_u32 s14, s18, s72
	s_addc_u32 s31, s19, s73
	s_add_u32 s72, s14, 0x100000
	s_addc_u32 s73, s31, 0
	s_add_i32 m0, s52, 0xc000
	ds_read_b128 v[178:181], v162
	ds_read_b128 v[182:185], v162 offset:1024
	ds_read_b128 v[186:189], v162 offset:2048
	ds_read_b128 v[190:193], v162 offset:3072
	ds_read_b128 v[194:197], v162 offset:4096
	ds_read_b128 v[198:201], v162 offset:5120
	ds_read_b128 v[202:205], v162 offset:6144
	ds_read_b128 v[206:209], v162 offset:7168
	global_load_lds_dwordx4 v132, s[72:73]
	s_add_i32 m0, s52, 0xe000
	s_nop 0
	global_load_lds_dwordx4 v136, s[72:73]
	s_waitcnt vmcnt(8)
	s_waitcnt lgkmcnt(0)
	s_barrier
	v_mfma_f32_16x16x32_bf16 v[128:131], v[140:143], v[178:181], v[128:131]
	v_mfma_f32_16x16x32_bf16 v[128:131], v[144:147], v[182:185], v[128:131]
	v_mfma_f32_16x16x32_bf16 v[124:127], v[148:151], v[178:181], v[124:127]
	v_mfma_f32_16x16x32_bf16 v[124:127], v[152:155], v[182:185], v[124:127]
	v_mfma_f32_16x16x32_bf16 v[96:99], v[156:159], v[178:181], v[96:99]
	v_mfma_f32_16x16x32_bf16 v[96:99], v[166:169], v[182:185], v[96:99]
	v_mfma_f32_16x16x32_bf16 v[92:95], v[170:173], v[178:181], v[92:95]
	v_mfma_f32_16x16x32_bf16 v[92:95], v[174:177], v[182:185], v[92:95]
	v_mfma_f32_16x16x32_bf16 v[84:87], v[170:173], v[186:189], v[84:87]
	v_mfma_f32_16x16x32_bf16 v[84:87], v[174:177], v[190:193], v[84:87]
	v_mfma_f32_16x16x32_bf16 v[88:91], v[156:159], v[186:189], v[88:91]
	v_mfma_f32_16x16x32_bf16 v[88:91], v[166:169], v[190:193], v[88:91]
	v_mfma_f32_16x16x32_bf16 v[116:119], v[148:151], v[186:189], v[116:119]
	v_mfma_f32_16x16x32_bf16 v[116:119], v[152:155], v[190:193], v[116:119]
	v_mfma_f32_16x16x32_bf16 v[120:123], v[140:143], v[186:189], v[120:123]
	v_mfma_f32_16x16x32_bf16 v[120:123], v[144:147], v[190:193], v[120:123]
	v_mfma_f32_16x16x32_bf16 v[112:115], v[140:143], v[194:197], v[112:115]
	v_mfma_f32_16x16x32_bf16 v[112:115], v[144:147], v[198:201], v[112:115]
	v_mfma_f32_16x16x32_bf16 v[108:111], v[148:151], v[194:197], v[108:111]
	v_mfma_f32_16x16x32_bf16 v[108:111], v[152:155], v[198:201], v[108:111]
	v_mfma_f32_16x16x32_bf16 v[80:83], v[156:159], v[194:197], v[80:83]
	v_mfma_f32_16x16x32_bf16 v[80:83], v[166:169], v[198:201], v[80:83]
	v_mfma_f32_16x16x32_bf16 v[76:79], v[170:173], v[194:197], v[76:79]
	v_mfma_f32_16x16x32_bf16 v[76:79], v[174:177], v[198:201], v[76:79]
	v_mfma_f32_16x16x32_bf16 v[68:71], v[170:173], v[202:205], v[68:71]
	v_mfma_f32_16x16x32_bf16 v[68:71], v[174:177], v[206:209], v[68:71]
	v_mfma_f32_16x16x32_bf16 v[72:75], v[156:159], v[202:205], v[72:75]
	v_mfma_f32_16x16x32_bf16 v[72:75], v[166:169], v[206:209], v[72:75]
	v_mfma_f32_16x16x32_bf16 v[100:103], v[148:151], v[202:205], v[100:103]
	v_mfma_f32_16x16x32_bf16 v[100:103], v[152:155], v[206:209], v[100:103]
	v_mfma_f32_16x16x32_bf16 v[104:107], v[140:143], v[202:205], v[104:107]
	v_mfma_f32_16x16x32_bf16 v[104:107], v[144:147], v[206:209], v[104:107]
	s_barrier
	s_mov_b32 m0, s53
	s_add_u32 s72, s34, 0x100000
	s_addc_u32 s73, s35, 0
	ds_read_b128 v[178:181], v162 offset:16384
	ds_read_b128 v[182:185], v162 offset:17408
	ds_read_b128 v[186:189], v162 offset:18432
	ds_read_b128 v[190:193], v162 offset:19456
	ds_read_b128 v[194:197], v162 offset:20480
	ds_read_b128 v[198:201], v162 offset:21504
	ds_read_b128 v[202:205], v162 offset:22528
	ds_read_b128 v[206:209], v162 offset:23552
	global_load_lds_dwordx4 v134, s[34:35]
	s_mov_b32 m0, s54
	s_nop 0
	global_load_lds_dwordx4 v138, s[34:35]
	s_mov_b32 m0, s55
	s_nop 0
	global_load_lds_dwordx4 v134, s[72:73]
	s_mov_b32 m0, s56
	s_nop 0
	global_load_lds_dwordx4 v138, s[72:73]
	s_mov_b32 m0, s52
	s_nop 0
	global_load_lds_dwordx4 v132, s[46:47]
	s_mov_b32 m0, s57
	s_nop 0
	global_load_lds_dwordx4 v136, s[46:47]
	s_waitcnt vmcnt(8)
	s_waitcnt lgkmcnt(0)
	s_barrier
; #define PG8_STAGE(bufoff, gbase, voff) do { _Pragma("unroll") for (int _i = 0; _i < 2; ++_i) \
;         __builtin_amdgcn_global_load_lds((const unsigned*)((const char*)(gbase) + (voff)[_i]), (LAS unsigned*)(lds + (bufoff) + ldsw + _i * 8192), 16, 0, 0); } while (0)
; #define PG8_LDA(dst, b, h) do { _Pragma("unroll") for (int m = 0; m < 4; ++m) _Pragma("unroll") for (int k = 0; k < 2; ++k) dst[m][k] = *(const LAS bf16x8*)(pA + PG8_SA(b, h) + m * 2048 + k * 1024); } while (0)
; #define PG8_LDB(dst, b, h) do { _Pragma("unroll") for (int n = 0; n < 2; ++n) _Pragma("unroll") for (int k = 0; k < 2; ++k) dst[n][k] = *(const LAS bf16x8*)(pB + (PG8_SB(b, h) - 4 * HTB) + n * 2048 + k * 1024); } while (0)
; #define PG8_MMA(ai, bj, At, Bt) do { __builtin_amdgcn_s_setprio(1); _Pragma("unroll") for (int m = 0; m < 4; ++m) _Pragma("unroll") for (int n = 0; n < 2; ++n) _Pragma("unroll") for (int k = 0; k < 2; ++k) \
;         acc[ai][bj][m][n] = __builtin_amdgcn_mfma_f32_16x16x32_bf16(Bt[n][k], At[m][k], acc[ai][bj][m][n], 0, 0, 0); __builtin_amdgcn_s_setprio(0); } while (0)
; #define PG8_WAIT_V(n) asm volatile("s_waitcnt vmcnt(" #n ")" ::: "memory")
; #define PG8_WAIT_L(n) asm volatile("s_waitcnt lgkmcnt(" #n ")" ::: "memory")
; #define PG8_BAR __builtin_amdgcn_s_barrier()
; #define PG8_SCHED __builtin_amdgcn_sched_barrier(0)
; template <class Desc, class Epi, bool ALIGN_EPI>
; __device__ __forceinline__ void gemm_phase(LAS unsigned char* lds, const Desc& D, const Epi& E, int G, int c) {
;     ...
;             PG8_WAIT_V(8); PG8_WAIT_L(0); PG8_BAR; PG8_MMA(1, 0, At, B0); PG8_MMA(1, 1, At, B1); PG8_BAR; PG8_SCHED;
;             PG8_LDB(B0, 1, 0); PG8_LDB(B1, 1, 1); PG8_SCHED; PG8_LDA(At, 1, 0); PG8_STAGE(PG8_SA(0, 1), a2 + hstepA, voffA);
;             PG8_WAIT_V(8); PG8_WAIT_L(0); PG8_BAR; PG8_MMA(0, 0, At, B0); PG8_MMA(0, 1, At, B1); PG8_BAR; PG8_SCHED;
	v_mfma_f32_16x16x32_bf16 v[64:67], v[140:143], v[178:181], v[64:67]
	v_mfma_f32_16x16x32_bf16 v[64:67], v[144:147], v[182:185], v[64:67]
	v_mfma_f32_16x16x32_bf16 v[52:55], v[148:151], v[178:181], v[52:55]
	v_mfma_f32_16x16x32_bf16 v[52:55], v[152:155], v[182:185], v[52:55]
	v_mfma_f32_16x16x32_bf16 v[60:63], v[156:159], v[178:181], v[60:63]
	v_mfma_f32_16x16x32_bf16 v[60:63], v[166:169], v[182:185], v[60:63]
	v_mfma_f32_16x16x32_bf16 v[56:59], v[170:173], v[178:181], v[56:59]
	v_mfma_f32_16x16x32_bf16 v[56:59], v[174:177], v[182:185], v[56:59]
	v_mfma_f32_16x16x32_bf16 v[44:47], v[170:173], v[186:189], v[44:47]
	v_mfma_f32_16x16x32_bf16 v[44:47], v[174:177], v[190:193], v[44:47]
	v_mfma_f32_16x16x32_bf16 v[48:51], v[156:159], v[186:189], v[48:51]
	v_mfma_f32_16x16x32_bf16 v[48:51], v[166:169], v[190:193], v[48:51]
	v_mfma_f32_16x16x32_bf16 v[20:23], v[148:151], v[186:189], v[20:23]
	v_mfma_f32_16x16x32_bf16 v[20:23], v[152:155], v[190:193], v[20:23]
	v_mfma_f32_16x16x32_bf16 v[32:35], v[140:143], v[186:189], v[32:35]
	v_mfma_f32_16x16x32_bf16 v[32:35], v[144:147], v[190:193], v[32:35]
	v_mfma_f32_16x16x32_bf16 v[16:19], v[140:143], v[194:197], v[16:19]
	v_mfma_f32_16x16x32_bf16 v[16:19], v[144:147], v[198:201], v[16:19]
	v_mfma_f32_16x16x32_bf16 v[12:15], v[148:151], v[194:197], v[12:15]
	v_mfma_f32_16x16x32_bf16 v[12:15], v[152:155], v[198:201], v[12:15]
	v_mfma_f32_16x16x32_bf16 v[40:43], v[156:159], v[194:197], v[40:43]
	v_mfma_f32_16x16x32_bf16 v[40:43], v[166:169], v[198:201], v[40:43]
	v_mfma_f32_16x16x32_bf16 v[36:39], v[170:173], v[194:197], v[36:39]
	v_mfma_f32_16x16x32_bf16 v[36:39], v[174:177], v[198:201], v[36:39]
	v_mfma_f32_16x16x32_bf16 v[24:27], v[170:173], v[202:205], v[24:27]
	v_mfma_f32_16x16x32_bf16 v[24:27], v[174:177], v[206:209], v[24:27]
	v_mfma_f32_16x16x32_bf16 v[28:31], v[156:159], v[202:205], v[28:31]
	v_mfma_f32_16x16x32_bf16 v[28:31], v[166:169], v[206:209], v[28:31]
	v_mfma_f32_16x16x32_bf16 v[4:7], v[148:151], v[202:205], v[4:7]
	v_mfma_f32_16x16x32_bf16 v[4:7], v[152:155], v[206:209], v[4:7]
	v_mfma_f32_16x16x32_bf16 v[8:11], v[140:143], v[202:205], v[8:11]
	v_mfma_f32_16x16x32_bf16 v[8:11], v[144:147], v[206:209], v[8:11]
	s_barrier
	ds_read_b128 v[140:143], v163 offset:32768
	ds_read_b128 v[144:147], v163 offset:33792
	ds_read_b128 v[148:151], v163 offset:34816
	ds_read_b128 v[152:155], v163 offset:35840
	ds_read_b128 v[156:159], v163 offset:49152
	ds_read_b128 v[166:169], v163 offset:50176
	ds_read_b128 v[170:173], v163 offset:51200
	ds_read_b128 v[174:177], v163 offset:52224
	s_add_u32 s46, s46, 0x100000
	s_addc_u32 s47, s47, 0
	s_mov_b32 m0, s58
	ds_read_b128 v[178:181], v162 offset:32768
	ds_read_b128 v[182:185], v162 offset:33792
	ds_read_b128 v[186:189], v162 offset:34816
	ds_read_b128 v[190:193], v162 offset:35840
	ds_read_b128 v[194:197], v162 offset:36864
	ds_read_b128 v[198:201], v162 offset:37888
	ds_read_b128 v[202:205], v162 offset:38912
	ds_read_b128 v[206:209], v162 offset:39936
	global_load_lds_dwordx4 v132, s[46:47]
	s_mov_b32 m0, s59
	s_nop 0
	global_load_lds_dwordx4 v136, s[46:47]
	s_waitcnt vmcnt(8)
	s_waitcnt lgkmcnt(0)
	s_barrier
	v_mfma_f32_16x16x32_bf16 v[128:131], v[140:143], v[178:181], v[128:131]
	v_mfma_f32_16x16x32_bf16 v[128:131], v[144:147], v[182:185], v[128:131]
	v_mfma_f32_16x16x32_bf16 v[124:127], v[148:151], v[178:181], v[124:127]
	v_mfma_f32_16x16x32_bf16 v[124:127], v[152:155], v[182:185], v[124:127]
	v_mfma_f32_16x16x32_bf16 v[96:99], v[156:159], v[178:181], v[96:99]
	v_mfma_f32_16x16x32_bf16 v[96:99], v[166:169], v[182:185], v[96:99]
	v_mfma_f32_16x16x32_bf16 v[92:95], v[170:173], v[178:181], v[92:95]
	v_mfma_f32_16x16x32_bf16 v[92:95], v[174:177], v[182:185], v[92:95]
	v_mfma_f32_16x16x32_bf16 v[84:87], v[170:173], v[186:189], v[84:87]
	v_mfma_f32_16x16x32_bf16 v[84:87], v[174:177], v[190:193], v[84:87]
	v_mfma_f32_16x16x32_bf16 v[88:91], v[156:159], v[186:189], v[88:91]
	v_mfma_f32_16x16x32_bf16 v[88:91], v[166:169], v[190:193], v[88:91]
	v_mfma_f32_16x16x32_bf16 v[116:119], v[148:151], v[186:189], v[116:119]
	v_mfma_f32_16x16x32_bf16 v[116:119], v[152:155], v[190:193], v[116:119]
	v_mfma_f32_16x16x32_bf16 v[120:123], v[140:143], v[186:189], v[120:123]
	v_mfma_f32_16x16x32_bf16 v[120:123], v[144:147], v[190:193], v[120:123]
	v_mfma_f32_16x16x32_bf16 v[112:115], v[140:143], v[194:197], v[112:115]
	v_mfma_f32_16x16x32_bf16 v[112:115], v[144:147], v[198:201], v[112:115]
	v_mfma_f32_16x16x32_bf16 v[108:111], v[148:151], v[194:197], v[108:111]
	v_mfma_f32_16x16x32_bf16 v[108:111], v[152:155], v[198:201], v[108:111]
	v_mfma_f32_16x16x32_bf16 v[80:83], v[156:159], v[194:197], v[80:83]
	v_mfma_f32_16x16x32_bf16 v[80:83], v[166:169], v[198:201], v[80:83]
	v_mfma_f32_16x16x32_bf16 v[76:79], v[170:173], v[194:197], v[76:79]
	v_mfma_f32_16x16x32_bf16 v[76:79], v[174:177], v[198:201], v[76:79]
	v_mfma_f32_16x16x32_bf16 v[68:71], v[170:173], v[202:205], v[68:71]
	v_mfma_f32_16x16x32_bf16 v[68:71], v[174:177], v[206:209], v[68:71]
	v_mfma_f32_16x16x32_bf16 v[72:75], v[156:159], v[202:205], v[72:75]
	v_mfma_f32_16x16x32_bf16 v[72:75], v[166:169], v[206:209], v[72:75]
	v_mfma_f32_16x16x32_bf16 v[100:103], v[148:151], v[202:205], v[100:103]
	v_mfma_f32_16x16x32_bf16 v[100:103], v[152:155], v[206:209], v[100:103]
	v_mfma_f32_16x16x32_bf16 v[104:107], v[140:143], v[202:205], v[104:107]
	v_mfma_f32_16x16x32_bf16 v[104:107], v[144:147], v[206:209], v[104:107]
	s_barrier
; #define PG8_STAGE(bufoff, gbase, voff) do { _Pragma("unroll") for (int _i = 0; _i < 2; ++_i) \
;         __builtin_amdgcn_global_load_lds((const unsigned*)((const char*)(gbase) + (voff)[_i]), (LAS unsigned*)(lds + (bufoff) + ldsw + _i * 8192), 16, 0, 0); } while (0)
; #define PG8_LDA(dst, b, h) do { _Pragma("unroll") for (int m = 0; m < 4; ++m) _Pragma("unroll") for (int k = 0; k < 2; ++k) dst[m][k] = *(const LAS bf16x8*)(pA + PG8_SA(b, h) + m * 2048 + k * 1024); } while (0)
; #define PG8_MMA(ai, bj, At, Bt) do { __builtin_amdgcn_s_setprio(1); _Pragma("unroll") for (int m = 0; m < 4; ++m) _Pragma("unroll") for (int n = 0; n < 2; ++n) _Pragma("unroll") for (int k = 0; k < 2; ++k) \
;         acc[ai][bj][m][n] = __builtin_amdgcn_mfma_f32_16x16x32_bf16(Bt[n][k], At[m][k], acc[ai][bj][m][n], 0, 0, 0); __builtin_amdgcn_s_setprio(0); } while (0)
; #define PG8_WAIT_V(n) asm volatile("s_waitcnt vmcnt(" #n ")" ::: "memory")
; #define PG8_WAIT_L(n) asm volatile("s_waitcnt lgkmcnt(" #n ")" ::: "memory")
; #define PG8_BAR __builtin_amdgcn_s_barrier()
; #define PG8_SCHED __builtin_amdgcn_sched_barrier(0)
; template <class Desc, class Epi, bool ALIGN_EPI>
; __device__ __forceinline__ void gemm_phase(LAS unsigned char* lds, const Desc& D, const Epi& E, int G, int c) {
;     ...
;             PG8_LDA(At, 1, 1); PG8_STAGE(PG8_SB(1, 0), b3, voffB); PG8_STAGE(PG8_SB(1, 1), b3 + hstepB, voffB); PG8_STAGE(PG8_SA(1, 0), a3, voffA);
;             PG8_WAIT_V(8); PG8_WAIT_L(0); PG8_BAR; PG8_MMA(1, 0, At, B0); PG8_MMA(1, 1, At, B1); PG8_BAR; PG8_SCHED;
;         }
	s_mov_b32 m0, s61
	s_add_u32 s74, s34, 0x80
	s_addc_u32 s75, s35, 0
	s_add_u32 s34, s34, 0x100080
	s_addc_u32 s35, s35, 0
	ds_read_b128 v[178:181], v162 offset:49152
	ds_read_b128 v[182:185], v162 offset:50176
	ds_read_b128 v[186:189], v162 offset:51200
	ds_read_b128 v[190:193], v162 offset:52224
	ds_read_b128 v[194:197], v162 offset:53248
	ds_read_b128 v[198:201], v162 offset:54272
	ds_read_b128 v[202:205], v162 offset:55296
	ds_read_b128 v[206:209], v162 offset:56320
	global_load_lds_dwordx4 v134, s[74:75]
	s_mov_b32 m0, s62
	s_nop 0
	global_load_lds_dwordx4 v138, s[74:75]
	s_mov_b32 m0, s65
	s_nop 0
	global_load_lds_dwordx4 v134, s[34:35]
	s_mov_b32 m0, s67
	s_nop 0
	global_load_lds_dwordx4 v138, s[34:35]
	s_sub_u32 s74, s46, 0xfff80
	s_subb_u32 s75, s47, 0
	s_mov_b32 m0, s63
	s_nop 0
	global_load_lds_dwordx4 v132, s[74:75]
	s_mov_b32 m0, s64
	s_nop 0
	global_load_lds_dwordx4 v136, s[74:75]
	s_waitcnt vmcnt(8)
	s_waitcnt lgkmcnt(0)
	s_barrier
	v_mfma_f32_16x16x32_bf16 v[64:67], v[140:143], v[178:181], v[64:67]
	v_mfma_f32_16x16x32_bf16 v[64:67], v[144:147], v[182:185], v[64:67]
	v_mfma_f32_16x16x32_bf16 v[52:55], v[148:151], v[178:181], v[52:55]
	v_mfma_f32_16x16x32_bf16 v[52:55], v[152:155], v[182:185], v[52:55]
	v_mfma_f32_16x16x32_bf16 v[60:63], v[156:159], v[178:181], v[60:63]
	v_mfma_f32_16x16x32_bf16 v[60:63], v[166:169], v[182:185], v[60:63]
	v_mfma_f32_16x16x32_bf16 v[56:59], v[170:173], v[178:181], v[56:59]
	v_mfma_f32_16x16x32_bf16 v[56:59], v[174:177], v[182:185], v[56:59]
	v_mfma_f32_16x16x32_bf16 v[44:47], v[170:173], v[186:189], v[44:47]
	v_mfma_f32_16x16x32_bf16 v[44:47], v[174:177], v[190:193], v[44:47]
	v_mfma_f32_16x16x32_bf16 v[48:51], v[156:159], v[186:189], v[48:51]
	v_mfma_f32_16x16x32_bf16 v[48:51], v[166:169], v[190:193], v[48:51]
	v_mfma_f32_16x16x32_bf16 v[20:23], v[148:151], v[186:189], v[20:23]
	v_mfma_f32_16x16x32_bf16 v[20:23], v[152:155], v[190:193], v[20:23]
	v_mfma_f32_16x16x32_bf16 v[32:35], v[140:143], v[186:189], v[32:35]
	v_mfma_f32_16x16x32_bf16 v[32:35], v[144:147], v[190:193], v[32:35]
	v_mfma_f32_16x16x32_bf16 v[16:19], v[140:143], v[194:197], v[16:19]
	v_mfma_f32_16x16x32_bf16 v[16:19], v[144:147], v[198:201], v[16:19]
	v_mfma_f32_16x16x32_bf16 v[12:15], v[148:151], v[194:197], v[12:15]
	v_mfma_f32_16x16x32_bf16 v[12:15], v[152:155], v[198:201], v[12:15]
	v_mfma_f32_16x16x32_bf16 v[40:43], v[156:159], v[194:197], v[40:43]
	v_mfma_f32_16x16x32_bf16 v[40:43], v[166:169], v[198:201], v[40:43]
	v_mfma_f32_16x16x32_bf16 v[36:39], v[170:173], v[194:197], v[36:39]
	v_mfma_f32_16x16x32_bf16 v[36:39], v[174:177], v[198:201], v[36:39]
	v_mfma_f32_16x16x32_bf16 v[24:27], v[170:173], v[202:205], v[24:27]
	v_mfma_f32_16x16x32_bf16 v[24:27], v[174:177], v[206:209], v[24:27]
	v_mfma_f32_16x16x32_bf16 v[28:31], v[156:159], v[202:205], v[28:31]
	v_mfma_f32_16x16x32_bf16 v[28:31], v[166:169], v[206:209], v[28:31]
	v_mfma_f32_16x16x32_bf16 v[4:7], v[148:151], v[202:205], v[4:7]
	v_mfma_f32_16x16x32_bf16 v[4:7], v[152:155], v[206:209], v[4:7]
	v_mfma_f32_16x16x32_bf16 v[8:11], v[140:143], v[202:205], v[8:11]
	v_mfma_f32_16x16x32_bf16 v[8:11], v[144:147], v[206:209], v[8:11]
	s_barrier
	s_cmp_ge_u32 s30, s2
	s_cbranch_scc1 .LBB0_1591

;     __device__ __forceinline__ int nt(const Unit& u) const { return (u.pn >> 1) < 2 ? 22 : 20; }
; #define PG8_STAGE(bufoff, gbase, voff) do { _Pragma("unroll") for (int _i = 0; _i < 2; ++_i) \
;         __builtin_amdgcn_global_load_lds((const unsigned*)((const char*)(gbase) + (voff)[_i]), (LAS unsigned*)(lds + (bufoff) + ldsw + _i * 8192), 16, 0, 0); } while (0)
; #define PG8_LDA(dst, b, h) do { _Pragma("unroll") for (int m = 0; m < 4; ++m) _Pragma("unroll") for (int k = 0; k < 2; ++k) dst[m][k] = *(const LAS bf16x8*)(pA + PG8_SA(b, h) + m * 2048 + k * 1024); } while (0)
; #define PG8_LDB(dst, b, h) do { _Pragma("unroll") for (int n = 0; n < 2; ++n) _Pragma("unroll") for (int k = 0; k < 2; ++k) dst[n][k] = *(const LAS bf16x8*)(pB + (PG8_SB(b, h) - 4 * HTB) + n * 2048 + k * 1024); } while (0)
; #define PG8_MMA(ai, bj, At, Bt) do { __builtin_amdgcn_s_setprio(1); _Pragma("unroll") for (int m = 0; m < 4; ++m) _Pragma("unroll") for (int n = 0; n < 2; ++n) _Pragma("unroll") for (int k = 0; k < 2; ++k) \
;         acc[ai][bj][m][n] = __builtin_amdgcn_mfma_f32_16x16x32_bf16(Bt[n][k], At[m][k], acc[ai][bj][m][n], 0, 0, 0); __builtin_amdgcn_s_setprio(0); } while (0)
; #define PG8_WAIT_V(n) asm volatile("s_waitcnt vmcnt(" #n ")" ::: "memory")
; #define PG8_WAIT_L(n) asm volatile("s_waitcnt lgkmcnt(" #n ")" ::: "memory")
; template <class Desc, class Epi, bool ALIGN_EPI>
; __device__ __forceinline__ void gemm_phase(LAS unsigned char* lds, const Desc& D, const Epi& E, int G, int c) {
;     ...
;             const bool last = (t == nt - 2);
;             if (last && has_next) PG8_AWAIT(nxt);
;             const char* a1 = cA + (size_t)(t + 1) * kstep;
;             const char* a2 = last ? nA : cA + (size_t)(t + 2) * kstep; const char* b2 = last ? nB : cB + (size_t)(t + 2) * kstep;
;             const char* a3 = a2 + kstep; const char* b3 = b2 + kstep;
;             PG8_LDB(B0, 0, 0); PG8_LDB(B1, 0, 1); PG8_SCHED; PG8_LDA(At, 0, 0); PG8_STAGE(PG8_SA(1, 1), a1 + hstepA, voffA);
;             PG8_WAIT_V(8); PG8_WAIT_L(0); PG8_BAR; PG8_MMA(0, 0, At, B0); PG8_MMA(0, 1, At, B1); PG8_BAR; PG8_SCHED;
;             PG8_LDA(At, 0, 1); PG8_STAGE(PG8_SB(0, 0), b2, voffB); PG8_STAGE(PG8_SB(0, 1), b2 + hstepB, voffB); PG8_STAGE(PG8_SA(0, 0), a2, voffA);
;             PG8_WAIT_V(8); PG8_WAIT_L(0); PG8_BAR; PG8_MMA(1, 0, At, B0); PG8_MMA(1, 1, At, B1); PG8_BAR; PG8_SCHED;
.LBB0_1765:
	s_or_b32 s14, s39, 1
	s_lshl_b64 s[40:41], s[14:15], 7
	s_add_i32 s14, s39, 2
	s_lshl_b64 s[42:43], s[14:15], 7
	s_add_u32 s39, s12, s42
	s_waitcnt lgkmcnt(0)
	ds_read_b128 v[132:135], v248
	ds_read_b128 v[136:139], v248 offset:1024
	ds_read_b128 v[140:143], v248 offset:2048
	ds_read_b128 v[144:147], v248 offset:3072
	ds_read_b128 v[148:151], v248 offset:16384
	ds_read_b128 v[152:155], v248 offset:17408
	ds_read_b128 v[156:159], v248 offset:18432
	ds_read_b128 v[160:163], v248 offset:19456
	s_addc_u32 s78, s13, s43
	s_and_b64 s[30:31], s[20:21], exec
	s_cselect_b32 s31, s49, s78
	s_cselect_b32 s30, s48, s39
	s_add_u32 s39, s16, s42
	s_addc_u32 s42, s17, s43
	s_and_b64 s[20:21], s[20:21], exec
	s_cselect_b32 s21, s51, s42
	s_cselect_b32 s20, s50, s39
	s_add_u32 s39, s12, s40
	s_addc_u32 s41, s13, s41
	s_add_u32 s40, s39, 0x2b0000
	s_addc_u32 s41, s41, 0
	v_lshl_add_u64 v[196:197], s[40:41], 0, v[200:201]
	s_add_i32 m0, s56, 0xc000
	ds_read_b128 v[164:167], v247
	ds_read_b128 v[168:171], v247 offset:1024
	ds_read_b128 v[172:175], v247 offset:2048
	ds_read_b128 v[176:179], v247 offset:3072
	ds_read_b128 v[180:183], v247 offset:4096
	ds_read_b128 v[184:187], v247 offset:5120
	ds_read_b128 v[188:191], v247 offset:6144
	ds_read_b128 v[192:195], v247 offset:7168
	global_load_lds_dwordx4 v[196:197], off
	v_lshl_add_u64 v[196:197], s[40:41], 0, v[204:205]
	s_add_i32 m0, s56, 0xe000
	s_nop 0
	global_load_lds_dwordx4 v[196:197], off
	s_waitcnt vmcnt(8)
	s_waitcnt lgkmcnt(0)
	s_barrier
	v_mfma_f32_16x16x32_bf16 v[128:131], v[132:135], v[164:167], v[128:131]
	v_mfma_f32_16x16x32_bf16 v[128:131], v[136:139], v[168:171], v[128:131]
	v_mfma_f32_16x16x32_bf16 v[124:127], v[140:143], v[164:167], v[124:127]
	v_mfma_f32_16x16x32_bf16 v[124:127], v[144:147], v[168:171], v[124:127]
	v_mfma_f32_16x16x32_bf16 v[96:99], v[148:151], v[164:167], v[96:99]
	v_mfma_f32_16x16x32_bf16 v[96:99], v[152:155], v[168:171], v[96:99]
	v_mfma_f32_16x16x32_bf16 v[92:95], v[156:159], v[164:167], v[92:95]
	v_mfma_f32_16x16x32_bf16 v[92:95], v[160:163], v[168:171], v[92:95]
	v_mfma_f32_16x16x32_bf16 v[80:83], v[156:159], v[172:175], v[80:83]
	v_mfma_f32_16x16x32_bf16 v[80:83], v[160:163], v[176:179], v[80:83]
	v_mfma_f32_16x16x32_bf16 v[88:91], v[148:151], v[172:175], v[88:91]
	v_mfma_f32_16x16x32_bf16 v[88:91], v[152:155], v[176:179], v[88:91]
	v_mfma_f32_16x16x32_bf16 v[116:119], v[140:143], v[172:175], v[116:119]
	v_mfma_f32_16x16x32_bf16 v[116:119], v[144:147], v[176:179], v[116:119]
	v_mfma_f32_16x16x32_bf16 v[120:123], v[132:135], v[172:175], v[120:123]
	v_mfma_f32_16x16x32_bf16 v[120:123], v[136:139], v[176:179], v[120:123]
	v_mfma_f32_16x16x32_bf16 v[112:115], v[132:135], v[180:183], v[112:115]
	v_mfma_f32_16x16x32_bf16 v[112:115], v[136:139], v[184:187], v[112:115]
	v_mfma_f32_16x16x32_bf16 v[108:111], v[140:143], v[180:183], v[108:111]
	v_mfma_f32_16x16x32_bf16 v[108:111], v[144:147], v[184:187], v[108:111]
	v_mfma_f32_16x16x32_bf16 v[64:67], v[148:151], v[180:183], v[64:67]
	v_mfma_f32_16x16x32_bf16 v[64:67], v[152:155], v[184:187], v[64:67]
	v_mfma_f32_16x16x32_bf16 v[52:55], v[156:159], v[180:183], v[52:55]
	v_mfma_f32_16x16x32_bf16 v[52:55], v[160:163], v[184:187], v[52:55]
	v_mfma_f32_16x16x32_bf16 v[20:23], v[156:159], v[188:191], v[20:23]
	v_mfma_f32_16x16x32_bf16 v[20:23], v[160:163], v[192:195], v[20:23]
	v_mfma_f32_16x16x32_bf16 v[32:35], v[148:151], v[188:191], v[32:35]
	v_mfma_f32_16x16x32_bf16 v[32:35], v[152:155], v[192:195], v[32:35]
	v_mfma_f32_16x16x32_bf16 v[100:103], v[140:143], v[188:191], v[100:103]
	v_mfma_f32_16x16x32_bf16 v[100:103], v[144:147], v[192:195], v[100:103]
	v_mfma_f32_16x16x32_bf16 v[104:107], v[132:135], v[188:191], v[104:107]
	v_mfma_f32_16x16x32_bf16 v[104:107], v[136:139], v[192:195], v[104:107]
	s_barrier
	s_mov_b32 m0, s57
	v_lshl_add_u64 v[196:197], s[20:21], 0, v[202:203]
	s_add_u32 s40, s20, 0x2b0000
	ds_read_b128 v[164:167], v247 offset:16384
	ds_read_b128 v[168:171], v247 offset:17408
	ds_read_b128 v[172:175], v247 offset:18432
	ds_read_b128 v[176:179], v247 offset:19456
	ds_read_b128 v[180:183], v247 offset:20480
	ds_read_b128 v[184:187], v247 offset:21504
	ds_read_b128 v[188:191], v247 offset:22528
	ds_read_b128 v[192:195], v247 offset:23552
	global_load_lds_dwordx4 v[196:197], off
	v_lshl_add_u64 v[198:199], s[20:21], 0, v[206:207]
	s_mov_b32 m0, s58
	s_addc_u32 s41, s21, 0
	global_load_lds_dwordx4 v[198:199], off
	v_lshl_add_u64 v[208:209], s[40:41], 0, v[202:203]
	s_mov_b32 m0, s59
	v_lshl_add_u64 v[210:211], s[30:31], 0, v[204:205]
	global_load_lds_dwordx4 v[208:209], off
	v_lshl_add_u64 v[208:209], s[40:41], 0, v[206:207]
	s_mov_b32 m0, s60
	s_nop 0
	global_load_lds_dwordx4 v[208:209], off
	v_lshl_add_u64 v[208:209], s[30:31], 0, v[200:201]
	s_mov_b32 m0, s56
	s_nop 0
	global_load_lds_dwordx4 v[208:209], off
	s_mov_b32 m0, s61
	s_nop 0
	global_load_lds_dwordx4 v[210:211], off
	s_waitcnt vmcnt(8)
	s_waitcnt lgkmcnt(0)
	s_barrier
; #define PG8_STAGE(bufoff, gbase, voff) do { _Pragma("unroll") for (int _i = 0; _i < 2; ++_i) \
;         __builtin_amdgcn_global_load_lds((const unsigned*)((const char*)(gbase) + (voff)[_i]), (LAS unsigned*)(lds + (bufoff) + ldsw + _i * 8192), 16, 0, 0); } while (0)
; #define PG8_LDA(dst, b, h) do { _Pragma("unroll") for (int m = 0; m < 4; ++m) _Pragma("unroll") for (int k = 0; k < 2; ++k) dst[m][k] = *(const LAS bf16x8*)(pA + PG8_SA(b, h) + m * 2048 + k * 1024); } while (0)
; #define PG8_LDB(dst, b, h) do { _Pragma("unroll") for (int n = 0; n < 2; ++n) _Pragma("unroll") for (int k = 0; k < 2; ++k) dst[n][k] = *(const LAS bf16x8*)(pB + (PG8_SB(b, h) - 4 * HTB) + n * 2048 + k * 1024); } while (0)
; #define PG8_MMA(ai, bj, At, Bt) do { __builtin_amdgcn_s_setprio(1); _Pragma("unroll") for (int m = 0; m < 4; ++m) _Pragma("unroll") for (int n = 0; n < 2; ++n) _Pragma("unroll") for (int k = 0; k < 2; ++k) \
;         acc[ai][bj][m][n] = __builtin_amdgcn_mfma_f32_16x16x32_bf16(Bt[n][k], At[m][k], acc[ai][bj][m][n], 0, 0, 0); __builtin_amdgcn_s_setprio(0); } while (0)
; #define PG8_WAIT_V(n) asm volatile("s_waitcnt vmcnt(" #n ")" ::: "memory")
; #define PG8_WAIT_L(n) asm volatile("s_waitcnt lgkmcnt(" #n ")" ::: "memory")
; #define PG8_BAR __builtin_amdgcn_s_barrier()
; #define PG8_SCHED __builtin_amdgcn_sched_barrier(0)
; template <class Desc, class Epi, bool ALIGN_EPI>
; __device__ __forceinline__ void gemm_phase(LAS unsigned char* lds, const Desc& D, const Epi& E, int G, int c) {
;     ...
;             PG8_WAIT_V(8); PG8_WAIT_L(0); PG8_BAR; PG8_MMA(1, 0, At, B0); PG8_MMA(1, 1, At, B1); PG8_BAR; PG8_SCHED;
;             PG8_LDB(B0, 1, 0); PG8_LDB(B1, 1, 1); PG8_SCHED; PG8_LDA(At, 1, 0); PG8_STAGE(PG8_SA(0, 1), a2 + hstepA, voffA);
;             PG8_WAIT_V(8); PG8_WAIT_L(0); PG8_BAR; PG8_MMA(0, 0, At, B0); PG8_MMA(0, 1, At, B1); PG8_BAR; PG8_SCHED;
	v_mfma_f32_16x16x32_bf16 v[84:87], v[132:135], v[164:167], v[84:87]
	v_mfma_f32_16x16x32_bf16 v[84:87], v[136:139], v[168:171], v[84:87]
	v_mfma_f32_16x16x32_bf16 v[76:79], v[140:143], v[164:167], v[76:79]
	v_mfma_f32_16x16x32_bf16 v[76:79], v[144:147], v[168:171], v[76:79]
	v_mfma_f32_16x16x32_bf16 v[40:43], v[148:151], v[164:167], v[40:43]
	v_mfma_f32_16x16x32_bf16 v[40:43], v[152:155], v[168:171], v[40:43]
	v_mfma_f32_16x16x32_bf16 v[36:39], v[156:159], v[164:167], v[36:39]
	v_mfma_f32_16x16x32_bf16 v[36:39], v[160:163], v[168:171], v[36:39]
	v_mfma_f32_16x16x32_bf16 v[24:27], v[156:159], v[172:175], v[24:27]
	v_mfma_f32_16x16x32_bf16 v[24:27], v[160:163], v[176:179], v[24:27]
	v_mfma_f32_16x16x32_bf16 v[28:31], v[148:151], v[172:175], v[28:31]
	v_mfma_f32_16x16x32_bf16 v[28:31], v[152:155], v[176:179], v[28:31]
	v_mfma_f32_16x16x32_bf16 v[68:71], v[140:143], v[172:175], v[68:71]
	v_mfma_f32_16x16x32_bf16 v[68:71], v[144:147], v[176:179], v[68:71]
	v_mfma_f32_16x16x32_bf16 v[72:75], v[132:135], v[172:175], v[72:75]
	v_mfma_f32_16x16x32_bf16 v[72:75], v[136:139], v[176:179], v[72:75]
	v_mfma_f32_16x16x32_bf16 v[60:63], v[132:135], v[180:183], v[60:63]
	v_mfma_f32_16x16x32_bf16 v[60:63], v[136:139], v[184:187], v[60:63]
	v_mfma_f32_16x16x32_bf16 v[56:59], v[140:143], v[180:183], v[56:59]
	v_mfma_f32_16x16x32_bf16 v[56:59], v[144:147], v[184:187], v[56:59]
	v_mfma_f32_16x16x32_bf16 v[16:19], v[148:151], v[180:183], v[16:19]
	v_mfma_f32_16x16x32_bf16 v[16:19], v[152:155], v[184:187], v[16:19]
	v_mfma_f32_16x16x32_bf16 v[12:15], v[156:159], v[180:183], v[12:15]
	v_mfma_f32_16x16x32_bf16 v[12:15], v[160:163], v[184:187], v[12:15]
	v_mfma_f32_16x16x32_bf16 v[4:7], v[156:159], v[188:191], v[4:7]
	v_mfma_f32_16x16x32_bf16 v[4:7], v[160:163], v[192:195], v[4:7]
	v_mfma_f32_16x16x32_bf16 v[8:11], v[148:151], v[188:191], v[8:11]
	v_mfma_f32_16x16x32_bf16 v[8:11], v[152:155], v[192:195], v[8:11]
	v_mfma_f32_16x16x32_bf16 v[44:47], v[140:143], v[188:191], v[44:47]
	v_mfma_f32_16x16x32_bf16 v[44:47], v[144:147], v[192:195], v[44:47]
	v_mfma_f32_16x16x32_bf16 v[48:51], v[132:135], v[188:191], v[48:51]
	v_mfma_f32_16x16x32_bf16 v[48:51], v[136:139], v[192:195], v[48:51]
	s_barrier
	ds_read_b128 v[132:135], v248 offset:32768
	ds_read_b128 v[136:139], v248 offset:33792
	ds_read_b128 v[140:143], v248 offset:34816
	ds_read_b128 v[144:147], v248 offset:35840
	ds_read_b128 v[148:151], v248 offset:49152
	ds_read_b128 v[152:155], v248 offset:50176
	ds_read_b128 v[156:159], v248 offset:51200
	ds_read_b128 v[160:163], v248 offset:52224
	s_add_u32 s30, s30, 0x2b0000
	s_addc_u32 s31, s31, 0
	s_mov_b32 m0, s62
	v_lshl_add_u64 v[212:213], s[30:31], 0, v[200:201]
	ds_read_b128 v[164:167], v247 offset:32768
	ds_read_b128 v[168:171], v247 offset:33792
	ds_read_b128 v[172:175], v247 offset:34816
	ds_read_b128 v[176:179], v247 offset:35840
	ds_read_b128 v[180:183], v247 offset:36864
	ds_read_b128 v[184:187], v247 offset:37888
	ds_read_b128 v[188:191], v247 offset:38912
	ds_read_b128 v[192:195], v247 offset:39936
	global_load_lds_dwordx4 v[212:213], off
	v_lshl_add_u64 v[212:213], s[30:31], 0, v[204:205]
	s_mov_b32 m0, s63
	s_nop 0
	global_load_lds_dwordx4 v[212:213], off
	s_waitcnt vmcnt(8)
	s_waitcnt lgkmcnt(0)
	s_barrier
	v_mfma_f32_16x16x32_bf16 v[128:131], v[132:135], v[164:167], v[128:131]
	v_mfma_f32_16x16x32_bf16 v[128:131], v[136:139], v[168:171], v[128:131]
	v_mfma_f32_16x16x32_bf16 v[124:127], v[140:143], v[164:167], v[124:127]
	v_mfma_f32_16x16x32_bf16 v[124:127], v[144:147], v[168:171], v[124:127]
	v_mfma_f32_16x16x32_bf16 v[96:99], v[148:151], v[164:167], v[96:99]
	v_mfma_f32_16x16x32_bf16 v[96:99], v[152:155], v[168:171], v[96:99]
	v_mfma_f32_16x16x32_bf16 v[92:95], v[156:159], v[164:167], v[92:95]
	v_mfma_f32_16x16x32_bf16 v[92:95], v[160:163], v[168:171], v[92:95]
	v_mfma_f32_16x16x32_bf16 v[80:83], v[156:159], v[172:175], v[80:83]
	v_mfma_f32_16x16x32_bf16 v[80:83], v[160:163], v[176:179], v[80:83]
	v_mfma_f32_16x16x32_bf16 v[88:91], v[148:151], v[172:175], v[88:91]
	v_mfma_f32_16x16x32_bf16 v[88:91], v[152:155], v[176:179], v[88:91]
	v_mfma_f32_16x16x32_bf16 v[116:119], v[140:143], v[172:175], v[116:119]
	v_mfma_f32_16x16x32_bf16 v[116:119], v[144:147], v[176:179], v[116:119]
	v_mfma_f32_16x16x32_bf16 v[120:123], v[132:135], v[172:175], v[120:123]
	v_mfma_f32_16x16x32_bf16 v[120:123], v[136:139], v[176:179], v[120:123]
	v_mfma_f32_16x16x32_bf16 v[112:115], v[132:135], v[180:183], v[112:115]
	v_mfma_f32_16x16x32_bf16 v[112:115], v[136:139], v[184:187], v[112:115]
	v_mfma_f32_16x16x32_bf16 v[108:111], v[140:143], v[180:183], v[108:111]
	v_mfma_f32_16x16x32_bf16 v[108:111], v[144:147], v[184:187], v[108:111]
	v_mfma_f32_16x16x32_bf16 v[64:67], v[148:151], v[180:183], v[64:67]
	v_mfma_f32_16x16x32_bf16 v[64:67], v[152:155], v[184:187], v[64:67]
	v_mfma_f32_16x16x32_bf16 v[52:55], v[156:159], v[180:183], v[52:55]
	v_mfma_f32_16x16x32_bf16 v[52:55], v[160:163], v[184:187], v[52:55]
	v_mfma_f32_16x16x32_bf16 v[20:23], v[156:159], v[188:191], v[20:23]
	v_mfma_f32_16x16x32_bf16 v[20:23], v[160:163], v[192:195], v[20:23]
	v_mfma_f32_16x16x32_bf16 v[32:35], v[148:151], v[188:191], v[32:35]
	v_mfma_f32_16x16x32_bf16 v[32:35], v[152:155], v[192:195], v[32:35]
	v_mfma_f32_16x16x32_bf16 v[100:103], v[140:143], v[188:191], v[100:103]
	v_mfma_f32_16x16x32_bf16 v[100:103], v[144:147], v[192:195], v[100:103]
	v_mfma_f32_16x16x32_bf16 v[104:107], v[132:135], v[188:191], v[104:107]
	v_mfma_f32_16x16x32_bf16 v[104:107], v[136:139], v[192:195], v[104:107]
	s_barrier
; #define PG8_STAGE(bufoff, gbase, voff) do { _Pragma("unroll") for (int _i = 0; _i < 2; ++_i) \
;         __builtin_amdgcn_global_load_lds((const unsigned*)((const char*)(gbase) + (voff)[_i]), (LAS unsigned*)(lds + (bufoff) + ldsw + _i * 8192), 16, 0, 0); } while (0)
; #define PG8_LDA(dst, b, h) do { _Pragma("unroll") for (int m = 0; m < 4; ++m) _Pragma("unroll") for (int k = 0; k < 2; ++k) dst[m][k] = *(const LAS bf16x8*)(pA + PG8_SA(b, h) + m * 2048 + k * 1024); } while (0)
; #define PG8_MMA(ai, bj, At, Bt) do { __builtin_amdgcn_s_setprio(1); _Pragma("unroll") for (int m = 0; m < 4; ++m) _Pragma("unroll") for (int n = 0; n < 2; ++n) _Pragma("unroll") for (int k = 0; k < 2; ++k) \
;         acc[ai][bj][m][n] = __builtin_amdgcn_mfma_f32_16x16x32_bf16(Bt[n][k], At[m][k], acc[ai][bj][m][n], 0, 0, 0); __builtin_amdgcn_s_setprio(0); } while (0)
; #define PG8_WAIT_V(n) asm volatile("s_waitcnt vmcnt(" #n ")" ::: "memory")
; #define PG8_WAIT_L(n) asm volatile("s_waitcnt lgkmcnt(" #n ")" ::: "memory")
; #define PG8_BAR __builtin_amdgcn_s_barrier()
; #define PG8_SCHED __builtin_amdgcn_sched_barrier(0)
; template <class Desc, class Epi, bool ALIGN_EPI>
; __device__ __forceinline__ void gemm_phase(LAS unsigned char* lds, const Desc& D, const Epi& E, int G, int c) {
;     ...
;             PG8_LDA(At, 1, 1); PG8_STAGE(PG8_SB(1, 0), b3, voffB); PG8_STAGE(PG8_SB(1, 1), b3 + hstepB, voffB); PG8_STAGE(PG8_SA(1, 0), a3, voffA);
;             PG8_WAIT_V(8); PG8_WAIT_L(0); PG8_BAR; PG8_MMA(1, 0, At, B0); PG8_MMA(1, 1, At, B1); PG8_BAR; PG8_SCHED;
;         }
	s_mov_b32 m0, s64
	v_lshl_add_u64 v[196:197], v[196:197], 0, s[76:77]
	s_add_u32 s20, s20, 0x2b0080
	ds_read_b128 v[164:167], v247 offset:49152
	ds_read_b128 v[168:171], v247 offset:50176
	ds_read_b128 v[172:175], v247 offset:51200
	ds_read_b128 v[176:179], v247 offset:52224
	ds_read_b128 v[180:183], v247 offset:53248
	ds_read_b128 v[184:187], v247 offset:54272
	ds_read_b128 v[188:191], v247 offset:55296
	ds_read_b128 v[192:195], v247 offset:56320
	global_load_lds_dwordx4 v[196:197], off
	v_lshl_add_u64 v[196:197], v[198:199], 0, s[76:77]
	s_mov_b32 m0, s65
	s_addc_u32 s21, s21, 0
	global_load_lds_dwordx4 v[196:197], off
	v_lshl_add_u64 v[196:197], s[20:21], 0, v[202:203]
	s_mov_b32 m0, s69
	s_nop 0
	global_load_lds_dwordx4 v[196:197], off
	v_lshl_add_u64 v[196:197], s[20:21], 0, v[206:207]
	s_mov_b32 m0, s70
	s_nop 0
	global_load_lds_dwordx4 v[196:197], off
	v_lshl_add_u64 v[196:197], v[208:209], 0, s[76:77]
	s_mov_b32 m0, s66
	s_nop 0
	global_load_lds_dwordx4 v[196:197], off
	v_lshl_add_u64 v[196:197], v[210:211], 0, s[76:77]
	s_mov_b32 m0, s67
	s_nop 0
	global_load_lds_dwordx4 v[196:197], off
	s_waitcnt vmcnt(8)
	s_waitcnt lgkmcnt(0)
	s_barrier
	v_mfma_f32_16x16x32_bf16 v[84:87], v[132:135], v[164:167], v[84:87]
	v_mfma_f32_16x16x32_bf16 v[84:87], v[136:139], v[168:171], v[84:87]
	v_mfma_f32_16x16x32_bf16 v[76:79], v[140:143], v[164:167], v[76:79]
	v_mfma_f32_16x16x32_bf16 v[76:79], v[144:147], v[168:171], v[76:79]
	v_mfma_f32_16x16x32_bf16 v[40:43], v[148:151], v[164:167], v[40:43]
	v_mfma_f32_16x16x32_bf16 v[40:43], v[152:155], v[168:171], v[40:43]
	v_mfma_f32_16x16x32_bf16 v[36:39], v[156:159], v[164:167], v[36:39]
	v_mfma_f32_16x16x32_bf16 v[36:39], v[160:163], v[168:171], v[36:39]
	v_mfma_f32_16x16x32_bf16 v[24:27], v[156:159], v[172:175], v[24:27]
	v_mfma_f32_16x16x32_bf16 v[24:27], v[160:163], v[176:179], v[24:27]
	v_mfma_f32_16x16x32_bf16 v[28:31], v[148:151], v[172:175], v[28:31]
	v_mfma_f32_16x16x32_bf16 v[28:31], v[152:155], v[176:179], v[28:31]
	v_mfma_f32_16x16x32_bf16 v[68:71], v[140:143], v[172:175], v[68:71]
	v_mfma_f32_16x16x32_bf16 v[68:71], v[144:147], v[176:179], v[68:71]
	v_mfma_f32_16x16x32_bf16 v[72:75], v[132:135], v[172:175], v[72:75]
	v_mfma_f32_16x16x32_bf16 v[72:75], v[136:139], v[176:179], v[72:75]
	v_mfma_f32_16x16x32_bf16 v[60:63], v[132:135], v[180:183], v[60:63]
	v_mfma_f32_16x16x32_bf16 v[60:63], v[136:139], v[184:187], v[60:63]
	v_mfma_f32_16x16x32_bf16 v[56:59], v[140:143], v[180:183], v[56:59]
	v_mfma_f32_16x16x32_bf16 v[56:59], v[144:147], v[184:187], v[56:59]
	v_mfma_f32_16x16x32_bf16 v[16:19], v[148:151], v[180:183], v[16:19]
	v_mfma_f32_16x16x32_bf16 v[16:19], v[152:155], v[184:187], v[16:19]
	v_mfma_f32_16x16x32_bf16 v[12:15], v[156:159], v[180:183], v[12:15]
	v_mfma_f32_16x16x32_bf16 v[12:15], v[160:163], v[184:187], v[12:15]
	v_mfma_f32_16x16x32_bf16 v[4:7], v[156:159], v[188:191], v[4:7]
	v_mfma_f32_16x16x32_bf16 v[4:7], v[160:163], v[192:195], v[4:7]
	v_mfma_f32_16x16x32_bf16 v[8:11], v[148:151], v[188:191], v[8:11]
	v_mfma_f32_16x16x32_bf16 v[8:11], v[152:155], v[192:195], v[8:11]
	v_mfma_f32_16x16x32_bf16 v[44:47], v[140:143], v[188:191], v[44:47]
	v_mfma_f32_16x16x32_bf16 v[44:47], v[144:147], v[192:195], v[44:47]
	v_mfma_f32_16x16x32_bf16 v[48:51], v[132:135], v[188:191], v[48:51]
	v_mfma_f32_16x16x32_bf16 v[48:51], v[136:139], v[192:195], v[48:51]
	s_barrier
	s_cmp_ge_u32 s14, s24
	s_mov_b32 s39, s14
	s_cbranch_scc1 .LBB0_1776
